# non-temporal hint also on the out-proj residual loads and on the read-once input loads of the prep phases (0, 1)
# baseline (speedup 1.0000x reference)
.LBB0_23:
	v_ashrrev_i32_e32 v12, 5, v0
	v_ashrrev_i32_e32 v13, 31, v12
	s_waitcnt lgkmcnt(0)
	v_lshl_add_u64 v[12:13], v[12:13], 2, s[14:15]
	global_load_dword v1, v[12:13], off nt
	s_waitcnt vmcnt(0)
	v_cvt_f32_i32_e32 v1, v1
	v_mul_f32_e32 v1, v4, v1
	v_and_b32_e32 v11, 0x7fffffff, v1
	v_cmp_nlt_f32_e64 s[2:3], |v1|, s21
	s_and_saveexec_b64 s[4:5], s[2:3]
	s_xor_b64 s[18:19], exec, s[4:5]
	s_cbranch_execz .LBB0_25
	v_lshrrev_b32_e32 v2, 23, v11
	v_add_u32_e32 v2, 0xffffff88, v2
	v_cmp_lt_u32_e32 vcc, 63, v2
	s_nop 1
	v_cndmask_b32_e32 v12, 0, v9, vcc
	v_add_u32_e32 v2, v12, v2
	v_cmp_lt_u32_e64 s[2:3], 31, v2
	s_nop 1
	v_cndmask_b32_e64 v12, 0, v10, s[2:3]
	v_add_u32_e32 v2, v12, v2
	v_cmp_lt_u32_e64 s[4:5], 31, v2
	s_nop 1
	v_cndmask_b32_e64 v12, 0, v10, s[4:5]
	v_add_u32_e32 v26, v12, v2
	v_and_b32_e32 v2, 0x7fffff, v11
	v_or_b32_e32 v24, 0x800000, v2
	v_mad_u64_u32 v[12:13], s[6:7], v24, s24, 0
	v_mov_b32_e32 v2, v13
	v_mad_u64_u32 v[14:15], s[6:7], v24, s25, v[2:3]
	v_mov_b32_e32 v2, v15
	v_mad_u64_u32 v[16:17], s[6:7], v24, s26, v[2:3]
	v_mov_b32_e32 v2, v17
	v_mad_u64_u32 v[18:19], s[6:7], v24, s27, v[2:3]
	v_mov_b32_e32 v2, v19
	v_mad_u64_u32 v[20:21], s[6:7], v24, s28, v[2:3]
	v_mov_b32_e32 v2, v21
	v_mad_u64_u32 v[22:23], s[6:7], v24, s29, v[2:3]
	v_mov_b32_e32 v2, v23
	v_mad_u64_u32 v[24:25], s[6:7], v24, s30, v[2:3]
	v_cndmask_b32_e32 v13, v22, v18, vcc
	v_cndmask_b32_e32 v2, v24, v20, vcc
	v_cndmask_b32_e32 v17, v25, v22, vcc
	v_cndmask_b32_e64 v15, v2, v13, s[2:3]
	v_cndmask_b32_e64 v2, v17, v2, s[2:3]
	v_cndmask_b32_e32 v17, v20, v16, vcc
	v_cndmask_b32_e64 v13, v13, v17, s[2:3]
	v_cndmask_b32_e64 v2, v2, v15, s[4:5]
	v_cndmask_b32_e64 v15, v15, v13, s[4:5]
	v_sub_u32_e32 v19, 32, v26
	v_alignbit_b32 v20, v2, v15, v19
	v_cmp_eq_u32_e64 s[6:7], 0, v26
	v_cndmask_b32_e32 v12, v16, v12, vcc
	s_nop 0
	v_cndmask_b32_e64 v20, v20, v2, s[6:7]
	v_cndmask_b32_e32 v2, v18, v14, vcc
	v_cndmask_b32_e64 v14, v17, v2, s[2:3]
	v_cndmask_b32_e64 v13, v13, v14, s[4:5]
	v_alignbit_b32 v17, v15, v13, v19
	v_cndmask_b32_e64 v15, v17, v15, s[6:7]
	v_bfe_u32 v21, v20, 29, 1
	v_cndmask_b32_e64 v2, v2, v12, s[2:3]
	v_alignbit_b32 v17, v20, v15, 30
	v_sub_u32_e32 v22, 0, v21
	v_cndmask_b32_e64 v2, v14, v2, s[4:5]
	v_xor_b32_e32 v17, v17, v22
	v_alignbit_b32 v12, v13, v2, v19
	v_cndmask_b32_e64 v12, v12, v13, s[6:7]
	v_ffbh_u32_e32 v14, v17
	v_alignbit_b32 v13, v15, v12, 30
	v_min_u32_e32 v14, 32, v14
	v_alignbit_b32 v2, v12, v2, 30
	v_xor_b32_e32 v13, v13, v22
	v_sub_u32_e32 v15, 31, v14
	v_xor_b32_e32 v2, v2, v22
	v_alignbit_b32 v16, v17, v13, v15
	v_alignbit_b32 v2, v13, v2, v15
	v_alignbit_b32 v12, v16, v2, 9
	v_ffbh_u32_e32 v13, v12
	v_min_u32_e32 v13, 32, v13
	v_lshrrev_b32_e32 v18, 29, v20
	v_not_b32_e32 v15, v13
	v_alignbit_b32 v2, v12, v2, v15
	v_lshlrev_b32_e32 v12, 31, v18
	v_or_b32_e32 v15, 0x33000000, v12
	v_add_lshl_u32 v13, v13, v14, 23
	v_lshrrev_b32_e32 v2, 9, v2
	v_sub_u32_e32 v13, v15, v13
	v_or_b32_e32 v12, 0.5, v12
	v_lshlrev_b32_e32 v14, 23, v14
	v_or_b32_e32 v2, v13, v2
	v_lshrrev_b32_e32 v13, 9, v16
	v_sub_u32_e32 v12, v12, v14
	v_or_b32_e32 v12, v13, v12
	v_mul_f32_e32 v13, 0x3fc90fda, v12
	v_fma_f32 v14, v12, s31, -v13
	v_fmac_f32_e32 v14, 0x33a22168, v12
	v_fmac_f32_e32 v14, 0x3fc90fda, v2
	v_lshrrev_b32_e32 v12, 30, v20
	v_add_f32_e32 v2, v13, v14
	v_add_u32_e32 v12, v21, v12

.LBB0_32:
	global_load_dword v4, v[0:1], off nt
	v_add_u32_e32 v3, 0x200, v3
	v_cmp_lt_i32_e32 vcc, s27, v3
	v_lshl_add_u64 v[0:1], v[0:1], 0, s[12:13]
	s_or_b64 s[16:17], vcc, s[16:17]
	s_waitcnt vmcnt(0)
	v_mul_f32_e32 v5, 0xbfb8aa3b, v4
	v_exp_f32_e32 v5, v5
	s_nop 0
	v_add_f32_e32 v5, 1.0, v5
	v_rcp_f32_e32 v5, v5
	s_nop 0
	v_mul_f32_e32 v4, v4, v5
	ds_write_b32 v2, v4
	v_add_u32_e32 v2, 0x800, v2
	s_andn2_b64 exec, exec, s[16:17]
	s_cbranch_execnz .LBB0_32

.LBB0_35:
	v_add_co_u32_e32 v128, vcc, 0xfffd3000, v118
	ds_read_b128 v[76:79], v139
	ds_read_b128 v[60:63], v139 offset:16
	ds_read_b128 v[48:51], v139 offset:32
	ds_read_b128 v[44:47], v139 offset:48
	ds_read_b128 v[0:3], v139 offset:4112
	ds_read_b128 v[4:7], v139 offset:4096
	ds_read_b128 v[72:75], v139 offset:8208
	ds_read_b128 v[88:91], v139 offset:8192
	ds_read_b128 v[8:11], v139 offset:12304
	ds_read_b128 v[12:15], v139 offset:12288
	ds_read_b128 v[80:83], v139 offset:16400
	ds_read_b128 v[92:95], v139 offset:16384
	ds_read_b128 v[16:19], v139 offset:20496
	ds_read_b128 v[20:23], v139 offset:20480
	ds_read_b128 v[28:31], v139 offset:24592
	ds_read_b128 v[104:107], v139 offset:24576
	ds_read_b128 v[36:39], v139 offset:28688
	ds_read_b128 v[56:59], v139 offset:28672
	ds_read_b128 v[40:43], v139 offset:24608
	ds_read_b128 v[32:35], v139 offset:24624
	ds_read_b128 v[52:55], v139 offset:28704
	ds_read_b128 v[24:27], v139 offset:28720
	ds_read_b128 v[68:71], v139 offset:4128
	ds_read_b128 v[64:67], v139 offset:4144
	ds_read_b128 v[142:145], v139 offset:8224
	ds_read_b128 v[146:149], v139 offset:8240
	ds_read_b128 v[96:99], v139 offset:12320
	ds_read_b128 v[84:87], v139 offset:12336
	ds_read_b128 v[150:153], v139 offset:16416
	ds_read_b128 v[154:157], v139 offset:16432
	ds_read_b128 v[108:111], v139 offset:20512
	ds_read_b128 v[100:103], v139 offset:20528
	v_addc_co_u32_e32 v129, vcc, -1, v119, vcc
	v_add_co_u32_e32 v158, vcc, 0xfffd6000, v118
	s_waitcnt lgkmcnt(14)
	v_mov_b32_e32 v170, v88
	v_addc_co_u32_e32 v159, vcc, -1, v119, vcc
	v_add_co_u32_e32 v160, vcc, 0xfffd9000, v118
	v_mov_b32_e32 v88, v90
	s_nop 0
	v_addc_co_u32_e32 v161, vcc, -1, v119, vcc
	v_add_co_u32_e32 v162, vcc, 0xfffdc000, v118
	v_mov_b32_e32 v90, v72
	s_nop 0
	v_addc_co_u32_e32 v163, vcc, -1, v119, vcc
	v_add_co_u32_e32 v164, vcc, 0xfffdf000, v118
	v_mov_b32_e32 v72, v106
	s_nop 0
	v_addc_co_u32_e32 v165, vcc, -1, v119, vcc
	v_add_co_u32_e32 v166, vcc, 0xfffe2000, v118
	s_waitcnt lgkmcnt(6)
	v_mov_b32_e32 v106, v146
	v_addc_co_u32_e32 v167, vcc, -1, v119, vcc
	s_waitcnt lgkmcnt(3)
	v_mov_b32_e32 v146, v152
	v_add_co_u32_e32 v152, vcc, 0xfffe5000, v118
	v_mov_b32_e32 v171, v12
	v_mov_b32_e32 v12, v89
	v_mov_b32_e32 v89, v14
	v_mov_b32_e32 v14, v91
	v_mov_b32_e32 v91, v8
	v_mov_b32_e32 v8, v73
	v_mov_b32_e32 v73, v58
	v_mov_b32_e32 v58, v107
	v_mov_b32_e32 v107, v84
	v_mov_b32_e32 v84, v147
	s_waitcnt lgkmcnt(1)
	v_mov_b32_e32 v147, v110
	v_mov_b32_e32 v110, v153
	v_addc_co_u32_e32 v153, vcc, -1, v119, vcc
	global_load_dword v128, v[128:129], off nt
	s_nop 0
	global_load_dword v158, v[158:159], off nt
	s_nop 0
	global_load_dword v160, v[160:161], off nt
	s_nop 0
	global_load_dword v162, v[162:163], off nt
	v_mov_b32_e32 v168, v76
	v_mov_b32_e32 v76, v78
	v_mov_b32_e32 v78, v60
	v_mov_b32_e32 v172, v92
	v_mov_b32_e32 v92, v94
	v_mov_b32_e32 v94, v80
	v_mov_b32_e32 v60, v104
	v_mov_b32_e32 v80, v62
	v_mov_b32_e32 v62, v48
	v_mov_b32_e32 v48, v50
	v_mov_b32_e32 v50, v44
	v_mov_b32_e32 v44, v46
	v_mov_b32_e32 v46, v74
	v_mov_b32_e32 v74, v142
	v_mov_b32_e32 v104, v144
	v_mov_b32_e32 v142, v148
	v_mov_b32_e32 v144, v82
	v_mov_b32_e32 v82, v150
	v_mov_b32_e32 v148, v154
	v_mov_b32_e32 v150, v156
	global_load_dword v154, v[164:165], off nt
	global_load_dword v156, v[166:167], off nt
	v_add_co_u32_e32 v164, vcc, 0xfffe8000, v118
	global_load_dword v152, v[152:153], off nt
	s_nop 0
	v_addc_co_u32_e32 v165, vcc, -1, v119, vcc
	v_add_co_u32_e32 v166, vcc, 0xfffeb000, v118
	v_mov_b32_e32 v169, v4
	s_nop 0
	v_addc_co_u32_e32 v167, vcc, -1, v119, vcc
	global_load_dword v166, v[166:167], off nt
	v_mov_b32_e32 v173, v20
	global_load_dword v153, v[164:165], off nt
	v_add_co_u32_e32 v164, vcc, 0xfffee000, v118
	v_mov_b32_e32 v4, v77
	s_nop 0
	v_addc_co_u32_e32 v165, vcc, -1, v119, vcc
	v_add_co_u32_e32 v174, vcc, 0xffff1000, v118
	global_load_dword v167, v[164:165], off nt
	s_nop 0
	v_addc_co_u32_e32 v175, vcc, -1, v119, vcc
	global_load_dword v174, v[174:175], off nt
	v_add_co_u32_e32 v164, vcc, 0xffff4000, v118
	v_mov_b32_e32 v20, v93
	s_nop 0
	v_addc_co_u32_e32 v165, vcc, -1, v119, vcc
	v_add_co_u32_e32 v176, vcc, 0xffff7000, v118
	global_load_dword v175, v[164:165], off nt
	s_nop 0
	v_addc_co_u32_e32 v177, vcc, -1, v119, vcc
	global_load_dword v176, v[176:177], off nt
	v_add_co_u32_e32 v164, vcc, 0xffffa000, v118
	v_mov_b32_e32 v77, v6
	s_nop 0
	v_addc_co_u32_e32 v165, vcc, -1, v119, vcc
	v_add_co_u32_e32 v178, vcc, 0xffffd000, v118
	global_load_dword v177, v[164:165], off nt
	s_nop 0
	v_addc_co_u32_e32 v179, vcc, -1, v119, vcc
	global_load_dword v164, v[178:179], off nt
	s_nop 0
	global_load_dword v178, v[118:119], off nt
	v_mov_b32_e32 v93, v22
	v_mov_b32_e32 v6, v79
	v_mov_b32_e32 v79, v0
	v_mov_b32_e32 v22, v95
	v_mov_b32_e32 v0, v61
	v_mov_b32_e32 v61, v56
	v_mov_b32_e32 v95, v16
	v_mov_b32_e32 v56, v105
	v_mov_b32_e32 v16, v81
	v_mov_b32_e32 v81, v2
	s_waitcnt vmcnt(15)
	v_pk_fma_f32 v[126:127], v[128:129], v[168:169], v[126:127] op_sel_hi:[0,1,1]
	v_pk_fma_f32 v[124:125], v[128:129], v[170:171], v[124:125] op_sel_hi:[0,1,1]
	v_pk_fma_f32 v[122:123], v[128:129], v[172:173], v[122:123] op_sel_hi:[0,1,1]
	s_waitcnt vmcnt(14)
	v_pk_fma_f32 v[4:5], v[158:159], v[4:5], v[126:127] op_sel_hi:[0,1,1]
	v_pk_fma_f32 v[12:13], v[158:159], v[12:13], v[124:125] op_sel_hi:[0,1,1]
	v_pk_fma_f32 v[20:21], v[158:159], v[20:21], v[122:123] op_sel_hi:[0,1,1]
	s_waitcnt vmcnt(13)
	v_pk_fma_f32 v[4:5], v[160:161], v[76:77], v[4:5] op_sel_hi:[0,1,1]
	v_pk_fma_f32 v[12:13], v[160:161], v[88:89], v[12:13] op_sel_hi:[0,1,1]
	v_pk_fma_f32 v[20:21], v[160:161], v[92:93], v[20:21] op_sel_hi:[0,1,1]
	v_pk_fma_f32 v[60:61], v[128:129], v[60:61], v[120:121] op_sel_hi:[0,1,1]
	s_waitcnt vmcnt(12)
	v_pk_fma_f32 v[4:5], v[162:163], v[6:7], v[4:5] op_sel_hi:[0,1,1]
	v_pk_fma_f32 v[6:7], v[162:163], v[14:15], v[12:13] op_sel_hi:[0,1,1]
	v_pk_fma_f32 v[12:13], v[162:163], v[22:23], v[20:21] op_sel_hi:[0,1,1]
	v_mov_b32_e32 v2, v63
	v_mov_b32_e32 v63, v68
	v_mov_b32_e32 v68, v49
	v_mov_b32_e32 v49, v70
	v_mov_b32_e32 v70, v51
	v_mov_b32_e32 v51, v64
	v_mov_b32_e32 v64, v45
	v_mov_b32_e32 v45, v66
	v_mov_b32_e32 v66, v47
	v_mov_b32_e32 v47, v10
	v_mov_b32_e32 v10, v75
	v_mov_b32_e32 v75, v96
	v_mov_b32_e32 v96, v143
	v_mov_b32_e32 v143, v86
	v_mov_b32_e32 v86, v149
	s_waitcnt lgkmcnt(0)
	v_mov_b32_e32 v149, v100
	v_mov_b32_e32 v100, v155
	v_pk_fma_f32 v[56:57], v[158:159], v[56:57], v[60:61] op_sel_hi:[0,1,1]
	s_waitcnt vmcnt(11)
	v_pk_fma_f32 v[4:5], v[154:155], v[78:79], v[4:5] op_sel_hi:[0,1,1]
	v_pk_fma_f32 v[6:7], v[154:155], v[90:91], v[6:7] op_sel_hi:[0,1,1]
	v_pk_fma_f32 v[12:13], v[154:155], v[94:95], v[12:13] op_sel_hi:[0,1,1]
	s_waitcnt vmcnt(10)
	v_mov_b32_e32 v155, v156
	v_mov_b32_e32 v105, v98
	v_mov_b32_e32 v98, v145
	v_mov_b32_e32 v145, v18
	v_pk_fma_f32 v[56:57], v[160:161], v[72:73], v[56:57] op_sel_hi:[0,1,1]
	v_pk_fma_f32 v[0:1], v[156:157], v[0:1], v[4:5] op_sel_hi:[0,1,1]
	v_pk_fma_f32 v[4:5], v[156:157], v[8:9], v[6:7] op_sel_hi:[0,1,1]
	v_pk_fma_f32 v[6:7], v[156:157], v[16:17], v[12:13] op_sel_hi:[0,1,1]
	v_pk_mul_f32 v[8:9], v[154:155], v[36:37]
	v_mov_b32_e32 v18, v83
	v_pk_fma_f32 v[14:15], v[162:163], v[58:59], v[56:57] op_sel_hi:[0,1,1]
	v_mul_f32_e32 v20, v154, v28
	v_mov_b32_e32 v21, v8
	s_waitcnt vmcnt(7)
	v_pk_fma_f32 v[0:1], v[152:153], v[80:81], v[0:1] op_sel_hi:[0,1,1]
	v_mov_b32_e32 v28, v153
	v_pk_fma_f32 v[4:5], v[152:153], v[46:47], v[4:5] op_sel_hi:[0,1,1]
	v_pk_fma_f32 v[6:7], v[152:153], v[144:145], v[6:7] op_sel_hi:[0,1,1]
	v_mov_b32_e32 v83, v108
	v_mul_f32_e32 v22, v156, v29
	v_pk_mul_f32 v[16:17], v[152:153], v[38:39]
	v_mov_b32_e32 v23, v9
	v_pk_add_f32 v[14:15], v[14:15], v[20:21]
	v_pk_fma_f32 v[0:1], v[28:29], v[2:3], v[0:1] op_sel_hi:[0,1,1]
	v_pk_fma_f32 v[2:3], v[28:29], v[10:11], v[4:5] op_sel_hi:[0,1,1]
	v_pk_fma_f32 v[4:5], v[28:29], v[18:19], v[6:7] op_sel_hi:[0,1,1]
	v_mov_b32_e32 v108, v151
	v_mul_f32_e32 v12, v152, v30
	v_mov_b32_e32 v13, v16
	s_waitcnt vmcnt(6)
	v_pk_fma_f32 v[0:1], v[166:167], v[62:63], v[0:1] op_sel_hi:[0,1,1]
	v_mov_b32_e32 v16, v167
	v_pk_fma_f32 v[2:3], v[166:167], v[74:75], v[2:3] op_sel_hi:[0,1,1]
	v_pk_fma_f32 v[4:5], v[166:167], v[82:83], v[4:5] op_sel_hi:[0,1,1]
	v_pk_add_f32 v[14:15], v[14:15], v[22:23]
	v_mul_f32_e32 v8, v153, v31
	v_mov_b32_e32 v9, v17
	v_pk_mul_f32 v[10:11], v[166:167], v[52:53]
	v_pk_fma_f32 v[0:1], v[16:17], v[68:69], v[0:1] op_sel_hi:[0,1,1]
	v_pk_fma_f32 v[2:3], v[16:17], v[96:97], v[2:3] op_sel_hi:[0,1,1]
	v_pk_fma_f32 v[4:5], v[16:17], v[108:109], v[4:5] op_sel_hi:[0,1,1]
	v_pk_add_f32 v[12:13], v[14:15], v[12:13]
	v_mul_f32_e32 v20, v166, v40
	v_mov_b32_e32 v21, v10
	s_waitcnt vmcnt(4)
	v_pk_fma_f32 v[0:1], v[174:175], v[48:49], v[0:1] op_sel_hi:[0,1,1]
	v_mov_b32_e32 v16, v175
	v_pk_fma_f32 v[2:3], v[174:175], v[104:105], v[2:3] op_sel_hi:[0,1,1]
	v_pk_fma_f32 v[4:5], v[174:175], v[146:147], v[4:5] op_sel_hi:[0,1,1]
	v_pk_add_f32 v[8:9], v[12:13], v[8:9]
	v_mul_f32_e32 v6, v167, v41
	v_mov_b32_e32 v7, v11
	v_pk_mul_f32 v[14:15], v[174:175], v[54:55]
	v_pk_fma_f32 v[0:1], v[16:17], v[70:71], v[0:1] op_sel_hi:[0,1,1]
	v_pk_fma_f32 v[2:3], v[16:17], v[98:99], v[2:3] op_sel_hi:[0,1,1]
	v_pk_fma_f32 v[4:5], v[16:17], v[110:111], v[4:5] op_sel_hi:[0,1,1]
	v_pk_add_f32 v[8:9], v[8:9], v[20:21]
	v_mul_f32_e32 v18, v174, v42
	v_mov_b32_e32 v19, v14
	s_waitcnt vmcnt(2)
	v_pk_fma_f32 v[0:1], v[176:177], v[50:51], v[0:1] op_sel_hi:[0,1,1]
	v_mov_b32_e32 v20, v177
	v_pk_fma_f32 v[2:3], v[176:177], v[106:107], v[2:3] op_sel_hi:[0,1,1]
	v_pk_fma_f32 v[4:5], v[176:177], v[148:149], v[4:5] op_sel_hi:[0,1,1]
	v_pk_add_f32 v[6:7], v[8:9], v[6:7]
	v_mov_b32_e32 v151, v102
	v_mul_f32_e32 v10, v175, v43
	v_mov_b32_e32 v11, v15
	v_pk_mul_f32 v[16:17], v[176:177], v[24:25]
	v_pk_fma_f32 v[0:1], v[20:21], v[64:65], v[0:1] op_sel_hi:[0,1,1]
	v_pk_fma_f32 v[2:3], v[20:21], v[84:85], v[2:3] op_sel_hi:[0,1,1]
	v_pk_fma_f32 v[4:5], v[20:21], v[100:101], v[4:5] op_sel_hi:[0,1,1]
	v_pk_add_f32 v[6:7], v[6:7], v[18:19]
	v_mul_f32_e32 v12, v176, v32
	v_mov_b32_e32 v13, v16
	s_waitcnt vmcnt(1)
	v_pk_fma_f32 v[0:1], v[164:165], v[44:45], v[0:1] op_sel_hi:[0,1,1]
	v_pk_fma_f32 v[2:3], v[164:165], v[142:143], v[2:3] op_sel_hi:[0,1,1]
	v_pk_fma_f32 v[4:5], v[164:165], v[150:151], v[4:5] op_sel_hi:[0,1,1]
	s_waitcnt vmcnt(0)
	v_mov_b32_e32 v165, v178
	v_pk_add_f32 v[6:7], v[6:7], v[10:11]
	v_mul_f32_e32 v14, v177, v33
	v_mov_b32_e32 v15, v17
	v_pk_fma_f32 v[126:127], v[178:179], v[66:67], v[0:1] op_sel_hi:[0,1,1]
	v_pk_fma_f32 v[124:125], v[178:179], v[86:87], v[2:3] op_sel_hi:[0,1,1]
	v_pk_mul_f32 v[0:1], v[164:165], v[26:27]
	v_pk_add_f32 v[2:3], v[6:7], v[12:13]
	v_add_u32_e32 v140, 16, v140
	v_mul_f32_e32 v8, v164, v34
	v_pk_add_f32 v[2:3], v[2:3], v[14:15]
	v_mov_b32_e32 v9, v0
	v_cmp_ge_i32_e64 s[8:9], v140, v133
	v_mov_b32_e32 v102, v157
	v_mul_f32_e32 v20, v178, v35
	v_mov_b32_e32 v21, v1
	v_pk_add_f32 v[0:1], v[2:3], v[8:9]
	v_add_u32_e32 v139, 64, v139
	s_or_b64 s[20:21], s[8:9], s[20:21]
	v_lshl_add_u64 v[118:119], v[118:119], 0, s[14:15]
	v_pk_fma_f32 v[122:123], v[178:179], v[102:103], v[4:5] op_sel_hi:[0,1,1]
	v_pk_add_f32 v[120:121], v[0:1], v[20:21]
	s_andn2_b64 exec, exec, s[20:21]
	s_cbranch_execnz .LBB0_35
	s_or_b64 exec, exec, s[20:21]

.LBB0_39:
	global_load_dword v5, v[0:1], off nt
	v_and_b32_e32 v7, 0x3fffffc0, v4
	v_ashrrev_i32_e32 v6, 6, v4
	v_add_u32_e32 v8, 0x200, v4
	v_lshl_or_b32 v14, v7, 2, v134
	v_cmp_lt_i32_e32 vcc, -1, v4
	v_ashrrev_i32_e32 v7, 31, v6
	v_mov_b32_e32 v4, v8
	ds_read2st64_b32 v[8:9], v14 offset0:128 offset1:136
	ds_read2st64_b32 v[10:11], v14 offset0:144 offset1:152
	ds_read2st64_b32 v[12:13], v14 offset0:160 offset1:168
	ds_read2st64_b32 v[14:15], v14 offset0:176 offset1:184
	v_lshl_add_u64 v[6:7], s[16:17], 0, v[6:7]
	v_mad_u64_u32 v[16:17], s[20:21], v6, s26, v[2:3]
	s_waitcnt lgkmcnt(3)
	v_add_f32_e32 v6, 0, v8
	v_add_f32_e32 v6, v6, v9
	s_waitcnt lgkmcnt(2)
	v_add_f32_e32 v6, v6, v10
	v_add_f32_e32 v6, v6, v11
	s_waitcnt lgkmcnt(1)
	v_add_f32_e32 v6, v6, v12
	v_add_f32_e32 v6, v6, v13
	s_waitcnt lgkmcnt(0)
	v_add_f32_e32 v6, v6, v14
	v_add_f32_e32 v6, v6, v15
	s_or_b64 s[18:19], vcc, s[18:19]
	v_mad_i32_i24 v17, v7, s26, v17
	s_waitcnt vmcnt(0)
	v_add_f32_e32 v5, v6, v5
	global_store_dword v[16:17], v5, off
	s_andn2_b64 exec, exec, s[18:19]
	s_cbranch_execnz .LBB0_39
	s_branch .LBB0_29

.LBB0_104:
	global_load_dword v13, v[2:3], off nt
	global_load_dword v14, v[4:5], off nt
	v_add_u32_e32 v11, 1, v11
	v_cmp_ge_i32_e64 s[2:3], v11, v10
	v_lshl_add_u64 v[2:3], v[2:3], 0, 4
	v_lshl_add_u64 v[4:5], v[4:5], 0, s[6:7]
	s_or_b64 s[8:9], s[2:3], s[8:9]
	s_waitcnt vmcnt(0)
	v_fmac_f32_e32 v12, v13, v14
	s_andn2_b64 exec, exec, s[8:9]
	s_cbranch_execnz .LBB0_104
	s_or_b64 exec, exec, s[8:9]
	ds_write_b32 v9, v12
	s_waitcnt lgkmcnt(0)
	s_barrier
	s_and_saveexec_b64 s[2:3], vcc
	s_cbranch_execz .LBB0_102
	ds_read2st64_b32 v[2:3], v9 offset1:2
	ds_read2st64_b32 v[4:5], v9 offset0:4 offset1:6
	s_load_dwordx2 s[8:9], s[0:1], 0x150
	v_add_u32_e32 v10, s16, v6
	v_ashrrev_i32_e32 v11, 31, v10
	s_waitcnt lgkmcnt(0)
	v_add_f32_e32 v2, 0, v2
	v_add_f32_e32 v2, v2, v3
	v_add_f32_e32 v2, v2, v4
	v_add_f32_e32 v4, v2, v5
	v_lshl_add_u64 v[2:3], v[10:11], 2, s[8:9]
	global_store_dword v[2:3], v4, off
	s_branch .LBB0_102

.LBB0_114:
	s_or_saveexec_b64 s[4:5], s[4:5]
	s_lshl_b32 s20, s20, 10
	s_sub_i32 s20, 0, s20
	v_mov_b32_e32 v5, 0
	v_mov_b32_e32 v16, 0
	v_mov_b32_e32 v17, 0
	v_mov_b32_e32 v18, 0
	s_xor_b64 exec, exec, s[4:5]
	s_cbranch_execz .LBB0_111
	s_add_i32 s21, s20, s17
	v_ashrrev_i32_e32 v5, 31, v4
	v_add_u32_e32 v16, s21, v6
	v_lshl_add_u64 v[4:5], v[4:5], 2, s[2:3]
	v_add_u32_e32 v17, 8, v16
	v_mad_i64_i32 v[22:23], s[24:25], v17, s36, v[4:5]
	v_add_u32_e32 v17, 16, v16
	v_mad_i64_i32 v[24:25], s[24:25], v17, s36, v[4:5]
	v_add_u32_e32 v17, 24, v16
	v_mad_i64_i32 v[26:27], s[24:25], v17, s36, v[4:5]
	v_add_u32_e32 v17, 32, v16
	v_mad_i64_i32 v[28:29], s[24:25], v17, s36, v[4:5]
	v_add_u32_e32 v17, 40, v16
	v_mad_i64_i32 v[20:21], s[24:25], v16, s36, v[4:5]
	v_mad_i64_i32 v[30:31], s[24:25], v17, s36, v[4:5]
	v_add_u32_e32 v17, 48, v16
	v_add_u32_e32 v16, 56, v16
	v_mad_i64_i32 v[34:35], s[24:25], v17, s36, v[4:5]
	v_mad_i64_i32 v[36:37], s[24:25], v16, s36, v[4:5]
	global_load_dword v4, v[20:21], off nt
	global_load_dword v19, v[22:23], off nt
	global_load_dword v33, v[24:25], off nt
	global_load_dword v38, v[26:27], off nt
	global_load_dword v5, v[28:29], off nt
	global_load_dword v16, v[30:31], off nt
	global_load_dword v17, v[34:35], off nt
	global_load_dword v18, v[36:37], off nt
	s_waitcnt vmcnt(7)
	ds_write_b32 v15, v4
	s_waitcnt vmcnt(6)
	ds_write_b32 v15, v19 offset:2080
	s_waitcnt vmcnt(5)
	ds_write_b32 v15, v33 offset:4160
	s_waitcnt vmcnt(4)
	ds_write_b32 v15, v38 offset:6240
	s_branch .LBB0_111

.LBB0_119:
	s_ashr_i32 s4, s50, 31
	s_lshr_b32 s4, s4, 30
	s_add_i32 s4, s50, s4
	s_ashr_i32 s24, s4, 2
	s_lshl_b32 s53, s24, 6
	v_or_b32_e32 v6, s53, v12
	v_cmp_lt_i32_e64 s[4:5], s37, v6
	s_barrier
	s_and_saveexec_b64 s[20:21], s[4:5]
	s_xor_b64 s[20:21], exec, s[20:21]
	ds_write_b32 v20, v1
	s_or_saveexec_b64 s[20:21], s[20:21]
	s_lshl_b32 s24, s24, 8
	v_ashrrev_i32_e32 v7, 31, v6
	s_sub_i32 s54, 0, s24
	v_lshl_add_u64 v[6:7], v[6:7], 2, s[16:17]
	v_mov_b32_e32 v8, 0
	s_xor_b64 exec, exec, s[20:21]
	s_cbranch_execz .LBB0_126
	s_add_i32 s24, s54, s51
	v_add_u32_e32 v8, s24, v2
	v_mad_i64_i32 v[10:11], s[24:25], v8, s38, v[6:7]
	global_load_dword v21, v[10:11], off nt
	v_ashrrev_i32_e32 v9, 31, v8
	s_and_b64 vcc, exec, s[2:3]
	v_lshl_add_u64 v[10:11], v[8:9], 2, s[18:19]
	s_cbranch_vccnz .LBB0_124
	global_load_dword v9, v[10:11], off nt
	s_waitcnt vmcnt(0)
	v_mul_f32_e32 v21, v21, v9
.LBB0_124:
	v_add_u32_e32 v8, 8, v8
	v_mad_i64_i32 v[8:9], s[24:25], v8, s38, v[6:7]
	global_load_dword v8, v[8:9], off nt
	s_and_b64 vcc, exec, s[2:3]
	s_waitcnt vmcnt(1)
	ds_write_b32 v20, v21
	s_cbranch_vccnz .LBB0_126
	global_load_dword v9, v[10:11], off offset:32 nt
	s_waitcnt vmcnt(0)
	v_mul_f32_e32 v8, v8, v9
.LBB0_126:
	s_or_b64 exec, exec, s[20:21]
	s_waitcnt vmcnt(0)
	ds_write_b32 v20, v8 offset:2080
	s_and_saveexec_b64 s[20:21], s[4:5]
	s_xor_b64 s[20:21], exec, s[20:21]
	ds_write_b32 v20, v1 offset:4160
	s_or_saveexec_b64 s[24:25], s[20:21]
	s_add_i32 s20, s51, s54
	v_mov_b32_e32 v9, 0
	v_add_u32_e32 v8, s20, v2
	s_xor_b64 exec, exec, s[24:25]
	s_cbranch_execz .LBB0_133
	v_add_u32_e32 v9, 16, v8
	v_mad_i64_i32 v[10:11], s[54:55], v9, s38, v[6:7]
	global_load_dword v10, v[10:11], off nt
	s_and_b64 vcc, exec, s[2:3]
	s_cbranch_vccnz .LBB0_131
	s_ashr_i32 s21, s20, 31
	v_lshl_add_u64 v[22:23], s[20:21], 0, v[2:3]
	v_lshl_add_u64 v[22:23], v[22:23], 2, s[18:19]
	global_load_dword v9, v[22:23], off offset:64 nt
	s_waitcnt vmcnt(0)
	v_mul_f32_e32 v10, v10, v9
.LBB0_131:
	v_add_u32_e32 v9, 24, v8
	v_mad_i64_i32 v[22:23], s[54:55], v9, s38, v[6:7]
	global_load_dword v9, v[22:23], off nt
	s_and_b64 vcc, exec, s[2:3]
	s_waitcnt vmcnt(1)
	ds_write_b32 v20, v10 offset:4160
	s_cbranch_vccnz .LBB0_133
	s_ashr_i32 s21, s20, 31
	v_lshl_add_u64 v[10:11], s[20:21], 0, v[2:3]
	v_lshl_add_u64 v[10:11], v[10:11], 2, s[18:19]
	global_load_dword v10, v[10:11], off offset:96 nt
	s_waitcnt vmcnt(0)
	v_mul_f32_e32 v9, v9, v10
.LBB0_133:
	s_or_b64 exec, exec, s[24:25]
	s_waitcnt vmcnt(0)
	ds_write_b32 v20, v9 offset:6240
	s_and_saveexec_b64 s[24:25], s[4:5]
	s_xor_b64 s[24:25], exec, s[24:25]
	ds_write_b32 v20, v1 offset:8320
	s_or_saveexec_b64 s[24:25], s[24:25]
	v_mov_b32_e32 v9, 0
	s_xor_b64 exec, exec, s[24:25]
	s_cbranch_execz .LBB0_140
	v_add_u32_e32 v9, 32, v8
	v_mad_i64_i32 v[10:11], s[54:55], v9, s38, v[6:7]
	global_load_dword v10, v[10:11], off nt
	s_and_b64 vcc, exec, s[2:3]
	s_cbranch_vccnz .LBB0_138
	s_ashr_i32 s21, s20, 31
	v_lshl_add_u64 v[22:23], s[20:21], 0, v[2:3]
	v_lshl_add_u64 v[22:23], v[22:23], 2, s[18:19]
	global_load_dword v9, v[22:23], off offset:128 nt
	s_waitcnt vmcnt(0)
	v_mul_f32_e32 v10, v10, v9
.LBB0_138:
	v_add_u32_e32 v9, 40, v8
	v_mad_i64_i32 v[22:23], s[54:55], v9, s38, v[6:7]
	global_load_dword v9, v[22:23], off nt
	s_and_b64 vcc, exec, s[2:3]
	s_waitcnt vmcnt(1)
	ds_write_b32 v20, v10 offset:8320
	s_cbranch_vccnz .LBB0_140
	s_ashr_i32 s21, s20, 31
	v_lshl_add_u64 v[10:11], s[20:21], 0, v[2:3]
	v_lshl_add_u64 v[10:11], v[10:11], 2, s[18:19]
	global_load_dword v10, v[10:11], off offset:160 nt
	s_waitcnt vmcnt(0)
	v_mul_f32_e32 v9, v9, v10
.LBB0_140:
	s_or_b64 exec, exec, s[24:25]
	s_waitcnt vmcnt(0)
	ds_write_b32 v20, v9 offset:10400
	s_and_saveexec_b64 s[24:25], s[4:5]
	s_xor_b64 s[4:5], exec, s[24:25]
	ds_write_b32 v20, v1 offset:12480
	s_or_saveexec_b64 s[4:5], s[4:5]
	v_mov_b32_e32 v9, 0
	s_xor_b64 exec, exec, s[4:5]
	s_cbranch_execz .LBB0_118
	v_add_u32_e32 v9, 48, v8
	v_mad_i64_i32 v[10:11], s[24:25], v9, s38, v[6:7]
	global_load_dword v10, v[10:11], off nt
	s_and_b64 vcc, exec, s[2:3]
	s_cbranch_vccnz .LBB0_145
	s_ashr_i32 s21, s20, 31
	v_lshl_add_u64 v[22:23], s[20:21], 0, v[2:3]
	v_lshl_add_u64 v[22:23], v[22:23], 2, s[18:19]
	global_load_dword v9, v[22:23], off offset:192 nt
	s_waitcnt vmcnt(0)
	v_mul_f32_e32 v10, v10, v9
.LBB0_145:
	v_add_u32_e32 v8, 56, v8
	v_mad_i64_i32 v[6:7], s[24:25], v8, s38, v[6:7]
	global_load_dword v9, v[6:7], off nt
	s_and_b64 vcc, exec, s[2:3]
	s_waitcnt vmcnt(1)
	ds_write_b32 v20, v10 offset:12480
	s_cbranch_vccnz .LBB0_118
	s_ashr_i32 s21, s20, 31
	v_lshl_add_u64 v[6:7], s[20:21], 0, v[2:3]
	v_lshl_add_u64 v[6:7], v[6:7], 2, s[18:19]
	global_load_dword v6, v[6:7], off offset:224 nt
	s_waitcnt vmcnt(0)
	v_mul_f32_e32 v9, v9, v6
	s_branch .LBB0_118

.LBB0_150:
	s_lshr_b32 s2, s50, 31
	s_add_i32 s2, s50, s2
	s_ashr_i32 s24, s2, 1
	s_lshl_b32 s53, s24, 6
	v_or_b32_e32 v6, s53, v12
	v_cmp_lt_i32_e64 s[4:5], s39, v6
	s_barrier
	s_and_saveexec_b64 s[2:3], s[4:5]
	s_xor_b64 s[2:3], exec, s[2:3]
	ds_write_b32 v20, v1
	s_or_saveexec_b64 s[20:21], s[2:3]
	s_lshl_b32 s2, s24, 7
	v_ashrrev_i32_e32 v7, 31, v6
	s_sub_i32 s54, 0, s2
	v_lshl_add_u64 v[6:7], v[6:7], 2, s[16:17]
	v_mov_b32_e32 v10, 0
	v_cmp_ne_u32_e64 s[2:3], 1, v21
	s_xor_b64 exec, exec, s[20:21]
	s_cbranch_execz .LBB0_157
	s_add_i32 s24, s54, s51
	v_add_u32_e32 v10, s24, v2
	v_ashrrev_i32_e32 v11, 31, v10
	v_lshlrev_b64 v[8:9], 13, v[10:11]
	v_lshl_add_u64 v[8:9], v[6:7], 0, v[8:9]
	global_load_dword v22, v[8:9], off nt
	s_and_b64 vcc, exec, s[2:3]
	v_lshl_add_u64 v[8:9], v[10:11], 2, s[18:19]
	s_cbranch_vccnz .LBB0_155
	global_load_dword v11, v[8:9], off nt
	s_waitcnt vmcnt(0)
	v_mul_f32_e32 v22, v22, v11
.LBB0_155:
	v_add_u32_e32 v10, 8, v10
	v_ashrrev_i32_e32 v11, 31, v10
	v_lshlrev_b64 v[10:11], 13, v[10:11]
	v_lshl_add_u64 v[10:11], v[6:7], 0, v[10:11]
	global_load_dword v10, v[10:11], off nt
	s_and_b64 vcc, exec, s[2:3]
	s_waitcnt vmcnt(1)
	ds_write_b32 v20, v22
	s_cbranch_vccnz .LBB0_157
	global_load_dword v8, v[8:9], off offset:32 nt
	s_waitcnt vmcnt(0)
	v_mul_f32_e32 v10, v10, v8
.LBB0_157:
	s_or_b64 exec, exec, s[20:21]
	s_waitcnt vmcnt(0)
	ds_write_b32 v20, v10 offset:2080
	s_and_saveexec_b64 s[20:21], s[4:5]
	s_xor_b64 s[20:21], exec, s[20:21]
	ds_write_b32 v20, v1 offset:4160
	s_or_saveexec_b64 s[24:25], s[20:21]
	s_add_i32 s20, s51, s54
	v_mov_b32_e32 v9, 0
	v_add_u32_e32 v8, s20, v2
	s_xor_b64 exec, exec, s[24:25]
	s_cbranch_execz .LBB0_164
	v_add_u32_e32 v10, 16, v8
	v_ashrrev_i32_e32 v11, 31, v10
	v_lshlrev_b64 v[10:11], 13, v[10:11]
	v_lshl_add_u64 v[10:11], v[6:7], 0, v[10:11]
	global_load_dword v10, v[10:11], off nt
	s_and_b64 vcc, exec, s[2:3]
	s_cbranch_vccnz .LBB0_162
	s_ashr_i32 s21, s20, 31
	v_lshl_add_u64 v[22:23], s[20:21], 0, v[2:3]
	v_lshl_add_u64 v[22:23], v[22:23], 2, s[18:19]
	global_load_dword v9, v[22:23], off offset:64 nt
	s_waitcnt vmcnt(0)
	v_mul_f32_e32 v10, v10, v9
.LBB0_162:
	v_add_u32_e32 v22, 24, v8
	v_ashrrev_i32_e32 v23, 31, v22
	v_lshlrev_b64 v[22:23], 13, v[22:23]
	v_lshl_add_u64 v[22:23], v[6:7], 0, v[22:23]
	global_load_dword v9, v[22:23], off nt
	s_and_b64 vcc, exec, s[2:3]
	s_waitcnt vmcnt(1)
	ds_write_b32 v20, v10 offset:4160
	s_cbranch_vccnz .LBB0_164
	s_ashr_i32 s21, s20, 31
	v_lshl_add_u64 v[10:11], s[20:21], 0, v[2:3]
	v_lshl_add_u64 v[10:11], v[10:11], 2, s[18:19]
	global_load_dword v10, v[10:11], off offset:96 nt
	s_waitcnt vmcnt(0)
	v_mul_f32_e32 v9, v9, v10
.LBB0_164:
	s_or_b64 exec, exec, s[24:25]
	s_waitcnt vmcnt(0)
	ds_write_b32 v20, v9 offset:6240
	s_and_saveexec_b64 s[24:25], s[4:5]
	s_xor_b64 s[24:25], exec, s[24:25]
	ds_write_b32 v20, v1 offset:8320
	s_or_saveexec_b64 s[24:25], s[24:25]
	v_mov_b32_e32 v9, 0
	s_xor_b64 exec, exec, s[24:25]
	s_cbranch_execz .LBB0_171
	v_add_u32_e32 v10, 32, v8
	v_ashrrev_i32_e32 v11, 31, v10
	v_lshlrev_b64 v[10:11], 13, v[10:11]
	v_lshl_add_u64 v[10:11], v[6:7], 0, v[10:11]
	global_load_dword v10, v[10:11], off nt
	s_and_b64 vcc, exec, s[2:3]
	s_cbranch_vccnz .LBB0_169
	s_ashr_i32 s21, s20, 31
	v_lshl_add_u64 v[22:23], s[20:21], 0, v[2:3]
	v_lshl_add_u64 v[22:23], v[22:23], 2, s[18:19]
	global_load_dword v9, v[22:23], off offset:128 nt
	s_waitcnt vmcnt(0)
	v_mul_f32_e32 v10, v10, v9
.LBB0_169:
	v_add_u32_e32 v22, 40, v8
	v_ashrrev_i32_e32 v23, 31, v22
	v_lshlrev_b64 v[22:23], 13, v[22:23]
	v_lshl_add_u64 v[22:23], v[6:7], 0, v[22:23]
	global_load_dword v9, v[22:23], off nt
	s_and_b64 vcc, exec, s[2:3]
	s_waitcnt vmcnt(1)
	ds_write_b32 v20, v10 offset:8320
	s_cbranch_vccnz .LBB0_171
	s_ashr_i32 s21, s20, 31
	v_lshl_add_u64 v[10:11], s[20:21], 0, v[2:3]
	v_lshl_add_u64 v[10:11], v[10:11], 2, s[18:19]
	global_load_dword v10, v[10:11], off offset:160 nt
	s_waitcnt vmcnt(0)
	v_mul_f32_e32 v9, v9, v10
.LBB0_171:
	s_or_b64 exec, exec, s[24:25]
	s_waitcnt vmcnt(0)
	ds_write_b32 v20, v9 offset:10400
	s_and_saveexec_b64 s[24:25], s[4:5]
	s_xor_b64 s[4:5], exec, s[24:25]
	ds_write_b32 v20, v1 offset:12480
	s_or_saveexec_b64 s[4:5], s[4:5]
	v_mov_b32_e32 v9, 0
	s_xor_b64 exec, exec, s[4:5]
	s_cbranch_execz .LBB0_149
	v_add_u32_e32 v10, 48, v8
	v_ashrrev_i32_e32 v11, 31, v10
	v_lshlrev_b64 v[10:11], 13, v[10:11]
	v_lshl_add_u64 v[10:11], v[6:7], 0, v[10:11]
	global_load_dword v10, v[10:11], off nt
	s_and_b64 vcc, exec, s[2:3]
	s_cbranch_vccnz .LBB0_176
	s_ashr_i32 s21, s20, 31
	v_lshl_add_u64 v[22:23], s[20:21], 0, v[2:3]
	v_lshl_add_u64 v[22:23], v[22:23], 2, s[18:19]
	global_load_dword v9, v[22:23], off offset:192 nt
	s_waitcnt vmcnt(0)
	v_mul_f32_e32 v10, v10, v9
.LBB0_176:
	v_add_u32_e32 v8, 56, v8
	v_ashrrev_i32_e32 v9, 31, v8
	v_lshlrev_b64 v[8:9], 13, v[8:9]
	v_lshl_add_u64 v[6:7], v[6:7], 0, v[8:9]
	global_load_dword v9, v[6:7], off nt
	s_and_b64 vcc, exec, s[2:3]
	s_waitcnt vmcnt(1)
	ds_write_b32 v20, v10 offset:12480
	s_cbranch_vccnz .LBB0_149
	s_ashr_i32 s21, s20, 31
	v_lshl_add_u64 v[6:7], s[20:21], 0, v[2:3]
	v_lshl_add_u64 v[6:7], v[6:7], 2, s[18:19]
	global_load_dword v6, v[6:7], off offset:224 nt
	s_waitcnt vmcnt(0)
	v_mul_f32_e32 v9, v9, v6
	s_branch .LBB0_149

.LBB0_183:
	s_or_saveexec_b64 s[4:5], s[4:5]
	s_lshl_b32 s17, s17, 10
	s_sub_i32 s17, 0, s17
	v_mov_b32_e32 v5, 0
	v_mov_b32_e32 v16, 0
	v_mov_b32_e32 v17, 0
	v_mov_b32_e32 v18, 0
	s_xor_b64 exec, exec, s[4:5]
	s_cbranch_execz .LBB0_180
	s_add_i32 s18, s17, s8
	v_add_u32_e32 v16, s18, v6
	v_ashrrev_i32_e32 v5, 31, v4
	v_ashrrev_i32_e32 v17, 31, v16
	v_lshl_add_u64 v[4:5], v[4:5], 2, s[2:3]
	v_lshlrev_b64 v[18:19], 12, v[16:17]
	v_lshl_add_u64 v[20:21], v[4:5], 0, v[18:19]
	v_add_u32_e32 v18, 8, v16
	v_ashrrev_i32_e32 v19, 31, v18
	v_lshlrev_b64 v[18:19], 12, v[18:19]
	v_lshl_add_u64 v[22:23], v[4:5], 0, v[18:19]
	v_add_u32_e32 v18, 16, v16
	v_ashrrev_i32_e32 v19, 31, v18
	v_lshlrev_b64 v[18:19], 12, v[18:19]
	v_lshl_add_u64 v[24:25], v[4:5], 0, v[18:19]
	v_add_u32_e32 v18, 24, v16
	v_ashrrev_i32_e32 v19, 31, v18
	v_lshlrev_b64 v[18:19], 12, v[18:19]
	v_lshl_add_u64 v[26:27], v[4:5], 0, v[18:19]
	v_add_u32_e32 v18, 32, v16
	v_ashrrev_i32_e32 v19, 31, v18
	v_lshlrev_b64 v[18:19], 12, v[18:19]
	v_lshl_add_u64 v[28:29], v[4:5], 0, v[18:19]
	v_add_u32_e32 v18, 40, v16
	v_ashrrev_i32_e32 v19, 31, v18
	v_lshlrev_b64 v[18:19], 12, v[18:19]
	v_lshl_add_u64 v[30:31], v[4:5], 0, v[18:19]
	v_add_u32_e32 v18, 48, v16
	v_add_u32_e32 v16, 56, v16
	v_ashrrev_i32_e32 v19, 31, v18
	v_ashrrev_i32_e32 v17, 31, v16
	v_lshlrev_b64 v[18:19], 12, v[18:19]
	v_lshlrev_b64 v[16:17], 12, v[16:17]
	v_lshl_add_u64 v[34:35], v[4:5], 0, v[18:19]
	v_lshl_add_u64 v[36:37], v[4:5], 0, v[16:17]
	global_load_dword v4, v[20:21], off nt
	global_load_dword v19, v[22:23], off nt
	global_load_dword v33, v[24:25], off nt
	global_load_dword v38, v[26:27], off nt
	global_load_dword v5, v[28:29], off nt
	global_load_dword v16, v[30:31], off nt
	global_load_dword v17, v[34:35], off nt
	global_load_dword v18, v[36:37], off nt
	s_waitcnt vmcnt(7)
	ds_write_b32 v15, v4
	s_waitcnt vmcnt(6)
	ds_write_b32 v15, v19 offset:2080
	s_waitcnt vmcnt(5)
	ds_write_b32 v15, v33 offset:4160
	s_waitcnt vmcnt(4)
	ds_write_b32 v15, v38 offset:6240
	s_branch .LBB0_180

.LBB0_190:
	s_or_saveexec_b64 s[4:5], s[4:5]
	s_lshl_b32 s12, s12, 10
	s_sub_i32 s12, 0, s12
	v_mov_b32_e32 v5, 0
	v_mov_b32_e32 v16, 0
	v_mov_b32_e32 v17, 0
	v_mov_b32_e32 v18, 0
	s_xor_b64 exec, exec, s[4:5]
	s_cbranch_execz .LBB0_187
	s_add_i32 s13, s12, s7
	v_ashrrev_i32_e32 v5, 31, v4
	v_add_u32_e32 v16, s13, v6
	v_lshl_add_u64 v[4:5], v[4:5], 2, s[2:3]
	v_add_u32_e32 v17, 8, v16
	v_mad_i64_i32 v[22:23], s[14:15], v17, s10, v[4:5]
	v_add_u32_e32 v17, 16, v16
	v_mad_i64_i32 v[24:25], s[14:15], v17, s10, v[4:5]
	v_add_u32_e32 v17, 24, v16
	v_mad_i64_i32 v[26:27], s[14:15], v17, s10, v[4:5]
	v_add_u32_e32 v17, 32, v16
	v_mad_i64_i32 v[28:29], s[14:15], v17, s10, v[4:5]
	v_add_u32_e32 v17, 40, v16
	v_mad_i64_i32 v[20:21], s[14:15], v16, s10, v[4:5]
	v_mad_i64_i32 v[30:31], s[14:15], v17, s10, v[4:5]
	v_add_u32_e32 v17, 48, v16
	v_add_u32_e32 v16, 56, v16
	v_mad_i64_i32 v[34:35], s[14:15], v17, s10, v[4:5]
	v_mad_i64_i32 v[36:37], s[14:15], v16, s10, v[4:5]
	global_load_dword v4, v[20:21], off nt
	global_load_dword v19, v[22:23], off nt
	global_load_dword v33, v[24:25], off nt
	global_load_dword v38, v[26:27], off nt
	global_load_dword v5, v[28:29], off nt
	global_load_dword v16, v[30:31], off nt
	global_load_dword v17, v[34:35], off nt
	global_load_dword v18, v[36:37], off nt
	s_waitcnt vmcnt(7)
	ds_write_b32 v15, v4
	s_waitcnt vmcnt(6)
	ds_write_b32 v15, v19 offset:2080
	s_waitcnt vmcnt(5)
	ds_write_b32 v15, v33 offset:4160
	s_waitcnt vmcnt(4)
	ds_write_b32 v15, v38 offset:6240
	s_branch .LBB0_187

.LBB0_197:
	s_or_saveexec_b64 s[4:5], s[4:5]
	s_lshl_b32 s11, s11, 10
	s_sub_i32 s11, 0, s11
	v_mov_b32_e32 v5, 0
	v_mov_b32_e32 v16, 0
	v_mov_b32_e32 v17, 0
	v_mov_b32_e32 v18, 0
	s_xor_b64 exec, exec, s[4:5]
	s_cbranch_execz .LBB0_194
	s_add_i32 s12, s11, s7
	v_add_u32_e32 v16, s12, v6
	v_ashrrev_i32_e32 v5, 31, v4
	v_ashrrev_i32_e32 v17, 31, v16
	v_lshl_add_u64 v[4:5], v[4:5], 2, s[2:3]
	v_lshlrev_b64 v[18:19], 12, v[16:17]
	v_lshl_add_u64 v[20:21], v[4:5], 0, v[18:19]
	v_add_u32_e32 v18, 8, v16
	v_ashrrev_i32_e32 v19, 31, v18
	v_lshlrev_b64 v[18:19], 12, v[18:19]
	v_lshl_add_u64 v[22:23], v[4:5], 0, v[18:19]
	v_add_u32_e32 v18, 16, v16
	v_ashrrev_i32_e32 v19, 31, v18
	v_lshlrev_b64 v[18:19], 12, v[18:19]
	v_lshl_add_u64 v[24:25], v[4:5], 0, v[18:19]
	v_add_u32_e32 v18, 24, v16
	v_ashrrev_i32_e32 v19, 31, v18
	v_lshlrev_b64 v[18:19], 12, v[18:19]
	v_lshl_add_u64 v[26:27], v[4:5], 0, v[18:19]
	v_add_u32_e32 v18, 32, v16
	v_ashrrev_i32_e32 v19, 31, v18
	v_lshlrev_b64 v[18:19], 12, v[18:19]
	v_lshl_add_u64 v[28:29], v[4:5], 0, v[18:19]
	v_add_u32_e32 v18, 40, v16
	v_ashrrev_i32_e32 v19, 31, v18
	v_lshlrev_b64 v[18:19], 12, v[18:19]
	v_lshl_add_u64 v[30:31], v[4:5], 0, v[18:19]
	v_add_u32_e32 v18, 48, v16
	v_add_u32_e32 v16, 56, v16
	v_ashrrev_i32_e32 v19, 31, v18
	v_ashrrev_i32_e32 v17, 31, v16
	v_lshlrev_b64 v[18:19], 12, v[18:19]
	v_lshlrev_b64 v[16:17], 12, v[16:17]
	v_lshl_add_u64 v[34:35], v[4:5], 0, v[18:19]
	v_lshl_add_u64 v[36:37], v[4:5], 0, v[16:17]
	global_load_dword v4, v[20:21], off nt
	global_load_dword v19, v[22:23], off nt
	global_load_dword v33, v[24:25], off nt
	global_load_dword v38, v[26:27], off nt
	global_load_dword v5, v[28:29], off nt
	global_load_dword v16, v[30:31], off nt
	global_load_dword v17, v[34:35], off nt
	global_load_dword v18, v[36:37], off nt
	s_waitcnt vmcnt(7)
	ds_write_b32 v15, v4
	s_waitcnt vmcnt(6)
	ds_write_b32 v15, v19 offset:2080
	s_waitcnt vmcnt(5)
	ds_write_b32 v15, v33 offset:4160
	s_waitcnt vmcnt(4)
	ds_write_b32 v15, v38 offset:6240
	s_branch .LBB0_194

.LBB0_204:
	s_or_saveexec_b64 s[4:5], s[4:5]
	s_lshl_b32 s14, s14, 10
	s_sub_i32 s14, 0, s14
	v_mov_b32_e32 v15, 0
	v_mov_b32_e32 v16, 0
	v_mov_b32_e32 v17, 0
	v_mov_b32_e32 v18, 0
	s_xor_b64 exec, exec, s[4:5]
	s_cbranch_execz .LBB0_201
	v_cmp_gt_i32_e32 vcc, s10, v19
	s_add_i32 s15, s14, s7
	s_nop 0
	v_cndmask_b32_e64 v15, v14, 48, vcc
	v_cmp_lt_i32_e32 vcc, s11, v19
	s_nop 1
	v_cndmask_b32_e32 v15, 0, v15, vcc
	v_add_u32_e32 v16, v15, v19
	v_ashrrev_i32_e32 v17, 31, v16
	v_add_u32_e32 v15, s15, v4
	v_lshl_add_u64 v[16:17], v[16:17], 2, s[2:3]
	v_add_u32_e32 v18, 8, v15
	v_mad_i64_i32 v[22:23], s[16:17], v18, s12, v[16:17]
	v_add_u32_e32 v18, 16, v15
	v_mad_i64_i32 v[24:25], s[16:17], v18, s12, v[16:17]
	v_add_u32_e32 v18, 24, v15
	v_mad_i64_i32 v[26:27], s[16:17], v18, s12, v[16:17]
	v_add_u32_e32 v18, 32, v15
	v_mad_i64_i32 v[28:29], s[16:17], v18, s12, v[16:17]
	v_add_u32_e32 v18, 40, v15
	v_mad_i64_i32 v[20:21], s[16:17], v15, s12, v[16:17]
	v_mad_i64_i32 v[30:31], s[16:17], v18, s12, v[16:17]
	v_add_u32_e32 v18, 48, v15
	v_add_u32_e32 v15, 56, v15
	v_mad_i64_i32 v[34:35], s[16:17], v18, s12, v[16:17]
	v_mad_i64_i32 v[36:37], s[16:17], v15, s12, v[16:17]
	global_load_dword v19, v[20:21], off nt
	global_load_dword v33, v[22:23], off nt
	global_load_dword v38, v[24:25], off nt
	global_load_dword v39, v[26:27], off nt
	global_load_dword v15, v[28:29], off nt
	global_load_dword v16, v[30:31], off nt
	global_load_dword v17, v[34:35], off nt
	global_load_dword v18, v[36:37], off nt
	s_waitcnt vmcnt(7)
	ds_write_b32 v13, v19
	s_waitcnt vmcnt(6)
	ds_write_b32 v13, v33 offset:2080
	s_waitcnt vmcnt(5)
	ds_write_b32 v13, v38 offset:4160
	s_waitcnt vmcnt(4)
	ds_write_b32 v13, v39 offset:6240
	s_branch .LBB0_201

.LBB0_211:
	s_or_saveexec_b64 s[4:5], s[4:5]
	s_lshl_b32 s11, s11, 11
	s_sub_i32 s11, 0, s11
	v_mov_b32_e32 v5, 0
	v_mov_b32_e32 v16, 0
	v_mov_b32_e32 v17, 0
	v_mov_b32_e32 v18, 0
	s_xor_b64 exec, exec, s[4:5]
	s_cbranch_execz .LBB0_208
	s_add_i32 s12, s11, s8
	v_add_u32_e32 v16, s12, v6
	v_ashrrev_i32_e32 v5, 31, v4
	v_ashrrev_i32_e32 v17, 31, v16
	v_lshl_add_u64 v[4:5], v[4:5], 2, s[2:3]
	v_lshlrev_b64 v[18:19], 9, v[16:17]
	v_lshl_add_u64 v[20:21], v[4:5], 0, v[18:19]
	v_add_u32_e32 v18, 8, v16
	v_ashrrev_i32_e32 v19, 31, v18
	v_lshlrev_b64 v[18:19], 9, v[18:19]
	v_lshl_add_u64 v[22:23], v[4:5], 0, v[18:19]
	v_add_u32_e32 v18, 16, v16
	v_ashrrev_i32_e32 v19, 31, v18
	v_lshlrev_b64 v[18:19], 9, v[18:19]
	v_lshl_add_u64 v[24:25], v[4:5], 0, v[18:19]
	v_add_u32_e32 v18, 24, v16
	v_ashrrev_i32_e32 v19, 31, v18
	v_lshlrev_b64 v[18:19], 9, v[18:19]
	v_lshl_add_u64 v[26:27], v[4:5], 0, v[18:19]
	v_add_u32_e32 v18, 32, v16
	v_ashrrev_i32_e32 v19, 31, v18
	v_lshlrev_b64 v[18:19], 9, v[18:19]
	v_lshl_add_u64 v[28:29], v[4:5], 0, v[18:19]
	v_add_u32_e32 v18, 40, v16
	v_ashrrev_i32_e32 v19, 31, v18
	v_lshlrev_b64 v[18:19], 9, v[18:19]
	v_lshl_add_u64 v[30:31], v[4:5], 0, v[18:19]
	v_add_u32_e32 v18, 48, v16
	v_add_u32_e32 v16, 56, v16
	v_ashrrev_i32_e32 v19, 31, v18
	v_ashrrev_i32_e32 v17, 31, v16
	v_lshlrev_b64 v[18:19], 9, v[18:19]
	v_lshlrev_b64 v[16:17], 9, v[16:17]
	v_lshl_add_u64 v[34:35], v[4:5], 0, v[18:19]
	v_lshl_add_u64 v[36:37], v[4:5], 0, v[16:17]
	global_load_dword v4, v[20:21], off nt
	global_load_dword v19, v[22:23], off nt
	global_load_dword v33, v[24:25], off nt
	global_load_dword v38, v[26:27], off nt
	global_load_dword v5, v[28:29], off nt
	global_load_dword v16, v[30:31], off nt
	global_load_dword v17, v[34:35], off nt
	global_load_dword v18, v[36:37], off nt
	s_waitcnt vmcnt(7)
	ds_write_b32 v15, v4
	s_waitcnt vmcnt(6)
	ds_write_b32 v15, v19 offset:2080
	s_waitcnt vmcnt(5)
	ds_write_b32 v15, v33 offset:4160
	s_waitcnt vmcnt(4)
	ds_write_b32 v15, v38 offset:6240
	s_branch .LBB0_208

.LBB0_218:
	s_or_saveexec_b64 s[4:5], s[4:5]
	s_lshl_b32 s10, s10, 7
	s_sub_i32 s10, 0, s10
	v_mov_b32_e32 v5, 0
	v_mov_b32_e32 v16, 0
	v_mov_b32_e32 v17, 0
	v_mov_b32_e32 v18, 0
	s_xor_b64 exec, exec, s[4:5]
	s_cbranch_execz .LBB0_215
	s_add_i32 s11, s10, s7
	v_add_u32_e32 v16, s11, v6
	v_ashrrev_i32_e32 v5, 31, v4
	v_ashrrev_i32_e32 v17, 31, v16
	v_lshl_add_u64 v[4:5], v[4:5], 2, s[2:3]
	v_lshlrev_b64 v[18:19], 8, v[16:17]
	v_lshl_add_u64 v[20:21], v[4:5], 0, v[18:19]
	v_add_u32_e32 v18, 8, v16
	v_ashrrev_i32_e32 v19, 31, v18
	v_lshlrev_b64 v[18:19], 8, v[18:19]
	v_lshl_add_u64 v[22:23], v[4:5], 0, v[18:19]
	v_add_u32_e32 v18, 16, v16
	v_ashrrev_i32_e32 v19, 31, v18
	v_lshlrev_b64 v[18:19], 8, v[18:19]
	v_lshl_add_u64 v[24:25], v[4:5], 0, v[18:19]
	v_add_u32_e32 v18, 24, v16
	v_ashrrev_i32_e32 v19, 31, v18
	v_lshlrev_b64 v[18:19], 8, v[18:19]
	v_lshl_add_u64 v[26:27], v[4:5], 0, v[18:19]
	v_add_u32_e32 v18, 32, v16
	v_ashrrev_i32_e32 v19, 31, v18
	v_lshlrev_b64 v[18:19], 8, v[18:19]
	v_lshl_add_u64 v[28:29], v[4:5], 0, v[18:19]
	v_add_u32_e32 v18, 40, v16
	v_ashrrev_i32_e32 v19, 31, v18
	v_lshlrev_b64 v[18:19], 8, v[18:19]
	v_lshl_add_u64 v[30:31], v[4:5], 0, v[18:19]
	v_add_u32_e32 v18, 48, v16
	v_add_u32_e32 v16, 56, v16
	v_ashrrev_i32_e32 v19, 31, v18
	v_ashrrev_i32_e32 v17, 31, v16
	v_lshlrev_b64 v[18:19], 8, v[18:19]
	v_lshlrev_b64 v[16:17], 8, v[16:17]
	v_lshl_add_u64 v[34:35], v[4:5], 0, v[18:19]
	v_lshl_add_u64 v[36:37], v[4:5], 0, v[16:17]
	global_load_dword v4, v[20:21], off nt
	global_load_dword v19, v[22:23], off nt
	global_load_dword v33, v[24:25], off nt
	global_load_dword v38, v[26:27], off nt
	global_load_dword v5, v[28:29], off nt
	global_load_dword v16, v[30:31], off nt
	global_load_dword v17, v[34:35], off nt
	global_load_dword v18, v[36:37], off nt
	s_waitcnt vmcnt(7)
	ds_write_b32 v15, v4
	s_waitcnt vmcnt(6)
	ds_write_b32 v15, v19 offset:2080
	s_waitcnt vmcnt(5)
	ds_write_b32 v15, v33 offset:4160
	s_waitcnt vmcnt(4)
	ds_write_b32 v15, v38 offset:6240
	s_branch .LBB0_215

.LBB0_1279:
	ds_read_b128 v[128:131], v238
	ds_read_b128 v[136:139], v253
	ds_read_b128 v[132:135], v238 offset:4096
	ds_read_b128 v[140:143], v253 offset:4096
	ds_read_b128 v[144:147], v253 offset:8192
	ds_read_b128 v[148:151], v253 offset:12288
	s_waitcnt lgkmcnt(6)
	v_mfma_f32_32x32x16_bf16 v[112:127], v[188:191], v[196:199], v[112:127]
	v_mfma_f32_32x32x16_bf16 v[48:63], v[192:195], v[196:199], v[48:63]
	v_mfma_f32_32x32x16_bf16 v[96:111], v[188:191], v[200:203], v[96:111]
	v_mfma_f32_32x32x16_bf16 v[32:47], v[192:195], v[200:203], v[32:47]
	v_mfma_f32_32x32x16_bf16 v[80:95], v[188:191], v[204:207], v[80:95]
	v_mfma_f32_32x32x16_bf16 v[16:31], v[192:195], v[204:207], v[16:31]
	v_mfma_f32_32x32x16_bf16 v[64:79], v[188:191], v[226:229], v[64:79]
	v_mfma_f32_32x32x16_bf16 v[0:15], v[192:195], v[226:229], v[0:15]
	ds_read_b128 v[188:191], v239
	ds_read_b128 v[196:199], v254
	ds_read_b128 v[192:195], v239 offset:4096
	ds_read_b128 v[200:203], v254 offset:4096
	ds_read_b128 v[204:207], v254 offset:8192
	ds_read_b128 v[226:229], v254 offset:12288
	s_waitcnt lgkmcnt(6)
	v_mfma_f32_32x32x16_bf16 v[112:127], v[128:131], v[136:139], v[112:127]
	v_mfma_f32_32x32x16_bf16 v[48:63], v[132:135], v[136:139], v[48:63]
	v_mfma_f32_32x32x16_bf16 v[96:111], v[128:131], v[140:143], v[96:111]
	v_mfma_f32_32x32x16_bf16 v[32:47], v[132:135], v[140:143], v[32:47]
	v_mfma_f32_32x32x16_bf16 v[80:95], v[128:131], v[144:147], v[80:95]
	v_mfma_f32_32x32x16_bf16 v[16:31], v[132:135], v[144:147], v[16:31]
	v_mfma_f32_32x32x16_bf16 v[64:79], v[128:131], v[148:151], v[64:79]
	v_mfma_f32_32x32x16_bf16 v[0:15], v[132:135], v[148:151], v[0:15]
	ds_read_b128 v[128:131], v240
	ds_read_b128 v[136:139], v255
	ds_read_b128 v[132:135], v240 offset:4096
	ds_read_b128 v[140:143], v255 offset:4096
	ds_read_b128 v[144:147], v255 offset:8192
	ds_read_b128 v[148:151], v255 offset:12288
	s_waitcnt lgkmcnt(6)
	v_mfma_f32_32x32x16_bf16 v[112:127], v[188:191], v[196:199], v[112:127]
	v_mfma_f32_32x32x16_bf16 v[48:63], v[192:195], v[196:199], v[48:63]
	v_mfma_f32_32x32x16_bf16 v[96:111], v[188:191], v[200:203], v[96:111]
	v_mfma_f32_32x32x16_bf16 v[32:47], v[192:195], v[200:203], v[32:47]
	v_mfma_f32_32x32x16_bf16 v[80:95], v[188:191], v[204:207], v[80:95]
	v_mfma_f32_32x32x16_bf16 v[16:31], v[192:195], v[204:207], v[16:31]
	v_mfma_f32_32x32x16_bf16 v[64:79], v[188:191], v[226:229], v[64:79]
	v_mfma_f32_32x32x16_bf16 v[0:15], v[192:195], v[226:229], v[0:15]
	s_waitcnt vmcnt(0) lgkmcnt(0)
	s_barrier
	v_mfma_f32_32x32x16_bf16 v[112:127], v[128:131], v[136:139], v[112:127]
	v_mfma_f32_32x32x16_bf16 v[48:63], v[132:135], v[136:139], v[48:63]
	v_mfma_f32_32x32x16_bf16 v[96:111], v[128:131], v[140:143], v[96:111]
	v_mfma_f32_32x32x16_bf16 v[32:47], v[132:135], v[140:143], v[32:47]
	v_mfma_f32_32x32x16_bf16 v[80:95], v[128:131], v[144:147], v[80:95]
	v_mfma_f32_32x32x16_bf16 v[16:31], v[132:135], v[144:147], v[16:31]
	v_mfma_f32_32x32x16_bf16 v[64:79], v[128:131], v[148:151], v[64:79]
	v_mfma_f32_32x32x16_bf16 v[0:15], v[132:135], v[148:151], v[0:15]
	s_lshl_b32 s2, s5, 8
	s_sub_i32 s2, s2, s6
	v_mov_b32_e32 v168, v214
	s_add_i32 s55, s4, s30
	s_or_b32 s26, s2, s31
	s_ashr_i32 s27, s26, 31
	s_load_dwordx2 s[24:25], s[0:1], 0x140
	v_ashrrev_i32_e32 v180, 3, v168
	v_and_b32_e32 v183, -4, v180
	v_add_u32_e32 v225, s55, v183
	v_add_u32_e32 v190, 8, v225
	v_min_i32_e32 v190, 0x7fff, v190
	v_ashrrev_i32_e32 v190, 12, v190
	v_min_i32_e32 v184, 0x7fff, v225
	v_and_b32_e32 v182, 31, v168
	v_ashrrev_i32_e32 v184, 12, v184
	v_or_b32_e32 v180, s26, v182
	v_mul_hi_i32_i24_e32 v185, 0x3000, v184
	v_mul_i32_i24_e32 v184, 0x3000, v184
	v_ashrrev_i32_e32 v181, 31, v180
	s_waitcnt lgkmcnt(0)
	v_lshl_add_u64 v[184:185], s[24:25], 0, v[184:185]
	v_add_u32_e32 v188, 9, v225
	v_mul_hi_i32_i24_e32 v187, 0x3000, v190
	v_mul_i32_i24_e32 v186, 0x3000, v190
	v_min_i32_e32 v188, 0x7fff, v188
	v_add_u32_e32 v190, 10, v225
	v_ashrrev_i32_e32 v188, 12, v188
	v_min_i32_e32 v190, 0x7fff, v190
	v_mul_hi_i32_i24_e32 v189, 0x3000, v188
	v_mul_i32_i24_e32 v188, 0x3000, v188
	v_ashrrev_i32_e32 v190, 12, v190
	v_lshl_add_u64 v[188:189], s[24:25], 0, v[188:189]
	v_mul_hi_i32_i24_e32 v191, 0x3000, v190
	v_mul_i32_i24_e32 v190, 0x3000, v190
	v_lshl_add_u64 v[184:185], v[184:185], 0, s[18:19]
	v_lshlrev_b64 v[180:181], 2, v[180:181]
	v_lshl_add_u64 v[186:187], s[24:25], 0, v[186:187]
	v_lshl_add_u64 v[188:189], v[188:189], 0, s[18:19]
	v_lshl_add_u64 v[190:191], s[24:25], 0, v[190:191]
	v_lshl_add_u64 v[208:209], v[184:185], 0, v[180:181]
	v_lshl_add_u64 v[186:187], v[186:187], 0, s[18:19]
	v_lshl_add_u64 v[190:191], v[190:191], 0, s[18:19]
	v_lshl_add_u64 v[230:231], v[186:187], 0, v[180:181]
	v_lshl_add_u64 v[196:197], v[188:189], 0, v[180:181]
	v_lshl_add_u64 v[198:199], v[190:191], 0, v[180:181]
	global_load_dword v232, v[208:209], off
	global_load_dword v233, v[208:209], off offset:128
	global_load_dword v238, v[230:231], off
	global_load_dword v239, v[230:231], off offset:128
	global_load_dword v240, v[196:197], off
	global_load_dword v241, v[196:197], off offset:128
	global_load_dword v242, v[198:199], off
	global_load_dword v243, v[198:199], off offset:128
	v_add_u32_e32 v196, 17, v225
	v_min_i32_e32 v196, 0x7fff, v196
	v_add_u32_e32 v198, 18, v225
	v_ashrrev_i32_e32 v196, 12, v196
	v_min_i32_e32 v198, 0x7fff, v198
	v_mul_hi_i32_i24_e32 v197, 0x3000, v196
	v_mul_i32_i24_e32 v196, 0x3000, v196
	v_ashrrev_i32_e32 v198, 12, v198
	v_lshl_add_u64 v[196:197], s[24:25], 0, v[196:197]
	v_mul_hi_i32_i24_e32 v199, 0x3000, v198
	v_mul_i32_i24_e32 v198, 0x3000, v198
	v_add_u32_e32 v192, 11, v225
	v_add_u32_e32 v194, 16, v225
	v_min_i32_e32 v192, 0x7fff, v192
	v_min_i32_e32 v194, 0x7fff, v194
	v_ashrrev_i32_e32 v192, 12, v192
	v_ashrrev_i32_e32 v194, 12, v194
	v_mul_hi_i32_i24_e32 v193, 0x3000, v192
	v_mul_i32_i24_e32 v192, 0x3000, v192
	v_mul_hi_i32_i24_e32 v195, 0x3000, v194
	v_mul_i32_i24_e32 v194, 0x3000, v194
	v_lshl_add_u64 v[192:193], s[24:25], 0, v[192:193]
	v_lshl_add_u64 v[194:195], s[24:25], 0, v[194:195]
	v_lshl_add_u64 v[192:193], v[192:193], 0, s[18:19]
	v_lshl_add_u64 v[194:195], v[194:195], 0, s[18:19]
	v_lshl_add_u64 v[196:197], v[196:197], 0, s[18:19]
	v_lshl_add_u64 v[198:199], s[24:25], 0, v[198:199]
	v_lshl_add_u64 v[208:209], v[192:193], 0, v[180:181]
	v_lshl_add_u64 v[198:199], v[198:199], 0, s[18:19]
	v_lshl_add_u64 v[226:227], v[198:199], 0, v[180:181]
	s_waitcnt vmcnt(7)
	v_mul_f32_e32 v112, v112, v232
	v_lshl_add_u64 v[204:205], v[194:195], 0, v[180:181]
	v_lshl_add_u64 v[206:207], v[196:197], 0, v[180:181]
	s_waitcnt vmcnt(6)
	s_nop 2
	v_mul_f32_e32 v96, v96, v233
	v_mul_f32_e32 v97, v97, v233
	global_load_dword v234, v[208:209], off
	global_load_dword v235, v[208:209], off offset:128
	global_load_dword v236, v[204:205], off
	global_load_dword v237, v[204:205], off offset:128
	global_load_dword v244, v[206:207], off
	global_load_dword v245, v[206:207], off offset:128
	global_load_dword v246, v[226:227], off
	global_load_dword v247, v[226:227], off offset:128
	v_add_u32_e32 v204, 25, v225
	v_add_u32_e32 v206, 26, v225
	v_min_i32_e32 v204, 0x7fff, v204
	v_min_i32_e32 v206, 0x7fff, v206
	v_ashrrev_i32_e32 v204, 12, v204
	v_ashrrev_i32_e32 v206, 12, v206
	v_add_u32_e32 v200, 19, v225
	v_min_i32_e32 v200, 0x7fff, v200
	v_add_u32_e32 v202, 24, v225
	v_ashrrev_i32_e32 v200, 12, v200
	v_min_i32_e32 v202, 0x7fff, v202
	v_mul_hi_i32_i24_e32 v201, 0x3000, v200
	v_mul_i32_i24_e32 v200, 0x3000, v200
	v_ashrrev_i32_e32 v202, 12, v202
	v_mul_hi_i32_i24_e32 v205, 0x3000, v204
	v_mul_i32_i24_e32 v204, 0x3000, v204
	v_mul_hi_i32_i24_e32 v207, 0x3000, v206
	v_mul_i32_i24_e32 v206, 0x3000, v206
	v_lshl_add_u64 v[200:201], s[24:25], 0, v[200:201]
	v_mul_hi_i32_i24_e32 v203, 0x3000, v202
	v_mul_i32_i24_e32 v202, 0x3000, v202
	v_lshl_add_u64 v[204:205], s[24:25], 0, v[204:205]
	v_lshl_add_u64 v[206:207], s[24:25], 0, v[206:207]
	v_lshl_add_u64 v[200:201], v[200:201], 0, s[18:19]
	v_lshl_add_u64 v[202:203], s[24:25], 0, v[202:203]
	v_lshl_add_u64 v[204:205], v[204:205], 0, s[18:19]
	v_lshl_add_u64 v[206:207], v[206:207], 0, s[18:19]
	v_lshl_add_u64 v[208:209], v[200:201], 0, v[180:181]
	v_lshl_add_u64 v[202:203], v[202:203], 0, s[18:19]
	v_lshl_add_u64 v[228:229], v[204:205], 0, v[180:181]
	v_lshl_add_u64 v[230:231], v[206:207], 0, v[180:181]
	v_lshl_add_u64 v[226:227], v[202:203], 0, v[180:181]
	global_load_dword v248, v[208:209], off
	global_load_dword v249, v[208:209], off offset:128
	global_load_dword v250, v[226:227], off
	global_load_dword v251, v[226:227], off offset:128
	global_load_dword v252, v[228:229], off
	s_nop 0
	global_load_dword v228, v[228:229], off offset:128
	s_nop 0
	global_load_dword v229, v[230:231], off
	s_nop 0
	global_load_dword v230, v[230:231], off offset:128
	v_add_u32_e32 v208, 27, v225
	v_min_i32_e32 v208, 0x7fff, v208
	v_ashrrev_i32_e32 v208, 12, v208
	v_mul_hi_i32_i24_e32 v209, 0x3000, v208
	v_mul_i32_i24_e32 v208, 0x3000, v208
	v_lshl_add_u64 v[208:209], s[24:25], 0, v[208:209]
	v_lshl_add_u64 v[208:209], v[208:209], 0, s[18:19]
	v_lshl_add_u64 v[226:227], v[208:209], 0, v[180:181]
	global_load_dword v225, v[226:227], off
	s_nop 0
	global_load_dword v226, v[226:227], off offset:128
	v_mad_u64_u32 v[160:161], s[2:3], v183, s36, v[182:183]
	v_lshl_add_u32 v162, v160, 2, s34
	ds_write2_b32 v162, v112, v96 offset1:32
	v_mul_f32_e32 v96, v113, v232
	ds_write2_b32 v162, v96, v97 offset0:68 offset1:100
	v_mul_f32_e32 v96, v114, v232
	v_mul_f32_e32 v97, v98, v233
	ds_write2_b32 v162, v96, v97 offset0:136 offset1:168
	v_mul_f32_e32 v96, v115, v232
	v_mul_f32_e32 v97, v99, v233
	ds_write2_b32 v162, v96, v97 offset0:204 offset1:236
	s_waitcnt vmcnt(23)
	v_mul_f32_e32 v96, v116, v238
	s_waitcnt vmcnt(22)
	v_mul_f32_e32 v97, v100, v239
	v_add_u32_e32 v115, 0x800, v162
	ds_write2_b32 v115, v96, v97 offset0:32 offset1:64
	s_waitcnt vmcnt(21)
	v_mul_f32_e32 v96, v117, v240
	s_waitcnt vmcnt(20)
	v_mul_f32_e32 v97, v101, v241
	ds_write2_b32 v115, v96, v97 offset0:100 offset1:132
	s_waitcnt vmcnt(19)
	v_mul_f32_e32 v96, v118, v242
	s_waitcnt vmcnt(18)
	v_mul_f32_e32 v97, v102, v243
	ds_write2_b32 v115, v96, v97 offset0:168 offset1:200
	v_add_u32_e32 v116, 0xa00, v162
	v_add_u32_e32 v117, 0x1000, v162
	v_add_u32_e32 v118, 0x1400, v162
	v_ashrrev_i32_e32 v163, 4, v168
	v_and_b32_e32 v160, 15, v168
	v_mul_lo_u32 v161, v163, s37
	s_waitcnt vmcnt(17)
	v_mul_f32_e32 v96, v119, v234
	s_waitcnt vmcnt(16)
	v_mul_f32_e32 v97, v103, v235
	ds_write2_b32 v116, v96, v97 offset0:108 offset1:140
	s_waitcnt vmcnt(15)
	v_mul_f32_e32 v96, v120, v236
	s_waitcnt vmcnt(14)
	v_mul_f32_e32 v97, v104, v237
	ds_write2_b32 v117, v96, v97 offset0:64 offset1:96
	s_waitcnt vmcnt(13)
	v_mul_f32_e32 v96, v121, v244
	s_waitcnt vmcnt(12)
	v_mul_f32_e32 v97, v105, v245
	ds_write2_b32 v117, v96, v97 offset0:132 offset1:164
	s_waitcnt vmcnt(11)
	v_mul_f32_e32 v96, v122, v246
	s_waitcnt vmcnt(10)
	v_mul_f32_e32 v97, v106, v247
	ds_write2_b32 v117, v96, v97 offset0:200 offset1:232
	v_add_u32_e32 v119, 0x1800, v162
	v_add_u32_e32 v120, 0x1a00, v162
	v_lshl_add_u32 v164, v160, 4, s34
	v_lshlrev_b32_e32 v168, 2, v160
	v_add_u32_e32 v160, s55, v163
	v_add_u32_e32 v121, 0x1c00, v162
	v_cmp_gt_i32_e32 vcc, s38, v160
	v_add_u32_e32 v114, v164, v161
	v_ashrrev_i32_e32 v161, 31, v160
	s_waitcnt vmcnt(9)
	v_mul_f32_e32 v96, v123, v248
	s_waitcnt vmcnt(8)
	v_mul_f32_e32 v97, v107, v249
	ds_write2_b32 v118, v96, v97 offset0:12 offset1:44
	s_waitcnt vmcnt(7)
	v_mul_f32_e32 v96, v124, v250
	s_waitcnt vmcnt(6)
	v_mul_f32_e32 v97, v108, v251
	ds_write2_b32 v119, v96, v97 offset0:96 offset1:128
	s_waitcnt vmcnt(5)
	v_mul_f32_e32 v96, v125, v252
	s_waitcnt vmcnt(4)
	v_mul_f32_e32 v97, v109, v228
	ds_write2_b32 v119, v96, v97 offset0:164 offset1:196
	s_waitcnt vmcnt(3)
	v_mul_f32_e32 v96, v126, v229
	s_waitcnt vmcnt(2)
	v_mul_f32_e32 v97, v110, v230
	ds_write2_b32 v120, v96, v97 offset0:104 offset1:136
	s_waitcnt vmcnt(1)
	v_mul_f32_e32 v96, v127, v225
	s_waitcnt vmcnt(0)
	v_mul_f32_e32 v97, v111, v226
	ds_write2_b32 v121, v96, v97 offset0:44 offset1:76
	v_or_b32_e32 v96, s26, v168
	v_mov_b32_e32 v97, s27
	v_add_u32_e32 v128, 0, v160
	v_ashrrev_i32_e32 v129, 31, v128
	v_lshlrev_b64 v[128:129], 10, v[128:129]
	v_lshl_add_u64 v[128:129], v[128:129], 0, v[96:97]
	v_lshlrev_b64 v[128:129], 2, v[128:129]
	v_lshl_add_u64 v[128:129], s[16:17], 0, v[128:129]
	global_load_dwordx4 v[128:131], v[128:129], off nt
	v_add_u32_e32 v132, 4, v160
	v_ashrrev_i32_e32 v133, 31, v132
	v_lshlrev_b64 v[132:133], 10, v[132:133]
	v_lshl_add_u64 v[132:133], v[132:133], 0, v[96:97]
	v_lshlrev_b64 v[132:133], 2, v[132:133]
	v_lshl_add_u64 v[132:133], s[16:17], 0, v[132:133]
	global_load_dwordx4 v[132:135], v[132:133], off nt
	v_add_u32_e32 v136, 8, v160
	v_ashrrev_i32_e32 v137, 31, v136
	v_lshlrev_b64 v[136:137], 10, v[136:137]
	v_lshl_add_u64 v[136:137], v[136:137], 0, v[96:97]
	v_lshlrev_b64 v[136:137], 2, v[136:137]
	v_lshl_add_u64 v[136:137], s[16:17], 0, v[136:137]
	global_load_dwordx4 v[136:139], v[136:137], off nt
	v_add_u32_e32 v140, 12, v160
	v_ashrrev_i32_e32 v141, 31, v140
	v_lshlrev_b64 v[140:141], 10, v[140:141]
	v_lshl_add_u64 v[140:141], v[140:141], 0, v[96:97]
	v_lshlrev_b64 v[140:141], 2, v[140:141]
	v_lshl_add_u64 v[140:141], s[16:17], 0, v[140:141]
	global_load_dwordx4 v[140:143], v[140:141], off nt
	v_add_u32_e32 v144, 16, v160
	v_ashrrev_i32_e32 v145, 31, v144
	v_lshlrev_b64 v[144:145], 10, v[144:145]
	v_lshl_add_u64 v[144:145], v[144:145], 0, v[96:97]
	v_lshlrev_b64 v[144:145], 2, v[144:145]
	v_lshl_add_u64 v[144:145], s[16:17], 0, v[144:145]
	global_load_dwordx4 v[144:147], v[144:145], off nt
	v_add_u32_e32 v148, 20, v160
	v_ashrrev_i32_e32 v149, 31, v148
	v_lshlrev_b64 v[148:149], 10, v[148:149]
	v_lshl_add_u64 v[148:149], v[148:149], 0, v[96:97]
	v_lshlrev_b64 v[148:149], 2, v[148:149]
	v_lshl_add_u64 v[148:149], s[16:17], 0, v[148:149]
	global_load_dwordx4 v[148:151], v[148:149], off nt
	v_add_u32_e32 v152, 24, v160
	v_ashrrev_i32_e32 v153, 31, v152
	v_lshlrev_b64 v[152:153], 10, v[152:153]
	v_lshl_add_u64 v[152:153], v[152:153], 0, v[96:97]
	v_lshlrev_b64 v[152:153], 2, v[152:153]
	v_lshl_add_u64 v[152:153], s[16:17], 0, v[152:153]
	global_load_dwordx4 v[152:155], v[152:153], off nt
	v_add_u32_e32 v156, 28, v160
	v_ashrrev_i32_e32 v157, 31, v156
	v_lshlrev_b64 v[156:157], 10, v[156:157]
	v_lshl_add_u64 v[156:157], v[156:157], 0, v[96:97]
	v_lshlrev_b64 v[156:157], 2, v[156:157]
	v_lshl_add_u64 v[156:157], s[16:17], 0, v[156:157]
	global_load_dwordx4 v[156:159], v[156:157], off nt
	s_and_saveexec_b64 s[2:3], vcc
	s_cbranch_execz .LBB0_1281
	v_lshlrev_b64 v[98:99], 10, v[160:161]
	v_lshl_add_u64 v[98:99], v[98:99], 0, v[96:97]
	v_lshlrev_b64 v[106:107], 2, v[98:99]
	v_lshl_add_u64 v[98:99], s[16:17], 0, v[106:107]
	ds_read_b128 v[102:105], v114
	s_load_dwordx2 s[4:5], s[0:1], 0xb8
	s_waitcnt vmcnt(7) lgkmcnt(0)
	v_pk_add_f32 v[100:101], v[104:105], v[130:131]
	v_pk_add_f32 v[98:99], v[102:103], v[128:129]
	v_lshl_add_u64 v[102:103], s[4:5], 0, v[106:107]
	global_store_dwordx4 v[102:103], v[98:101], off

.LBB0_1295:
	s_or_b64 exec, exec, s[28:29]
	v_add3_u32 v98, v182, s26, 64
	v_ashrrev_i32_e32 v99, 31, v98
	v_lshlrev_b64 v[98:99], 2, v[98:99]
	v_lshl_add_u64 v[122:123], v[184:185], 0, v[98:99]
	v_lshl_add_u64 v[124:125], v[186:187], 0, v[98:99]
	v_lshl_add_u64 v[126:127], v[188:189], 0, v[98:99]
	v_lshl_add_u64 v[164:165], v[190:191], 0, v[98:99]
	global_load_dword v166, v[122:123], off
	global_load_dword v167, v[122:123], off offset:128
	global_load_dword v182, v[124:125], off
	global_load_dword v184, v[124:125], off offset:128
	global_load_dword v185, v[126:127], off
	global_load_dword v186, v[126:127], off offset:128
	global_load_dword v187, v[164:165], off
	global_load_dword v188, v[164:165], off offset:128
	v_lshl_add_u64 v[122:123], v[192:193], 0, v[98:99]
	v_lshl_add_u64 v[124:125], v[194:195], 0, v[98:99]
	v_lshl_add_u64 v[126:127], v[196:197], 0, v[98:99]
	v_lshl_add_u64 v[164:165], v[198:199], 0, v[98:99]
	global_load_dword v189, v[122:123], off
	global_load_dword v190, v[122:123], off offset:128
	global_load_dword v191, v[124:125], off
	global_load_dword v192, v[124:125], off offset:128
	global_load_dword v193, v[126:127], off
	global_load_dword v194, v[126:127], off offset:128
	global_load_dword v195, v[164:165], off
	global_load_dword v196, v[164:165], off offset:128
	v_lshl_add_u64 v[122:123], v[200:201], 0, v[98:99]
	v_lshl_add_u64 v[124:125], v[202:203], 0, v[98:99]
	v_lshl_add_u64 v[126:127], v[204:205], 0, v[98:99]
	v_lshl_add_u64 v[164:165], v[206:207], 0, v[98:99]
	global_load_dword v197, v[122:123], off
	global_load_dword v198, v[122:123], off offset:128
	global_load_dword v199, v[124:125], off
	s_nop 0
	global_load_dword v124, v[124:125], off offset:128
	s_nop 0
	global_load_dword v125, v[126:127], off
	s_nop 0
	global_load_dword v126, v[126:127], off offset:128
	s_nop 0
	global_load_dword v127, v[164:165], off
	s_nop 0
	global_load_dword v164, v[164:165], off offset:128
	v_lshl_add_u64 v[122:123], v[208:209], 0, v[98:99]
	global_load_dword v165, v[122:123], off
	s_nop 0
	global_load_dword v122, v[122:123], off offset:128
	s_waitcnt vmcnt(25)
	v_mul_f32_e32 v80, v80, v166
	s_waitcnt vmcnt(24)
	v_mul_f32_e32 v64, v64, v167
	v_mul_f32_e32 v65, v65, v167
	v_mul_f32_e32 v81, v81, v166
	v_mul_f32_e32 v82, v82, v166
	v_mul_f32_e32 v66, v66, v167
	v_mul_f32_e32 v83, v83, v166
	v_mul_f32_e32 v67, v67, v167
	s_waitcnt vmcnt(23)
	v_mul_f32_e32 v84, v84, v182
	s_waitcnt vmcnt(22)
	v_mul_f32_e32 v68, v68, v184
	s_waitcnt vmcnt(21)
	v_mul_f32_e32 v85, v85, v185
	s_waitcnt vmcnt(20)
	v_mul_f32_e32 v69, v69, v186
	s_waitcnt vmcnt(19)
	v_mul_f32_e32 v86, v86, v187
	s_waitcnt vmcnt(18)
	v_mul_f32_e32 v70, v70, v188
	s_waitcnt vmcnt(17)
	v_mul_f32_e32 v87, v87, v189
	s_waitcnt vmcnt(16)
	v_mul_f32_e32 v71, v71, v190
	s_waitcnt vmcnt(15)
	v_mul_f32_e32 v88, v88, v191
	s_waitcnt vmcnt(14)
	v_mul_f32_e32 v72, v72, v192
	s_waitcnt vmcnt(13)
	v_mul_f32_e32 v89, v89, v193
	s_waitcnt vmcnt(12)
	v_mul_f32_e32 v73, v73, v194
	s_waitcnt vmcnt(11)
	v_mul_f32_e32 v90, v90, v195
	s_waitcnt vmcnt(10)
	v_mul_f32_e32 v74, v74, v196
	s_waitcnt vmcnt(9)
	v_mul_f32_e32 v91, v91, v197
	s_waitcnt vmcnt(8)
	v_mul_f32_e32 v75, v75, v198
	s_waitcnt vmcnt(7)
	v_mul_f32_e32 v92, v92, v199
	s_waitcnt vmcnt(6)
	v_mul_f32_e32 v76, v76, v124
	s_waitcnt vmcnt(5)
	v_mul_f32_e32 v93, v93, v125
	s_waitcnt vmcnt(4)
	v_mul_f32_e32 v77, v77, v126
	s_waitcnt vmcnt(3)
	v_mul_f32_e32 v94, v94, v127
	s_waitcnt vmcnt(2)
	v_mul_f32_e32 v78, v78, v164
	ds_write2_b32 v162, v80, v64 offset1:32
	ds_write2_b32 v162, v81, v65 offset0:68 offset1:100
	ds_write2_b32 v162, v82, v66 offset0:136 offset1:168
	ds_write2_b32 v162, v83, v67 offset0:204 offset1:236
	ds_write2_b32 v115, v84, v68 offset0:32 offset1:64
	ds_write2_b32 v115, v85, v69 offset0:100 offset1:132
	ds_write2_b32 v115, v86, v70 offset0:168 offset1:200
	ds_write2_b32 v116, v87, v71 offset0:108 offset1:140
	ds_write2_b32 v117, v88, v72 offset0:64 offset1:96
	ds_write2_b32 v117, v89, v73 offset0:132 offset1:164
	ds_write2_b32 v117, v90, v74 offset0:200 offset1:232
	ds_write2_b32 v118, v91, v75 offset0:12 offset1:44
	ds_write2_b32 v119, v92, v76 offset0:96 offset1:128
	ds_write2_b32 v119, v93, v77 offset0:164 offset1:196
	ds_write2_b32 v120, v94, v78 offset0:104 offset1:136
	s_waitcnt vmcnt(1)
	v_mul_f32_e32 v64, v95, v165
	s_waitcnt vmcnt(0)
	v_mul_f32_e32 v65, v79, v122
	ds_write2_b32 v121, v64, v65 offset0:44 offset1:76
	v_lshl_add_u64 v[64:65], v[168:169], 0, s[26:27]
	v_add_u32_e32 v128, 0, v160
	v_ashrrev_i32_e32 v129, 31, v128
	v_lshlrev_b64 v[128:129], 10, v[128:129]
	v_lshl_add_u64 v[128:129], v[128:129], 0, v[64:65]
	v_lshlrev_b64 v[128:129], 2, v[128:129]
	v_lshl_add_u64 v[128:129], s[16:17], 0, v[128:129]
	global_load_dwordx4 v[128:131], v[128:129], off offset:256 nt
	v_add_u32_e32 v132, 4, v160
	v_ashrrev_i32_e32 v133, 31, v132
	v_lshlrev_b64 v[132:133], 10, v[132:133]
	v_lshl_add_u64 v[132:133], v[132:133], 0, v[64:65]
	v_lshlrev_b64 v[132:133], 2, v[132:133]
	v_lshl_add_u64 v[132:133], s[16:17], 0, v[132:133]
	global_load_dwordx4 v[132:135], v[132:133], off offset:256 nt
	v_add_u32_e32 v136, 8, v160
	v_ashrrev_i32_e32 v137, 31, v136
	v_lshlrev_b64 v[136:137], 10, v[136:137]
	v_lshl_add_u64 v[136:137], v[136:137], 0, v[64:65]
	v_lshlrev_b64 v[136:137], 2, v[136:137]
	v_lshl_add_u64 v[136:137], s[16:17], 0, v[136:137]
	global_load_dwordx4 v[136:139], v[136:137], off offset:256 nt
	v_add_u32_e32 v140, 12, v160
	v_ashrrev_i32_e32 v141, 31, v140
	v_lshlrev_b64 v[140:141], 10, v[140:141]
	v_lshl_add_u64 v[140:141], v[140:141], 0, v[64:65]
	v_lshlrev_b64 v[140:141], 2, v[140:141]
	v_lshl_add_u64 v[140:141], s[16:17], 0, v[140:141]
	global_load_dwordx4 v[140:143], v[140:141], off offset:256 nt
	v_add_u32_e32 v144, 16, v160
	v_ashrrev_i32_e32 v145, 31, v144
	v_lshlrev_b64 v[144:145], 10, v[144:145]
	v_lshl_add_u64 v[144:145], v[144:145], 0, v[64:65]
	v_lshlrev_b64 v[144:145], 2, v[144:145]
	v_lshl_add_u64 v[144:145], s[16:17], 0, v[144:145]
	global_load_dwordx4 v[144:147], v[144:145], off offset:256 nt
	v_add_u32_e32 v148, 20, v160
	v_ashrrev_i32_e32 v149, 31, v148
	v_lshlrev_b64 v[148:149], 10, v[148:149]
	v_lshl_add_u64 v[148:149], v[148:149], 0, v[64:65]
	v_lshlrev_b64 v[148:149], 2, v[148:149]
	v_lshl_add_u64 v[148:149], s[16:17], 0, v[148:149]
	global_load_dwordx4 v[148:151], v[148:149], off offset:256 nt
	v_add_u32_e32 v152, 24, v160
	v_ashrrev_i32_e32 v153, 31, v152
	v_lshlrev_b64 v[152:153], 10, v[152:153]
	v_lshl_add_u64 v[152:153], v[152:153], 0, v[64:65]
	v_lshlrev_b64 v[152:153], 2, v[152:153]
	v_lshl_add_u64 v[152:153], s[16:17], 0, v[152:153]
	global_load_dwordx4 v[152:155], v[152:153], off offset:256 nt
	v_add_u32_e32 v156, 28, v160
	v_ashrrev_i32_e32 v157, 31, v156
	v_lshlrev_b64 v[156:157], 10, v[156:157]
	v_lshl_add_u64 v[156:157], v[156:157], 0, v[64:65]
	v_lshlrev_b64 v[156:157], 2, v[156:157]
	v_lshl_add_u64 v[156:157], s[16:17], 0, v[156:157]
	global_load_dwordx4 v[156:159], v[156:157], off offset:256 nt
	s_and_saveexec_b64 s[26:27], vcc
	s_cbranch_execz .LBB0_1303
	v_lshlrev_b64 v[66:67], 10, v[160:161]
	v_lshl_add_u64 v[66:67], v[66:67], 0, v[64:65]
	v_lshlrev_b64 v[74:75], 2, v[66:67]
	v_lshl_add_u64 v[66:67], s[16:17], 0, v[74:75]
	ds_read_b128 v[70:73], v114
	s_load_dwordx2 s[28:29], s[0:1], 0xb8
	s_waitcnt vmcnt(7) lgkmcnt(0)
	v_pk_add_f32 v[68:69], v[72:73], v[130:131]
	v_pk_add_f32 v[66:67], v[70:71], v[128:129]
	v_lshl_add_u64 v[70:71], s[28:29], 0, v[74:75]
	global_store_dwordx4 v[70:71], v[66:69], off offset:256
	s_or_b64 exec, exec, s[26:27]
	s_and_saveexec_b64 s[26:27], s[2:3]
	s_cbranch_execnz .LBB0_1304

.LBB0_1311:
	s_or_b64 exec, exec, s[2:3]
	s_or_b32 s2, s55, 32
	v_add_u32_e32 v102, s2, v183
	v_min_i32_e32 v66, 0x7fff, v102
	v_add_u32_e32 v68, 8, v102
	v_add_u32_e32 v70, 9, v102
	v_add_u32_e32 v72, 10, v102
	v_ashrrev_i32_e32 v66, 12, v66
	v_min_i32_e32 v68, 0x7fff, v68
	v_min_i32_e32 v70, 0x7fff, v70
	v_min_i32_e32 v72, 0x7fff, v72
	v_mul_hi_i32_i24_e32 v67, 0x3000, v66
	v_mul_i32_i24_e32 v66, 0x3000, v66
	v_ashrrev_i32_e32 v68, 12, v68
	v_ashrrev_i32_e32 v70, 12, v70
	v_ashrrev_i32_e32 v72, 12, v72
	v_lshl_add_u64 v[66:67], s[24:25], 0, v[66:67]
	v_mul_hi_i32_i24_e32 v69, 0x3000, v68
	v_mul_i32_i24_e32 v68, 0x3000, v68
	v_mul_hi_i32_i24_e32 v71, 0x3000, v70
	v_mul_i32_i24_e32 v70, 0x3000, v70
	v_mul_hi_i32_i24_e32 v73, 0x3000, v72
	v_mul_i32_i24_e32 v72, 0x3000, v72
	v_lshl_add_u64 v[66:67], v[66:67], 0, s[18:19]
	v_lshl_add_u64 v[68:69], s[24:25], 0, v[68:69]
	v_lshl_add_u64 v[70:71], s[24:25], 0, v[70:71]
	v_lshl_add_u64 v[72:73], s[24:25], 0, v[72:73]
	v_lshl_add_u64 v[74:75], v[66:67], 0, v[180:181]
	v_lshl_add_u64 v[68:69], v[68:69], 0, s[18:19]
	v_lshl_add_u64 v[70:71], v[70:71], 0, s[18:19]
	v_lshl_add_u64 v[72:73], v[72:73], 0, s[18:19]
	v_lshl_add_u64 v[76:77], v[68:69], 0, v[180:181]
	v_lshl_add_u64 v[78:79], v[70:71], 0, v[180:181]
	v_lshl_add_u64 v[80:81], v[72:73], 0, v[180:181]
	global_load_dword v103, v[74:75], off
	global_load_dword v104, v[74:75], off offset:128
	global_load_dword v105, v[76:77], off
	global_load_dword v106, v[76:77], off offset:128
	global_load_dword v107, v[78:79], off
	global_load_dword v108, v[78:79], off offset:128
	global_load_dword v109, v[80:81], off
	global_load_dword v110, v[80:81], off offset:128
	v_add_u32_e32 v74, 11, v102
	v_add_u32_e32 v82, 18, v102
	v_min_i32_e32 v74, 0x7fff, v74
	v_add_u32_e32 v76, 16, v102
	v_add_u32_e32 v80, 17, v102
	v_min_i32_e32 v82, 0x7fff, v82
	v_ashrrev_i32_e32 v74, 12, v74
	v_min_i32_e32 v76, 0x7fff, v76
	v_min_i32_e32 v80, 0x7fff, v80
	v_ashrrev_i32_e32 v82, 12, v82
	v_mul_hi_i32_i24_e32 v75, 0x3000, v74
	v_mul_i32_i24_e32 v74, 0x3000, v74
	v_ashrrev_i32_e32 v76, 12, v76
	v_ashrrev_i32_e32 v80, 12, v80
	v_mul_hi_i32_i24_e32 v83, 0x3000, v82
	v_mul_i32_i24_e32 v82, 0x3000, v82
	v_lshl_add_u64 v[74:75], s[24:25], 0, v[74:75]
	v_mul_hi_i32_i24_e32 v77, 0x3000, v76
	v_mul_i32_i24_e32 v76, 0x3000, v76
	v_mul_hi_i32_i24_e32 v81, 0x3000, v80
	v_mul_i32_i24_e32 v80, 0x3000, v80
	v_lshl_add_u64 v[82:83], s[24:25], 0, v[82:83]
	v_lshl_add_u64 v[74:75], v[74:75], 0, s[18:19]
	v_lshl_add_u64 v[76:77], s[24:25], 0, v[76:77]
	v_lshl_add_u64 v[80:81], s[24:25], 0, v[80:81]
	v_lshl_add_u64 v[82:83], v[82:83], 0, s[18:19]
	v_lshl_add_u64 v[78:79], v[74:75], 0, v[180:181]
	v_lshl_add_u64 v[76:77], v[76:77], 0, s[18:19]
	v_lshl_add_u64 v[80:81], v[80:81], 0, s[18:19]
	v_lshl_add_u64 v[88:89], v[82:83], 0, v[180:181]
	v_lshl_add_u64 v[84:85], v[76:77], 0, v[180:181]
	v_lshl_add_u64 v[86:87], v[80:81], 0, v[180:181]
	global_load_dword v111, v[78:79], off
	global_load_dword v112, v[78:79], off offset:128
	global_load_dword v113, v[84:85], off
	global_load_dword v122, v[84:85], off offset:128
	global_load_dword v123, v[86:87], off
	global_load_dword v124, v[86:87], off offset:128
	global_load_dword v125, v[88:89], off
	global_load_dword v126, v[88:89], off offset:128
	v_add_u32_e32 v78, 19, v102
	v_add_u32_e32 v88, 25, v102
	v_add_u32_e32 v90, 26, v102
	v_min_i32_e32 v78, 0x7fff, v78
	v_add_u32_e32 v86, 24, v102
	v_min_i32_e32 v88, 0x7fff, v88
	v_min_i32_e32 v90, 0x7fff, v90
	v_ashrrev_i32_e32 v78, 12, v78
	v_min_i32_e32 v86, 0x7fff, v86
	v_ashrrev_i32_e32 v88, 12, v88
	v_ashrrev_i32_e32 v90, 12, v90
	v_mul_hi_i32_i24_e32 v79, 0x3000, v78
	v_mul_i32_i24_e32 v78, 0x3000, v78
	v_ashrrev_i32_e32 v86, 12, v86
	v_mul_hi_i32_i24_e32 v89, 0x3000, v88
	v_mul_i32_i24_e32 v88, 0x3000, v88
	v_mul_hi_i32_i24_e32 v91, 0x3000, v90
	v_mul_i32_i24_e32 v90, 0x3000, v90
	v_lshl_add_u64 v[78:79], s[24:25], 0, v[78:79]
	v_mul_hi_i32_i24_e32 v87, 0x3000, v86
	v_mul_i32_i24_e32 v86, 0x3000, v86
	v_lshl_add_u64 v[88:89], s[24:25], 0, v[88:89]
	v_lshl_add_u64 v[90:91], s[24:25], 0, v[90:91]
	v_lshl_add_u64 v[84:85], v[78:79], 0, s[18:19]
	v_lshl_add_u64 v[86:87], s[24:25], 0, v[86:87]
	v_lshl_add_u64 v[88:89], v[88:89], 0, s[18:19]
	v_lshl_add_u64 v[90:91], v[90:91], 0, s[18:19]
	v_lshl_add_u64 v[78:79], v[84:85], 0, v[180:181]
	v_lshl_add_u64 v[86:87], v[86:87], 0, s[18:19]
	v_lshl_add_u64 v[94:95], v[88:89], 0, v[180:181]
	v_lshl_add_u64 v[100:101], v[90:91], 0, v[180:181]
	v_lshl_add_u64 v[92:93], v[86:87], 0, v[180:181]
	global_load_dword v127, v[78:79], off
	global_load_dword v160, v[78:79], off offset:128
	global_load_dword v161, v[92:93], off
	global_load_dword v164, v[92:93], off offset:128
	global_load_dword v165, v[94:95], off
	s_nop 0
	global_load_dword v94, v[94:95], off offset:128
	s_nop 0
	global_load_dword v95, v[100:101], off
	s_nop 0
	global_load_dword v100, v[100:101], off offset:128
	v_add_u32_e32 v78, 27, v102
	v_min_i32_e32 v78, 0x7fff, v78
	v_ashrrev_i32_e32 v78, 12, v78
	v_mul_hi_i32_i24_e32 v79, 0x3000, v78
	v_mul_i32_i24_e32 v78, 0x3000, v78
	v_lshl_add_u64 v[78:79], s[24:25], 0, v[78:79]
	v_lshl_add_u64 v[92:93], v[78:79], 0, s[18:19]
	v_lshl_add_u64 v[78:79], v[92:93], 0, v[180:181]
	global_load_dword v101, v[78:79], off
	s_nop 0
	global_load_dword v79, v[78:79], off offset:128
	s_waitcnt vmcnt(25)
	v_mul_f32_e32 v48, v48, v103
	s_waitcnt vmcnt(24)
	v_mul_f32_e32 v32, v32, v104
	ds_write2_b32 v162, v48, v32 offset1:32
	v_mul_f32_e32 v32, v49, v103
	v_mul_f32_e32 v33, v33, v104
	ds_write2_b32 v162, v32, v33 offset0:68 offset1:100
	v_mul_f32_e32 v32, v50, v103
	v_mul_f32_e32 v33, v34, v104
	ds_write2_b32 v162, v32, v33 offset0:136 offset1:168
	v_mul_f32_e32 v32, v51, v103
	v_mul_f32_e32 v33, v35, v104
	ds_write2_b32 v162, v32, v33 offset0:204 offset1:236
	s_waitcnt vmcnt(23)
	v_mul_f32_e32 v32, v52, v105
	s_waitcnt vmcnt(22)
	v_mul_f32_e32 v33, v36, v106
	ds_write2_b32 v115, v32, v33 offset0:32 offset1:64
	s_waitcnt vmcnt(21)
	v_mul_f32_e32 v32, v53, v107
	s_waitcnt vmcnt(20)
	v_mul_f32_e32 v33, v37, v108
	ds_write2_b32 v115, v32, v33 offset0:100 offset1:132
	s_waitcnt vmcnt(19)
	v_mul_f32_e32 v32, v54, v109
	s_waitcnt vmcnt(18)
	v_mul_f32_e32 v33, v38, v110
	ds_write2_b32 v115, v32, v33 offset0:168 offset1:200
	v_add_u32_e32 v78, s2, v163
	v_cmp_gt_i32_e32 vcc, s38, v78
	s_waitcnt vmcnt(17)
	v_mul_f32_e32 v32, v55, v111
	s_waitcnt vmcnt(16)
	v_mul_f32_e32 v33, v39, v112
	ds_write2_b32 v116, v32, v33 offset0:108 offset1:140
	s_waitcnt vmcnt(15)
	v_mul_f32_e32 v32, v56, v113
	s_waitcnt vmcnt(14)
	v_mul_f32_e32 v33, v40, v122
	ds_write2_b32 v117, v32, v33 offset0:64 offset1:96
	s_waitcnt vmcnt(13)
	v_mul_f32_e32 v32, v57, v123
	s_waitcnt vmcnt(12)
	v_mul_f32_e32 v33, v41, v124
	ds_write2_b32 v117, v32, v33 offset0:132 offset1:164
	s_waitcnt vmcnt(11)
	v_mul_f32_e32 v32, v58, v125
	s_waitcnt vmcnt(10)
	v_mul_f32_e32 v33, v42, v126
	ds_write2_b32 v117, v32, v33 offset0:200 offset1:232
	s_waitcnt vmcnt(9)
	v_mul_f32_e32 v32, v59, v127
	s_waitcnt vmcnt(8)
	v_mul_f32_e32 v33, v43, v160
	ds_write2_b32 v118, v32, v33 offset0:12 offset1:44
	s_waitcnt vmcnt(7)
	v_mul_f32_e32 v32, v60, v161
	s_waitcnt vmcnt(6)
	v_mul_f32_e32 v33, v44, v164
	ds_write2_b32 v119, v32, v33 offset0:96 offset1:128
	s_waitcnt vmcnt(5)
	v_mul_f32_e32 v32, v61, v165
	s_waitcnt vmcnt(4)
	v_mul_f32_e32 v33, v45, v94
	ds_write2_b32 v119, v32, v33 offset0:164 offset1:196
	s_waitcnt vmcnt(3)
	v_mul_f32_e32 v32, v62, v95
	s_waitcnt vmcnt(2)
	v_mul_f32_e32 v33, v46, v100
	ds_write2_b32 v120, v32, v33 offset0:104 offset1:136
	s_waitcnt vmcnt(1)
	v_mul_f32_e32 v32, v63, v101
	s_waitcnt vmcnt(0)
	v_mul_f32_e32 v33, v47, v79
	v_ashrrev_i32_e32 v79, 31, v78
	ds_write2_b32 v121, v32, v33 offset0:44 offset1:76
	v_add_u32_e32 v128, 0, v78
	v_ashrrev_i32_e32 v129, 31, v128
	v_lshlrev_b64 v[128:129], 10, v[128:129]
	v_lshl_add_u64 v[128:129], v[128:129], 0, v[96:97]
	v_lshlrev_b64 v[128:129], 2, v[128:129]
	v_lshl_add_u64 v[128:129], s[16:17], 0, v[128:129]
	global_load_dwordx4 v[128:131], v[128:129], off nt
	v_add_u32_e32 v132, 4, v78
	v_ashrrev_i32_e32 v133, 31, v132
	v_lshlrev_b64 v[132:133], 10, v[132:133]
	v_lshl_add_u64 v[132:133], v[132:133], 0, v[96:97]
	v_lshlrev_b64 v[132:133], 2, v[132:133]
	v_lshl_add_u64 v[132:133], s[16:17], 0, v[132:133]
	global_load_dwordx4 v[132:135], v[132:133], off nt
	v_add_u32_e32 v136, 8, v78
	v_ashrrev_i32_e32 v137, 31, v136
	v_lshlrev_b64 v[136:137], 10, v[136:137]
	v_lshl_add_u64 v[136:137], v[136:137], 0, v[96:97]
	v_lshlrev_b64 v[136:137], 2, v[136:137]
	v_lshl_add_u64 v[136:137], s[16:17], 0, v[136:137]
	global_load_dwordx4 v[136:139], v[136:137], off nt
	v_add_u32_e32 v140, 12, v78
	v_ashrrev_i32_e32 v141, 31, v140
	v_lshlrev_b64 v[140:141], 10, v[140:141]
	v_lshl_add_u64 v[140:141], v[140:141], 0, v[96:97]
	v_lshlrev_b64 v[140:141], 2, v[140:141]
	v_lshl_add_u64 v[140:141], s[16:17], 0, v[140:141]
	global_load_dwordx4 v[140:143], v[140:141], off nt
	v_add_u32_e32 v144, 16, v78
	v_ashrrev_i32_e32 v145, 31, v144
	v_lshlrev_b64 v[144:145], 10, v[144:145]
	v_lshl_add_u64 v[144:145], v[144:145], 0, v[96:97]
	v_lshlrev_b64 v[144:145], 2, v[144:145]
	v_lshl_add_u64 v[144:145], s[16:17], 0, v[144:145]
	global_load_dwordx4 v[144:147], v[144:145], off nt
	v_add_u32_e32 v148, 20, v78
	v_ashrrev_i32_e32 v149, 31, v148
	v_lshlrev_b64 v[148:149], 10, v[148:149]
	v_lshl_add_u64 v[148:149], v[148:149], 0, v[96:97]
	v_lshlrev_b64 v[148:149], 2, v[148:149]
	v_lshl_add_u64 v[148:149], s[16:17], 0, v[148:149]
	global_load_dwordx4 v[148:151], v[148:149], off nt
	v_add_u32_e32 v152, 24, v78
	v_ashrrev_i32_e32 v153, 31, v152
	v_lshlrev_b64 v[152:153], 10, v[152:153]
	v_lshl_add_u64 v[152:153], v[152:153], 0, v[96:97]
	v_lshlrev_b64 v[152:153], 2, v[152:153]
	v_lshl_add_u64 v[152:153], s[16:17], 0, v[152:153]
	global_load_dwordx4 v[152:155], v[152:153], off nt
	v_add_u32_e32 v156, 28, v78
	v_ashrrev_i32_e32 v157, 31, v156
	v_lshlrev_b64 v[156:157], 10, v[156:157]
	v_lshl_add_u64 v[156:157], v[156:157], 0, v[96:97]
	v_lshlrev_b64 v[156:157], 2, v[156:157]
	v_lshl_add_u64 v[156:157], s[16:17], 0, v[156:157]
	global_load_dwordx4 v[156:159], v[156:157], off nt
	s_and_saveexec_b64 s[2:3], vcc
	s_cbranch_execz .LBB0_1313
	v_lshlrev_b64 v[32:33], 10, v[78:79]
	v_lshl_add_u64 v[32:33], v[32:33], 0, v[96:97]
	v_lshlrev_b64 v[40:41], 2, v[32:33]
	v_lshl_add_u64 v[32:33], s[16:17], 0, v[40:41]
	ds_read_b128 v[36:39], v114
	s_load_dwordx2 s[4:5], s[0:1], 0xb8
	s_waitcnt vmcnt(7) lgkmcnt(0)
	v_pk_add_f32 v[34:35], v[38:39], v[130:131]
	v_pk_add_f32 v[32:33], v[36:37], v[128:129]
	v_lshl_add_u64 v[36:37], s[4:5], 0, v[40:41]
	global_store_dwordx4 v[36:37], v[32:35], off

.LBB0_1327:
	s_or_b64 exec, exec, s[24:25]
	s_nop 0
	v_lshl_add_u64 v[46:47], v[66:67], 0, v[98:99]
	v_lshl_add_u64 v[48:49], v[68:69], 0, v[98:99]
	v_lshl_add_u64 v[50:51], v[70:71], 0, v[98:99]
	v_lshl_add_u64 v[52:53], v[72:73], 0, v[98:99]
	global_load_dword v54, v[46:47], off
	global_load_dword v55, v[46:47], off offset:128
	global_load_dword v56, v[48:49], off
	global_load_dword v57, v[48:49], off offset:128
	global_load_dword v58, v[50:51], off
	global_load_dword v59, v[50:51], off offset:128
	global_load_dword v60, v[52:53], off
	global_load_dword v61, v[52:53], off offset:128
	v_lshl_add_u64 v[46:47], v[74:75], 0, v[98:99]
	v_lshl_add_u64 v[48:49], v[76:77], 0, v[98:99]
	v_lshl_add_u64 v[50:51], v[80:81], 0, v[98:99]
	v_lshl_add_u64 v[52:53], v[82:83], 0, v[98:99]
	global_load_dword v62, v[46:47], off
	global_load_dword v63, v[46:47], off offset:128
	global_load_dword v66, v[48:49], off
	global_load_dword v67, v[48:49], off offset:128
	global_load_dword v68, v[50:51], off
	global_load_dword v69, v[50:51], off offset:128
	global_load_dword v70, v[52:53], off
	global_load_dword v71, v[52:53], off offset:128
	v_lshl_add_u64 v[46:47], v[84:85], 0, v[98:99]
	v_lshl_add_u64 v[48:49], v[86:87], 0, v[98:99]
	v_lshl_add_u64 v[50:51], v[88:89], 0, v[98:99]
	v_lshl_add_u64 v[52:53], v[90:91], 0, v[98:99]
	global_load_dword v72, v[46:47], off
	global_load_dword v73, v[46:47], off offset:128
	global_load_dword v74, v[48:49], off
	s_nop 0
	global_load_dword v48, v[48:49], off offset:128
	s_nop 0
	global_load_dword v49, v[50:51], off
	s_nop 0
	global_load_dword v50, v[50:51], off offset:128
	s_nop 0
	global_load_dword v51, v[52:53], off
	s_nop 0
	global_load_dword v52, v[52:53], off offset:128
	v_lshl_add_u64 v[46:47], v[92:93], 0, v[98:99]
	global_load_dword v53, v[46:47], off
	s_nop 0
	global_load_dword v46, v[46:47], off offset:128
	s_waitcnt vmcnt(25)
	v_mul_f32_e32 v16, v16, v54
	s_waitcnt vmcnt(24)
	v_mul_f32_e32 v0, v0, v55
	v_mul_f32_e32 v1, v1, v55
	v_mul_f32_e32 v17, v17, v54
	v_mul_f32_e32 v18, v18, v54
	v_mul_f32_e32 v2, v2, v55
	v_mul_f32_e32 v19, v19, v54
	v_mul_f32_e32 v3, v3, v55
	s_waitcnt vmcnt(23)
	v_mul_f32_e32 v20, v20, v56
	s_waitcnt vmcnt(22)
	v_mul_f32_e32 v4, v4, v57
	s_waitcnt vmcnt(21)
	v_mul_f32_e32 v21, v21, v58
	s_waitcnt vmcnt(20)
	v_mul_f32_e32 v5, v5, v59
	s_waitcnt vmcnt(19)
	v_mul_f32_e32 v22, v22, v60
	s_waitcnt vmcnt(18)
	v_mul_f32_e32 v6, v6, v61
	s_waitcnt vmcnt(17)
	v_mul_f32_e32 v23, v23, v62
	s_waitcnt vmcnt(16)
	v_mul_f32_e32 v7, v7, v63
	s_waitcnt vmcnt(15)
	v_mul_f32_e32 v24, v24, v66
	s_waitcnt vmcnt(14)
	v_mul_f32_e32 v8, v8, v67
	s_waitcnt vmcnt(13)
	v_mul_f32_e32 v25, v25, v68
	s_waitcnt vmcnt(12)
	v_mul_f32_e32 v9, v9, v69
	s_waitcnt vmcnt(11)
	v_mul_f32_e32 v26, v26, v70
	s_waitcnt vmcnt(10)
	v_mul_f32_e32 v10, v10, v71
	s_waitcnt vmcnt(9)
	v_mul_f32_e32 v27, v27, v72
	s_waitcnt vmcnt(8)
	v_mul_f32_e32 v11, v11, v73
	s_waitcnt vmcnt(7)
	v_mul_f32_e32 v28, v28, v74
	s_waitcnt vmcnt(6)
	v_mul_f32_e32 v12, v12, v48
	s_waitcnt vmcnt(5)
	v_mul_f32_e32 v29, v29, v49
	s_waitcnt vmcnt(4)
	v_mul_f32_e32 v13, v13, v50
	s_waitcnt vmcnt(3)
	v_mul_f32_e32 v30, v30, v51
	s_waitcnt vmcnt(2)
	v_mul_f32_e32 v14, v14, v52
	ds_write2_b32 v162, v16, v0 offset1:32
	ds_write2_b32 v162, v17, v1 offset0:68 offset1:100
	ds_write2_b32 v162, v18, v2 offset0:136 offset1:168
	ds_write2_b32 v162, v19, v3 offset0:204 offset1:236
	ds_write2_b32 v115, v20, v4 offset0:32 offset1:64
	ds_write2_b32 v115, v21, v5 offset0:100 offset1:132
	ds_write2_b32 v115, v22, v6 offset0:168 offset1:200
	ds_write2_b32 v116, v23, v7 offset0:108 offset1:140
	ds_write2_b32 v117, v24, v8 offset0:64 offset1:96
	ds_write2_b32 v117, v25, v9 offset0:132 offset1:164
	ds_write2_b32 v117, v26, v10 offset0:200 offset1:232
	ds_write2_b32 v118, v27, v11 offset0:12 offset1:44
	ds_write2_b32 v119, v28, v12 offset0:96 offset1:128
	ds_write2_b32 v119, v29, v13 offset0:164 offset1:196
	ds_write2_b32 v120, v30, v14 offset0:104 offset1:136
	s_waitcnt vmcnt(1)
	v_mul_f32_e32 v0, v31, v53
	s_waitcnt vmcnt(0)
	v_mul_f32_e32 v1, v15, v46
	ds_write2_b32 v121, v0, v1 offset0:44 offset1:76
	v_add_u32_e32 v128, 0, v78
	v_ashrrev_i32_e32 v129, 31, v128
	v_lshlrev_b64 v[128:129], 10, v[128:129]
	v_lshl_add_u64 v[128:129], v[128:129], 0, v[64:65]
	v_lshlrev_b64 v[128:129], 2, v[128:129]
	v_lshl_add_u64 v[128:129], s[16:17], 0, v[128:129]
	global_load_dwordx4 v[128:131], v[128:129], off offset:256 nt
	v_add_u32_e32 v132, 4, v78
	v_ashrrev_i32_e32 v133, 31, v132
	v_lshlrev_b64 v[132:133], 10, v[132:133]
	v_lshl_add_u64 v[132:133], v[132:133], 0, v[64:65]
	v_lshlrev_b64 v[132:133], 2, v[132:133]
	v_lshl_add_u64 v[132:133], s[16:17], 0, v[132:133]
	global_load_dwordx4 v[132:135], v[132:133], off offset:256 nt
	v_add_u32_e32 v136, 8, v78
	v_ashrrev_i32_e32 v137, 31, v136
	v_lshlrev_b64 v[136:137], 10, v[136:137]
	v_lshl_add_u64 v[136:137], v[136:137], 0, v[64:65]
	v_lshlrev_b64 v[136:137], 2, v[136:137]
	v_lshl_add_u64 v[136:137], s[16:17], 0, v[136:137]
	global_load_dwordx4 v[136:139], v[136:137], off offset:256 nt
	v_add_u32_e32 v140, 12, v78
	v_ashrrev_i32_e32 v141, 31, v140
	v_lshlrev_b64 v[140:141], 10, v[140:141]
	v_lshl_add_u64 v[140:141], v[140:141], 0, v[64:65]
	v_lshlrev_b64 v[140:141], 2, v[140:141]
	v_lshl_add_u64 v[140:141], s[16:17], 0, v[140:141]
	global_load_dwordx4 v[140:143], v[140:141], off offset:256 nt
	v_add_u32_e32 v144, 16, v78
	v_ashrrev_i32_e32 v145, 31, v144
	v_lshlrev_b64 v[144:145], 10, v[144:145]
	v_lshl_add_u64 v[144:145], v[144:145], 0, v[64:65]
	v_lshlrev_b64 v[144:145], 2, v[144:145]
	v_lshl_add_u64 v[144:145], s[16:17], 0, v[144:145]
	global_load_dwordx4 v[144:147], v[144:145], off offset:256 nt
	v_add_u32_e32 v148, 20, v78
	v_ashrrev_i32_e32 v149, 31, v148
	v_lshlrev_b64 v[148:149], 10, v[148:149]
	v_lshl_add_u64 v[148:149], v[148:149], 0, v[64:65]
	v_lshlrev_b64 v[148:149], 2, v[148:149]
	v_lshl_add_u64 v[148:149], s[16:17], 0, v[148:149]
	global_load_dwordx4 v[148:151], v[148:149], off offset:256 nt
	v_add_u32_e32 v152, 24, v78
	v_ashrrev_i32_e32 v153, 31, v152
	v_lshlrev_b64 v[152:153], 10, v[152:153]
	v_lshl_add_u64 v[152:153], v[152:153], 0, v[64:65]
	v_lshlrev_b64 v[152:153], 2, v[152:153]
	v_lshl_add_u64 v[152:153], s[16:17], 0, v[152:153]
	global_load_dwordx4 v[152:155], v[152:153], off offset:256 nt
	v_add_u32_e32 v156, 28, v78
	v_ashrrev_i32_e32 v157, 31, v156
	v_lshlrev_b64 v[156:157], 10, v[156:157]
	v_lshl_add_u64 v[156:157], v[156:157], 0, v[64:65]
	v_lshlrev_b64 v[156:157], 2, v[156:157]
	v_lshl_add_u64 v[156:157], s[16:17], 0, v[156:157]
	global_load_dwordx4 v[156:159], v[156:157], off offset:256 nt
	s_and_saveexec_b64 s[24:25], vcc
	s_cbranch_execz .LBB0_1335
	v_lshlrev_b64 v[0:1], 10, v[78:79]
	v_lshl_add_u64 v[0:1], v[0:1], 0, v[64:65]
	v_lshlrev_b64 v[8:9], 2, v[0:1]
	v_lshl_add_u64 v[0:1], s[16:17], 0, v[8:9]
	ds_read_b128 v[4:7], v114
	s_load_dwordx2 s[26:27], s[0:1], 0xb8
	s_waitcnt vmcnt(7) lgkmcnt(0)
	v_pk_add_f32 v[2:3], v[6:7], v[130:131]
	v_pk_add_f32 v[0:1], v[4:5], v[128:129]
	v_lshl_add_u64 v[4:5], s[26:27], 0, v[8:9]
	global_store_dwordx4 v[4:5], v[0:3], off offset:256
	s_or_b64 exec, exec, s[24:25]
	s_and_saveexec_b64 s[24:25], s[2:3]
	s_cbranch_execnz .LBB0_1336

.LBB0_2223:
	ds_read_b128 v[128:131], v238
	ds_read_b128 v[136:139], v253
	ds_read_b128 v[132:135], v238 offset:4096
	ds_read_b128 v[140:143], v253 offset:4096
	ds_read_b128 v[144:147], v253 offset:8192
	ds_read_b128 v[148:151], v253 offset:12288
	s_waitcnt lgkmcnt(6)
	v_mfma_f32_32x32x16_bf16 v[112:127], v[188:191], v[196:199], v[112:127]
	v_mfma_f32_32x32x16_bf16 v[48:63], v[192:195], v[196:199], v[48:63]
	v_mfma_f32_32x32x16_bf16 v[96:111], v[188:191], v[200:203], v[96:111]
	v_mfma_f32_32x32x16_bf16 v[32:47], v[192:195], v[200:203], v[32:47]
	v_mfma_f32_32x32x16_bf16 v[80:95], v[188:191], v[204:207], v[80:95]
	v_mfma_f32_32x32x16_bf16 v[16:31], v[192:195], v[204:207], v[16:31]
	v_mfma_f32_32x32x16_bf16 v[64:79], v[188:191], v[226:229], v[64:79]
	v_mfma_f32_32x32x16_bf16 v[0:15], v[192:195], v[226:229], v[0:15]
	ds_read_b128 v[188:191], v239
	ds_read_b128 v[196:199], v254
	ds_read_b128 v[192:195], v239 offset:4096
	ds_read_b128 v[200:203], v254 offset:4096
	ds_read_b128 v[204:207], v254 offset:8192
	ds_read_b128 v[226:229], v254 offset:12288
	s_waitcnt lgkmcnt(6)
	v_mfma_f32_32x32x16_bf16 v[112:127], v[128:131], v[136:139], v[112:127]
	v_mfma_f32_32x32x16_bf16 v[48:63], v[132:135], v[136:139], v[48:63]
	v_mfma_f32_32x32x16_bf16 v[96:111], v[128:131], v[140:143], v[96:111]
	v_mfma_f32_32x32x16_bf16 v[32:47], v[132:135], v[140:143], v[32:47]
	v_mfma_f32_32x32x16_bf16 v[80:95], v[128:131], v[144:147], v[80:95]
	v_mfma_f32_32x32x16_bf16 v[16:31], v[132:135], v[144:147], v[16:31]
	v_mfma_f32_32x32x16_bf16 v[64:79], v[128:131], v[148:151], v[64:79]
	v_mfma_f32_32x32x16_bf16 v[0:15], v[132:135], v[148:151], v[0:15]
	ds_read_b128 v[128:131], v240
	ds_read_b128 v[136:139], v255
	ds_read_b128 v[132:135], v240 offset:4096
	ds_read_b128 v[140:143], v255 offset:4096
	ds_read_b128 v[144:147], v255 offset:8192
	ds_read_b128 v[148:151], v255 offset:12288
	s_waitcnt lgkmcnt(6)
	v_mfma_f32_32x32x16_bf16 v[112:127], v[188:191], v[196:199], v[112:127]
	v_mfma_f32_32x32x16_bf16 v[48:63], v[192:195], v[196:199], v[48:63]
	v_mfma_f32_32x32x16_bf16 v[96:111], v[188:191], v[200:203], v[96:111]
	v_mfma_f32_32x32x16_bf16 v[32:47], v[192:195], v[200:203], v[32:47]
	v_mfma_f32_32x32x16_bf16 v[80:95], v[188:191], v[204:207], v[80:95]
	v_mfma_f32_32x32x16_bf16 v[16:31], v[192:195], v[204:207], v[16:31]
	v_mfma_f32_32x32x16_bf16 v[64:79], v[188:191], v[226:229], v[64:79]
	v_mfma_f32_32x32x16_bf16 v[0:15], v[192:195], v[226:229], v[0:15]
	s_waitcnt vmcnt(0) lgkmcnt(0)
	s_barrier
	v_mfma_f32_32x32x16_bf16 v[112:127], v[128:131], v[136:139], v[112:127]
	v_mfma_f32_32x32x16_bf16 v[48:63], v[132:135], v[136:139], v[48:63]
	v_mfma_f32_32x32x16_bf16 v[96:111], v[128:131], v[140:143], v[96:111]
	v_mfma_f32_32x32x16_bf16 v[32:47], v[132:135], v[140:143], v[32:47]
	v_mfma_f32_32x32x16_bf16 v[80:95], v[128:131], v[144:147], v[80:95]
	v_mfma_f32_32x32x16_bf16 v[16:31], v[132:135], v[144:147], v[16:31]
	v_mfma_f32_32x32x16_bf16 v[64:79], v[128:131], v[148:151], v[64:79]
	v_mfma_f32_32x32x16_bf16 v[0:15], v[132:135], v[148:151], v[0:15]
	s_lshl_b32 s2, s5, 8
	s_sub_i32 s2, s2, s6
	v_mov_b32_e32 v168, v214
	s_add_i32 s55, s4, s30
	s_or_b32 s26, s2, s31
	s_ashr_i32 s27, s26, 31
	s_load_dwordx2 s[24:25], s[0:1], 0x140
	v_ashrrev_i32_e32 v180, 3, v168
	v_and_b32_e32 v183, -4, v180
	v_add_u32_e32 v225, s55, v183
	v_add_u32_e32 v190, 8, v225
	v_min_i32_e32 v190, 0x7fff, v190
	v_ashrrev_i32_e32 v190, 12, v190
	v_add_u32_e32 v190, 8, v190
	v_mul_hi_i32_i24_e32 v191, 0x3000, v190
	v_mul_i32_i24_e32 v190, 0x3000, v190
	v_min_i32_e32 v184, 0x7fff, v225
	v_ashrrev_i32_e32 v184, 12, v184
	v_and_b32_e32 v182, 31, v168
	v_add_u32_e32 v184, 8, v184
	v_or_b32_e32 v180, s26, v182
	v_mul_hi_i32_i24_e32 v185, 0x3000, v184
	v_mul_i32_i24_e32 v184, 0x3000, v184
	v_ashrrev_i32_e32 v181, 31, v180
	s_waitcnt lgkmcnt(0)
	v_lshl_add_u64 v[184:185], s[24:25], 0, v[184:185]
	v_lshl_add_u64 v[184:185], v[184:185], 0, s[18:19]
	v_lshlrev_b64 v[180:181], 2, v[180:181]
	v_lshl_add_u64 v[196:197], v[184:185], 0, v[180:181]
	v_lshl_add_u64 v[186:187], s[24:25], 0, v[190:191]
	v_add_u32_e32 v188, 9, v225
	v_add_u32_e32 v190, 10, v225
	v_min_i32_e32 v188, 0x7fff, v188
	v_min_i32_e32 v190, 0x7fff, v190
	v_ashrrev_i32_e32 v188, 12, v188
	v_ashrrev_i32_e32 v190, 12, v190
	v_add_u32_e32 v188, 8, v188
	v_add_u32_e32 v190, 8, v190
	v_mul_hi_i32_i24_e32 v189, 0x3000, v188
	v_mul_i32_i24_e32 v188, 0x3000, v188
	v_mul_hi_i32_i24_e32 v191, 0x3000, v190
	v_mul_i32_i24_e32 v190, 0x3000, v190
	v_lshl_add_u64 v[188:189], s[24:25], 0, v[188:189]
	v_lshl_add_u64 v[190:191], s[24:25], 0, v[190:191]
	v_lshl_add_u64 v[186:187], v[186:187], 0, s[18:19]
	v_lshl_add_u64 v[188:189], v[188:189], 0, s[18:19]
	v_lshl_add_u64 v[190:191], v[190:191], 0, s[18:19]
	v_lshl_add_u64 v[206:207], v[186:187], 0, v[180:181]
	v_add_u32_e32 v208, 18, v225
	v_min_i32_e32 v208, 0x7fff, v208
	v_ashrrev_i32_e32 v208, 12, v208
	v_add_u32_e32 v208, 8, v208
	v_mul_hi_i32_i24_e32 v209, 0x3000, v208
	v_mul_i32_i24_e32 v208, 0x3000, v208
	v_lshl_add_u64 v[208:209], s[24:25], 0, v[208:209]
	v_lshl_add_u64 v[202:203], v[188:189], 0, v[180:181]
	v_lshl_add_u64 v[204:205], v[190:191], 0, v[180:181]
	global_load_dword v232, v[196:197], off
	global_load_dword v233, v[196:197], off offset:128
	global_load_dword v242, v[206:207], off
	global_load_dword v243, v[206:207], off offset:128
	global_load_dword v244, v[202:203], off
	global_load_dword v245, v[202:203], off offset:128
	global_load_dword v246, v[204:205], off
	global_load_dword v247, v[204:205], off offset:128
	v_add_u32_e32 v196, 17, v225
	v_min_i32_e32 v196, 0x7fff, v196
	v_ashrrev_i32_e32 v196, 12, v196
	v_add_u32_e32 v196, 8, v196
	v_mul_hi_i32_i24_e32 v197, 0x3000, v196
	v_mul_i32_i24_e32 v196, 0x3000, v196
	v_lshl_add_u64 v[196:197], s[24:25], 0, v[196:197]
	v_lshl_add_u64 v[196:197], v[196:197], 0, s[18:19]
	v_lshl_add_u64 v[206:207], v[196:197], 0, v[180:181]
	s_waitcnt vmcnt(7)
	s_nop 5
	v_mul_f32_e32 v112, v112, v232
	v_add_u32_e32 v192, 11, v225
	v_add_u32_e32 v194, 16, v225
	v_min_i32_e32 v192, 0x7fff, v192
	v_min_i32_e32 v194, 0x7fff, v194
	v_ashrrev_i32_e32 v192, 12, v192
	v_ashrrev_i32_e32 v194, 12, v194
	v_add_u32_e32 v192, 8, v192
	v_add_u32_e32 v194, 8, v194
	v_mul_hi_i32_i24_e32 v193, 0x3000, v192
	v_mul_i32_i24_e32 v192, 0x3000, v192
	v_mul_hi_i32_i24_e32 v195, 0x3000, v194
	v_mul_i32_i24_e32 v194, 0x3000, v194
	v_lshl_add_u64 v[192:193], s[24:25], 0, v[192:193]
	v_lshl_add_u64 v[194:195], s[24:25], 0, v[194:195]
	v_lshl_add_u64 v[192:193], v[192:193], 0, s[18:19]
	v_lshl_add_u64 v[194:195], v[194:195], 0, s[18:19]
	v_lshl_add_u64 v[202:203], v[192:193], 0, v[180:181]
	v_lshl_add_u64 v[204:205], v[194:195], 0, v[180:181]
	s_waitcnt vmcnt(6)
	s_nop 5
	v_mul_f32_e32 v96, v96, v233
	v_mul_f32_e32 v97, v97, v233
	v_lshl_add_u64 v[198:199], v[208:209], 0, s[18:19]
	v_lshl_add_u64 v[200:201], v[198:199], 0, v[180:181]
	global_load_dword v234, v[202:203], off
	global_load_dword v235, v[202:203], off offset:128
	global_load_dword v236, v[204:205], off
	global_load_dword v237, v[204:205], off offset:128
	global_load_dword v238, v[206:207], off
	global_load_dword v239, v[206:207], off offset:128
	global_load_dword v240, v[200:201], off
	global_load_dword v241, v[200:201], off offset:128
	v_add_u32_e32 v200, 19, v225
	v_add_u32_e32 v204, 25, v225
	v_add_u32_e32 v206, 26, v225
	v_min_i32_e32 v200, 0x7fff, v200
	v_add_u32_e32 v202, 24, v225
	v_min_i32_e32 v204, 0x7fff, v204
	v_min_i32_e32 v206, 0x7fff, v206
	v_ashrrev_i32_e32 v200, 12, v200
	v_min_i32_e32 v202, 0x7fff, v202
	v_ashrrev_i32_e32 v204, 12, v204
	v_ashrrev_i32_e32 v206, 12, v206
	v_add_u32_e32 v200, 8, v200
	v_ashrrev_i32_e32 v202, 12, v202
	v_add_u32_e32 v204, 8, v204
	v_add_u32_e32 v206, 8, v206
	v_mul_hi_i32_i24_e32 v201, 0x3000, v200
	v_mul_i32_i24_e32 v200, 0x3000, v200
	v_add_u32_e32 v202, 8, v202
	v_mul_hi_i32_i24_e32 v205, 0x3000, v204
	v_mul_i32_i24_e32 v204, 0x3000, v204
	v_mul_hi_i32_i24_e32 v207, 0x3000, v206
	v_mul_i32_i24_e32 v206, 0x3000, v206
	v_lshl_add_u64 v[200:201], s[24:25], 0, v[200:201]
	v_mul_hi_i32_i24_e32 v203, 0x3000, v202
	v_mul_i32_i24_e32 v202, 0x3000, v202
	v_lshl_add_u64 v[204:205], s[24:25], 0, v[204:205]
	v_lshl_add_u64 v[206:207], s[24:25], 0, v[206:207]
	v_lshl_add_u64 v[200:201], v[200:201], 0, s[18:19]
	v_lshl_add_u64 v[202:203], s[24:25], 0, v[202:203]
	v_lshl_add_u64 v[204:205], v[204:205], 0, s[18:19]
	v_lshl_add_u64 v[206:207], v[206:207], 0, s[18:19]
	v_lshl_add_u64 v[208:209], v[200:201], 0, v[180:181]
	v_lshl_add_u64 v[202:203], v[202:203], 0, s[18:19]
	v_lshl_add_u64 v[228:229], v[204:205], 0, v[180:181]
	v_lshl_add_u64 v[230:231], v[206:207], 0, v[180:181]
	v_lshl_add_u64 v[226:227], v[202:203], 0, v[180:181]
	global_load_dword v248, v[208:209], off
	global_load_dword v249, v[208:209], off offset:128
	global_load_dword v250, v[226:227], off
	global_load_dword v251, v[226:227], off offset:128
	global_load_dword v252, v[228:229], off
	s_nop 0
	global_load_dword v228, v[228:229], off offset:128
	s_nop 0
	global_load_dword v229, v[230:231], off
	s_nop 0
	global_load_dword v230, v[230:231], off offset:128
	v_add_u32_e32 v208, 27, v225
	v_min_i32_e32 v208, 0x7fff, v208
	v_ashrrev_i32_e32 v208, 12, v208
	v_add_u32_e32 v208, 8, v208
	v_mul_hi_i32_i24_e32 v209, 0x3000, v208
	v_mul_i32_i24_e32 v208, 0x3000, v208
	v_lshl_add_u64 v[208:209], s[24:25], 0, v[208:209]
	v_lshl_add_u64 v[208:209], v[208:209], 0, s[18:19]
	v_lshl_add_u64 v[226:227], v[208:209], 0, v[180:181]
	global_load_dword v225, v[226:227], off
	s_nop 0
	global_load_dword v226, v[226:227], off offset:128
	v_mad_u64_u32 v[160:161], s[2:3], v183, s36, v[182:183]
	v_lshl_add_u32 v162, v160, 2, s34
	ds_write2_b32 v162, v112, v96 offset1:32
	v_mul_f32_e32 v96, v113, v232
	ds_write2_b32 v162, v96, v97 offset0:68 offset1:100
	v_mul_f32_e32 v96, v114, v232
	v_mul_f32_e32 v97, v98, v233
	ds_write2_b32 v162, v96, v97 offset0:136 offset1:168
	v_mul_f32_e32 v96, v115, v232
	v_mul_f32_e32 v97, v99, v233
	ds_write2_b32 v162, v96, v97 offset0:204 offset1:236
	s_waitcnt vmcnt(23)
	v_mul_f32_e32 v96, v116, v242
	s_waitcnt vmcnt(22)
	v_mul_f32_e32 v97, v100, v243
	v_add_u32_e32 v115, 0x800, v162
	ds_write2_b32 v115, v96, v97 offset0:32 offset1:64
	s_waitcnt vmcnt(21)
	v_mul_f32_e32 v96, v117, v244
	s_waitcnt vmcnt(20)
	v_mul_f32_e32 v97, v101, v245
	ds_write2_b32 v115, v96, v97 offset0:100 offset1:132
	s_waitcnt vmcnt(19)
	v_mul_f32_e32 v96, v118, v246
	s_waitcnt vmcnt(18)
	v_mul_f32_e32 v97, v102, v247
	ds_write2_b32 v115, v96, v97 offset0:168 offset1:200
	v_add_u32_e32 v116, 0xa00, v162
	v_add_u32_e32 v117, 0x1000, v162
	s_waitcnt vmcnt(17)
	v_mul_f32_e32 v96, v119, v234
	s_waitcnt vmcnt(16)
	v_mul_f32_e32 v97, v103, v235
	ds_write2_b32 v116, v96, v97 offset0:108 offset1:140
	s_waitcnt vmcnt(15)
	v_mul_f32_e32 v96, v120, v236
	s_waitcnt vmcnt(14)
	v_mul_f32_e32 v97, v104, v237
	ds_write2_b32 v117, v96, v97 offset0:64 offset1:96
	s_waitcnt vmcnt(13)
	v_mul_f32_e32 v96, v121, v238
	s_waitcnt vmcnt(12)
	v_mul_f32_e32 v97, v105, v239
	ds_write2_b32 v117, v96, v97 offset0:132 offset1:164
	s_waitcnt vmcnt(11)
	v_mul_f32_e32 v96, v122, v240
	s_waitcnt vmcnt(10)
	v_mul_f32_e32 v97, v106, v241
	ds_write2_b32 v117, v96, v97 offset0:200 offset1:232
	v_add_u32_e32 v118, 0x1400, v162
	v_add_u32_e32 v119, 0x1800, v162
	v_ashrrev_i32_e32 v163, 4, v168
	v_and_b32_e32 v160, 15, v168
	v_add_u32_e32 v120, 0x1a00, v162
	v_mul_lo_u32 v164, v163, s37
	v_lshl_add_u32 v165, v160, 4, s34
	v_lshlrev_b32_e32 v168, 2, v160
	v_add_u32_e32 v160, s55, v163
	v_add_u32_e32 v121, 0x1c00, v162
	v_cmp_gt_i32_e32 vcc, s38, v160
	v_ashrrev_i32_e32 v161, 31, v160
	v_add_u32_e32 v114, v165, v164
	s_waitcnt vmcnt(9)
	v_mul_f32_e32 v96, v123, v248
	s_waitcnt vmcnt(8)
	v_mul_f32_e32 v97, v107, v249
	ds_write2_b32 v118, v96, v97 offset0:12 offset1:44
	s_waitcnt vmcnt(7)
	v_mul_f32_e32 v96, v124, v250
	s_waitcnt vmcnt(6)
	v_mul_f32_e32 v97, v108, v251
	ds_write2_b32 v119, v96, v97 offset0:96 offset1:128
	s_waitcnt vmcnt(5)
	v_mul_f32_e32 v96, v125, v252
	s_waitcnt vmcnt(4)
	v_mul_f32_e32 v97, v109, v228
	ds_write2_b32 v119, v96, v97 offset0:164 offset1:196
	s_waitcnt vmcnt(3)
	v_mul_f32_e32 v96, v126, v229
	s_waitcnt vmcnt(2)
	v_mul_f32_e32 v97, v110, v230
	ds_write2_b32 v120, v96, v97 offset0:104 offset1:136
	s_waitcnt vmcnt(1)
	v_mul_f32_e32 v96, v127, v225
	s_waitcnt vmcnt(0)
	v_mul_f32_e32 v97, v111, v226
	ds_write2_b32 v121, v96, v97 offset0:44 offset1:76
	v_or_b32_e32 v96, s26, v168
	v_mov_b32_e32 v97, s27
	v_add_u32_e32 v128, 0, v160
	v_ashrrev_i32_e32 v129, 31, v128
	v_lshlrev_b64 v[128:129], 12, v[128:129]
	v_lshl_add_u64 v[128:129], s[16:17], 0, v[128:129]
	v_lshl_add_u64 v[128:129], v[96:97], 2, v[128:129]
	global_load_dwordx4 v[128:131], v[128:129], off nt
	v_add_u32_e32 v132, 4, v160
	v_ashrrev_i32_e32 v133, 31, v132
	v_lshlrev_b64 v[132:133], 12, v[132:133]
	v_lshl_add_u64 v[132:133], s[16:17], 0, v[132:133]
	v_lshl_add_u64 v[132:133], v[96:97], 2, v[132:133]
	global_load_dwordx4 v[132:135], v[132:133], off nt
	v_add_u32_e32 v136, 8, v160
	v_ashrrev_i32_e32 v137, 31, v136
	v_lshlrev_b64 v[136:137], 12, v[136:137]
	v_lshl_add_u64 v[136:137], s[16:17], 0, v[136:137]
	v_lshl_add_u64 v[136:137], v[96:97], 2, v[136:137]
	global_load_dwordx4 v[136:139], v[136:137], off nt
	v_add_u32_e32 v140, 12, v160
	v_ashrrev_i32_e32 v141, 31, v140
	v_lshlrev_b64 v[140:141], 12, v[140:141]
	v_lshl_add_u64 v[140:141], s[16:17], 0, v[140:141]
	v_lshl_add_u64 v[140:141], v[96:97], 2, v[140:141]
	global_load_dwordx4 v[140:143], v[140:141], off nt
	v_add_u32_e32 v144, 16, v160
	v_ashrrev_i32_e32 v145, 31, v144
	v_lshlrev_b64 v[144:145], 12, v[144:145]
	v_lshl_add_u64 v[144:145], s[16:17], 0, v[144:145]
	v_lshl_add_u64 v[144:145], v[96:97], 2, v[144:145]
	global_load_dwordx4 v[144:147], v[144:145], off nt
	v_add_u32_e32 v148, 20, v160
	v_ashrrev_i32_e32 v149, 31, v148
	v_lshlrev_b64 v[148:149], 12, v[148:149]
	v_lshl_add_u64 v[148:149], s[16:17], 0, v[148:149]
	v_lshl_add_u64 v[148:149], v[96:97], 2, v[148:149]
	global_load_dwordx4 v[148:151], v[148:149], off nt
	v_add_u32_e32 v152, 24, v160
	v_ashrrev_i32_e32 v153, 31, v152
	v_lshlrev_b64 v[152:153], 12, v[152:153]
	v_lshl_add_u64 v[152:153], s[16:17], 0, v[152:153]
	v_lshl_add_u64 v[152:153], v[96:97], 2, v[152:153]
	global_load_dwordx4 v[152:155], v[152:153], off nt
	v_add_u32_e32 v156, 28, v160
	v_ashrrev_i32_e32 v157, 31, v156
	v_lshlrev_b64 v[156:157], 12, v[156:157]
	v_lshl_add_u64 v[156:157], s[16:17], 0, v[156:157]
	v_lshl_add_u64 v[156:157], v[96:97], 2, v[156:157]
	global_load_dwordx4 v[156:159], v[156:157], off nt
	s_and_saveexec_b64 s[2:3], vcc
	s_cbranch_execz .LBB0_2225
	v_lshlrev_b64 v[98:99], 12, v[160:161]
	v_lshl_add_u64 v[98:99], s[16:17], 0, v[98:99]
	v_lshl_add_u64 v[106:107], v[96:97], 2, v[98:99]
	ds_read_b128 v[102:105], v114
	s_waitcnt vmcnt(7) lgkmcnt(0)
	v_pk_add_f32 v[100:101], v[104:105], v[130:131]
	v_pk_add_f32 v[98:99], v[102:103], v[128:129]
	global_store_dwordx4 v[106:107], v[98:101], off

.LBB0_2239:
	s_or_b64 exec, exec, s[28:29]
	v_add3_u32 v98, v182, s26, 64
	v_ashrrev_i32_e32 v99, 31, v98
	v_lshlrev_b64 v[98:99], 2, v[98:99]
	v_lshl_add_u64 v[122:123], v[184:185], 0, v[98:99]
	v_lshl_add_u64 v[124:125], v[186:187], 0, v[98:99]
	v_lshl_add_u64 v[126:127], v[188:189], 0, v[98:99]
	v_lshl_add_u64 v[164:165], v[190:191], 0, v[98:99]
	global_load_dword v166, v[122:123], off
	global_load_dword v167, v[122:123], off offset:128
	global_load_dword v182, v[124:125], off
	global_load_dword v184, v[124:125], off offset:128
	global_load_dword v185, v[126:127], off
	global_load_dword v186, v[126:127], off offset:128
	global_load_dword v187, v[164:165], off
	global_load_dword v188, v[164:165], off offset:128
	v_lshl_add_u64 v[122:123], v[192:193], 0, v[98:99]
	v_lshl_add_u64 v[124:125], v[194:195], 0, v[98:99]
	v_lshl_add_u64 v[126:127], v[196:197], 0, v[98:99]
	v_lshl_add_u64 v[164:165], v[198:199], 0, v[98:99]
	global_load_dword v189, v[122:123], off
	global_load_dword v190, v[122:123], off offset:128
	global_load_dword v191, v[124:125], off
	global_load_dword v192, v[124:125], off offset:128
	global_load_dword v193, v[126:127], off
	global_load_dword v194, v[126:127], off offset:128
	global_load_dword v195, v[164:165], off
	global_load_dword v196, v[164:165], off offset:128
	v_lshl_add_u64 v[122:123], v[200:201], 0, v[98:99]
	v_lshl_add_u64 v[124:125], v[202:203], 0, v[98:99]
	v_lshl_add_u64 v[126:127], v[204:205], 0, v[98:99]
	v_lshl_add_u64 v[164:165], v[206:207], 0, v[98:99]
	global_load_dword v197, v[122:123], off
	global_load_dword v198, v[122:123], off offset:128
	global_load_dword v199, v[124:125], off
	s_nop 0
	global_load_dword v124, v[124:125], off offset:128
	s_nop 0
	global_load_dword v125, v[126:127], off
	s_nop 0
	global_load_dword v126, v[126:127], off offset:128
	s_nop 0
	global_load_dword v127, v[164:165], off
	s_nop 0
	global_load_dword v164, v[164:165], off offset:128
	v_lshl_add_u64 v[122:123], v[208:209], 0, v[98:99]
	global_load_dword v165, v[122:123], off
	s_nop 0
	global_load_dword v122, v[122:123], off offset:128
	s_waitcnt vmcnt(25)
	v_mul_f32_e32 v80, v80, v166
	s_waitcnt vmcnt(24)
	v_mul_f32_e32 v64, v64, v167
	v_mul_f32_e32 v65, v65, v167
	v_mul_f32_e32 v81, v81, v166
	v_mul_f32_e32 v82, v82, v166
	v_mul_f32_e32 v66, v66, v167
	v_mul_f32_e32 v83, v83, v166
	v_mul_f32_e32 v67, v67, v167
	s_waitcnt vmcnt(23)
	v_mul_f32_e32 v84, v84, v182
	s_waitcnt vmcnt(22)
	v_mul_f32_e32 v68, v68, v184
	s_waitcnt vmcnt(21)
	v_mul_f32_e32 v85, v85, v185
	s_waitcnt vmcnt(20)
	v_mul_f32_e32 v69, v69, v186
	s_waitcnt vmcnt(19)
	v_mul_f32_e32 v86, v86, v187
	s_waitcnt vmcnt(18)
	v_mul_f32_e32 v70, v70, v188
	s_waitcnt vmcnt(17)
	v_mul_f32_e32 v87, v87, v189
	s_waitcnt vmcnt(16)
	v_mul_f32_e32 v71, v71, v190
	s_waitcnt vmcnt(15)
	v_mul_f32_e32 v88, v88, v191
	s_waitcnt vmcnt(14)
	v_mul_f32_e32 v72, v72, v192
	s_waitcnt vmcnt(13)
	v_mul_f32_e32 v89, v89, v193
	s_waitcnt vmcnt(12)
	v_mul_f32_e32 v73, v73, v194
	s_waitcnt vmcnt(11)
	v_mul_f32_e32 v90, v90, v195
	s_waitcnt vmcnt(10)
	v_mul_f32_e32 v74, v74, v196
	s_waitcnt vmcnt(9)
	v_mul_f32_e32 v91, v91, v197
	s_waitcnt vmcnt(8)
	v_mul_f32_e32 v75, v75, v198
	s_waitcnt vmcnt(7)
	v_mul_f32_e32 v92, v92, v199
	s_waitcnt vmcnt(6)
	v_mul_f32_e32 v76, v76, v124
	s_waitcnt vmcnt(5)
	v_mul_f32_e32 v93, v93, v125
	s_waitcnt vmcnt(4)
	v_mul_f32_e32 v77, v77, v126
	s_waitcnt vmcnt(3)
	v_mul_f32_e32 v94, v94, v127
	s_waitcnt vmcnt(2)
	v_mul_f32_e32 v78, v78, v164
	ds_write2_b32 v162, v80, v64 offset1:32
	ds_write2_b32 v162, v81, v65 offset0:68 offset1:100
	ds_write2_b32 v162, v82, v66 offset0:136 offset1:168
	ds_write2_b32 v162, v83, v67 offset0:204 offset1:236
	ds_write2_b32 v115, v84, v68 offset0:32 offset1:64
	ds_write2_b32 v115, v85, v69 offset0:100 offset1:132
	ds_write2_b32 v115, v86, v70 offset0:168 offset1:200
	ds_write2_b32 v116, v87, v71 offset0:108 offset1:140
	ds_write2_b32 v117, v88, v72 offset0:64 offset1:96
	ds_write2_b32 v117, v89, v73 offset0:132 offset1:164
	ds_write2_b32 v117, v90, v74 offset0:200 offset1:232
	ds_write2_b32 v118, v91, v75 offset0:12 offset1:44
	ds_write2_b32 v119, v92, v76 offset0:96 offset1:128
	ds_write2_b32 v119, v93, v77 offset0:164 offset1:196
	ds_write2_b32 v120, v94, v78 offset0:104 offset1:136
	s_waitcnt vmcnt(1)
	v_mul_f32_e32 v64, v95, v165
	s_waitcnt vmcnt(0)
	v_mul_f32_e32 v65, v79, v122
	ds_write2_b32 v121, v64, v65 offset0:44 offset1:76
	v_lshl_add_u64 v[64:65], v[168:169], 0, s[26:27]
	v_add_u32_e32 v128, 0, v160
	v_ashrrev_i32_e32 v129, 31, v128
	v_lshlrev_b64 v[128:129], 12, v[128:129]
	v_lshl_add_u64 v[128:129], s[16:17], 0, v[128:129]
	v_lshl_add_u64 v[128:129], v[64:65], 2, v[128:129]
	global_load_dwordx4 v[128:131], v[128:129], off offset:256 nt
	v_add_u32_e32 v132, 4, v160
	v_ashrrev_i32_e32 v133, 31, v132
	v_lshlrev_b64 v[132:133], 12, v[132:133]
	v_lshl_add_u64 v[132:133], s[16:17], 0, v[132:133]
	v_lshl_add_u64 v[132:133], v[64:65], 2, v[132:133]
	global_load_dwordx4 v[132:135], v[132:133], off offset:256 nt
	v_add_u32_e32 v136, 8, v160
	v_ashrrev_i32_e32 v137, 31, v136
	v_lshlrev_b64 v[136:137], 12, v[136:137]
	v_lshl_add_u64 v[136:137], s[16:17], 0, v[136:137]
	v_lshl_add_u64 v[136:137], v[64:65], 2, v[136:137]
	global_load_dwordx4 v[136:139], v[136:137], off offset:256 nt
	v_add_u32_e32 v140, 12, v160
	v_ashrrev_i32_e32 v141, 31, v140
	v_lshlrev_b64 v[140:141], 12, v[140:141]
	v_lshl_add_u64 v[140:141], s[16:17], 0, v[140:141]
	v_lshl_add_u64 v[140:141], v[64:65], 2, v[140:141]
	global_load_dwordx4 v[140:143], v[140:141], off offset:256 nt
	v_add_u32_e32 v144, 16, v160
	v_ashrrev_i32_e32 v145, 31, v144
	v_lshlrev_b64 v[144:145], 12, v[144:145]
	v_lshl_add_u64 v[144:145], s[16:17], 0, v[144:145]
	v_lshl_add_u64 v[144:145], v[64:65], 2, v[144:145]
	global_load_dwordx4 v[144:147], v[144:145], off offset:256 nt
	v_add_u32_e32 v148, 20, v160
	v_ashrrev_i32_e32 v149, 31, v148
	v_lshlrev_b64 v[148:149], 12, v[148:149]
	v_lshl_add_u64 v[148:149], s[16:17], 0, v[148:149]
	v_lshl_add_u64 v[148:149], v[64:65], 2, v[148:149]
	global_load_dwordx4 v[148:151], v[148:149], off offset:256 nt
	v_add_u32_e32 v152, 24, v160
	v_ashrrev_i32_e32 v153, 31, v152
	v_lshlrev_b64 v[152:153], 12, v[152:153]
	v_lshl_add_u64 v[152:153], s[16:17], 0, v[152:153]
	v_lshl_add_u64 v[152:153], v[64:65], 2, v[152:153]
	global_load_dwordx4 v[152:155], v[152:153], off offset:256 nt
	v_add_u32_e32 v156, 28, v160
	v_ashrrev_i32_e32 v157, 31, v156
	v_lshlrev_b64 v[156:157], 12, v[156:157]
	v_lshl_add_u64 v[156:157], s[16:17], 0, v[156:157]
	v_lshl_add_u64 v[156:157], v[64:65], 2, v[156:157]
	global_load_dwordx4 v[156:159], v[156:157], off offset:256 nt
	s_and_saveexec_b64 s[26:27], vcc
	s_cbranch_execz .LBB0_2247
	v_lshlrev_b64 v[66:67], 12, v[160:161]
	v_lshl_add_u64 v[66:67], s[16:17], 0, v[66:67]
	v_lshl_add_u64 v[74:75], v[64:65], 2, v[66:67]
	ds_read_b128 v[70:73], v114
	s_waitcnt vmcnt(7) lgkmcnt(0)
	v_pk_add_f32 v[68:69], v[72:73], v[130:131]
	v_pk_add_f32 v[66:67], v[70:71], v[128:129]
	global_store_dwordx4 v[74:75], v[66:69], off offset:256
	s_or_b64 exec, exec, s[26:27]
	s_and_saveexec_b64 s[26:27], s[2:3]
	s_cbranch_execnz .LBB0_2248

.LBB0_2255:
	s_or_b64 exec, exec, s[2:3]
	s_or_b32 s2, s55, 32
	v_add_u32_e32 v102, s2, v183
	v_min_i32_e32 v66, 0x7fff, v102
	v_add_u32_e32 v68, 8, v102
	v_add_u32_e32 v70, 9, v102
	v_add_u32_e32 v72, 10, v102
	v_ashrrev_i32_e32 v66, 12, v66
	v_min_i32_e32 v68, 0x7fff, v68
	v_min_i32_e32 v70, 0x7fff, v70
	v_min_i32_e32 v72, 0x7fff, v72
	v_add_u32_e32 v66, 8, v66
	v_ashrrev_i32_e32 v68, 12, v68
	v_ashrrev_i32_e32 v70, 12, v70
	v_ashrrev_i32_e32 v72, 12, v72
	v_mul_hi_i32_i24_e32 v67, 0x3000, v66
	v_mul_i32_i24_e32 v66, 0x3000, v66
	v_add_u32_e32 v68, 8, v68
	v_add_u32_e32 v70, 8, v70
	v_add_u32_e32 v72, 8, v72
	v_lshl_add_u64 v[66:67], s[24:25], 0, v[66:67]
	v_mul_hi_i32_i24_e32 v69, 0x3000, v68
	v_mul_i32_i24_e32 v68, 0x3000, v68
	v_mul_hi_i32_i24_e32 v71, 0x3000, v70
	v_mul_i32_i24_e32 v70, 0x3000, v70
	v_mul_hi_i32_i24_e32 v73, 0x3000, v72
	v_mul_i32_i24_e32 v72, 0x3000, v72
	v_lshl_add_u64 v[66:67], v[66:67], 0, s[18:19]
	v_lshl_add_u64 v[68:69], s[24:25], 0, v[68:69]
	v_lshl_add_u64 v[70:71], s[24:25], 0, v[70:71]
	v_lshl_add_u64 v[72:73], s[24:25], 0, v[72:73]
	v_lshl_add_u64 v[74:75], v[66:67], 0, v[180:181]
	v_lshl_add_u64 v[68:69], v[68:69], 0, s[18:19]
	v_lshl_add_u64 v[70:71], v[70:71], 0, s[18:19]
	v_lshl_add_u64 v[72:73], v[72:73], 0, s[18:19]
	v_lshl_add_u64 v[76:77], v[68:69], 0, v[180:181]
	v_lshl_add_u64 v[78:79], v[70:71], 0, v[180:181]
	v_lshl_add_u64 v[80:81], v[72:73], 0, v[180:181]
	global_load_dword v103, v[74:75], off
	global_load_dword v104, v[74:75], off offset:128
	global_load_dword v105, v[76:77], off
	global_load_dword v106, v[76:77], off offset:128
	global_load_dword v107, v[78:79], off
	global_load_dword v108, v[78:79], off offset:128
	global_load_dword v109, v[80:81], off
	global_load_dword v110, v[80:81], off offset:128
	v_add_u32_e32 v74, 11, v102
	v_add_u32_e32 v82, 18, v102
	v_min_i32_e32 v74, 0x7fff, v74
	v_add_u32_e32 v76, 16, v102
	v_add_u32_e32 v78, 17, v102
	v_min_i32_e32 v82, 0x7fff, v82
	v_ashrrev_i32_e32 v74, 12, v74
	v_min_i32_e32 v76, 0x7fff, v76
	v_min_i32_e32 v78, 0x7fff, v78
	v_ashrrev_i32_e32 v82, 12, v82
	v_add_u32_e32 v74, 8, v74
	v_ashrrev_i32_e32 v76, 12, v76
	v_ashrrev_i32_e32 v78, 12, v78
	v_add_u32_e32 v82, 8, v82
	v_mul_hi_i32_i24_e32 v75, 0x3000, v74
	v_mul_i32_i24_e32 v74, 0x3000, v74
	v_add_u32_e32 v76, 8, v76
	v_add_u32_e32 v78, 8, v78
	v_mul_hi_i32_i24_e32 v83, 0x3000, v82
	v_mul_i32_i24_e32 v82, 0x3000, v82
	v_lshl_add_u64 v[74:75], s[24:25], 0, v[74:75]
	v_mul_hi_i32_i24_e32 v77, 0x3000, v76
	v_mul_i32_i24_e32 v76, 0x3000, v76
	v_mul_hi_i32_i24_e32 v79, 0x3000, v78
	v_mul_i32_i24_e32 v78, 0x3000, v78
	v_lshl_add_u64 v[82:83], s[24:25], 0, v[82:83]
	v_lshl_add_u64 v[74:75], v[74:75], 0, s[18:19]
	v_lshl_add_u64 v[76:77], s[24:25], 0, v[76:77]
	v_lshl_add_u64 v[78:79], s[24:25], 0, v[78:79]
	v_lshl_add_u64 v[82:83], v[82:83], 0, s[18:19]
	v_lshl_add_u64 v[80:81], v[74:75], 0, v[180:181]
	v_lshl_add_u64 v[76:77], v[76:77], 0, s[18:19]
	v_lshl_add_u64 v[78:79], v[78:79], 0, s[18:19]
	v_lshl_add_u64 v[88:89], v[82:83], 0, v[180:181]
	v_lshl_add_u64 v[84:85], v[76:77], 0, v[180:181]
	v_lshl_add_u64 v[86:87], v[78:79], 0, v[180:181]
	global_load_dword v111, v[80:81], off
	global_load_dword v112, v[80:81], off offset:128
	global_load_dword v113, v[84:85], off
	global_load_dword v122, v[84:85], off offset:128
	global_load_dword v123, v[86:87], off
	global_load_dword v124, v[86:87], off offset:128
	global_load_dword v125, v[88:89], off
	global_load_dword v126, v[88:89], off offset:128
	v_add_u32_e32 v80, 19, v102
	v_add_u32_e32 v88, 25, v102
	v_add_u32_e32 v90, 26, v102
	v_min_i32_e32 v80, 0x7fff, v80
	v_add_u32_e32 v86, 24, v102
	v_min_i32_e32 v88, 0x7fff, v88
	v_min_i32_e32 v90, 0x7fff, v90
	v_ashrrev_i32_e32 v80, 12, v80
	v_min_i32_e32 v86, 0x7fff, v86
	v_ashrrev_i32_e32 v88, 12, v88
	v_ashrrev_i32_e32 v90, 12, v90
	v_add_u32_e32 v80, 8, v80
	v_ashrrev_i32_e32 v86, 12, v86
	v_add_u32_e32 v88, 8, v88
	v_add_u32_e32 v90, 8, v90
	v_mul_hi_i32_i24_e32 v81, 0x3000, v80
	v_mul_i32_i24_e32 v80, 0x3000, v80
	v_add_u32_e32 v86, 8, v86
	v_mul_hi_i32_i24_e32 v89, 0x3000, v88
	v_mul_i32_i24_e32 v88, 0x3000, v88
	v_mul_hi_i32_i24_e32 v91, 0x3000, v90
	v_mul_i32_i24_e32 v90, 0x3000, v90
	v_lshl_add_u64 v[80:81], s[24:25], 0, v[80:81]
	v_mul_hi_i32_i24_e32 v87, 0x3000, v86
	v_mul_i32_i24_e32 v86, 0x3000, v86
	v_lshl_add_u64 v[88:89], s[24:25], 0, v[88:89]
	v_lshl_add_u64 v[90:91], s[24:25], 0, v[90:91]
	v_lshl_add_u64 v[84:85], v[80:81], 0, s[18:19]
	v_lshl_add_u64 v[86:87], s[24:25], 0, v[86:87]
	v_lshl_add_u64 v[88:89], v[88:89], 0, s[18:19]
	v_lshl_add_u64 v[90:91], v[90:91], 0, s[18:19]
	v_lshl_add_u64 v[80:81], v[84:85], 0, v[180:181]
	v_lshl_add_u64 v[86:87], v[86:87], 0, s[18:19]
	v_lshl_add_u64 v[94:95], v[88:89], 0, v[180:181]
	v_lshl_add_u64 v[100:101], v[90:91], 0, v[180:181]
	v_lshl_add_u64 v[92:93], v[86:87], 0, v[180:181]
	global_load_dword v127, v[80:81], off
	global_load_dword v160, v[80:81], off offset:128
	global_load_dword v161, v[92:93], off
	global_load_dword v164, v[92:93], off offset:128
	global_load_dword v165, v[94:95], off
	s_nop 0
	global_load_dword v94, v[94:95], off offset:128
	s_nop 0
	global_load_dword v95, v[100:101], off
	s_nop 0
	global_load_dword v100, v[100:101], off offset:128
	v_add_u32_e32 v80, 27, v102
	v_min_i32_e32 v80, 0x7fff, v80
	v_ashrrev_i32_e32 v80, 12, v80
	v_add_u32_e32 v80, 8, v80
	v_mul_hi_i32_i24_e32 v81, 0x3000, v80
	v_mul_i32_i24_e32 v80, 0x3000, v80
	v_lshl_add_u64 v[80:81], s[24:25], 0, v[80:81]
	v_lshl_add_u64 v[92:93], v[80:81], 0, s[18:19]
	v_lshl_add_u64 v[80:81], v[92:93], 0, v[180:181]
	global_load_dword v101, v[80:81], off
	s_nop 0
	global_load_dword v81, v[80:81], off offset:128
	s_waitcnt vmcnt(25)
	v_mul_f32_e32 v48, v48, v103
	s_waitcnt vmcnt(24)
	v_mul_f32_e32 v32, v32, v104
	ds_write2_b32 v162, v48, v32 offset1:32
	v_mul_f32_e32 v32, v49, v103
	v_mul_f32_e32 v33, v33, v104
	ds_write2_b32 v162, v32, v33 offset0:68 offset1:100
	v_mul_f32_e32 v32, v50, v103
	v_mul_f32_e32 v33, v34, v104
	ds_write2_b32 v162, v32, v33 offset0:136 offset1:168
	v_mul_f32_e32 v32, v51, v103
	v_mul_f32_e32 v33, v35, v104
	ds_write2_b32 v162, v32, v33 offset0:204 offset1:236
	s_waitcnt vmcnt(23)
	v_mul_f32_e32 v32, v52, v105
	s_waitcnt vmcnt(22)
	v_mul_f32_e32 v33, v36, v106
	ds_write2_b32 v115, v32, v33 offset0:32 offset1:64
	s_waitcnt vmcnt(21)
	v_mul_f32_e32 v32, v53, v107
	s_waitcnt vmcnt(20)
	v_mul_f32_e32 v33, v37, v108
	ds_write2_b32 v115, v32, v33 offset0:100 offset1:132
	s_waitcnt vmcnt(19)
	v_mul_f32_e32 v32, v54, v109
	s_waitcnt vmcnt(18)
	v_mul_f32_e32 v33, v38, v110
	ds_write2_b32 v115, v32, v33 offset0:168 offset1:200
	v_add_u32_e32 v80, s2, v163
	v_cmp_gt_i32_e32 vcc, s38, v80
	s_waitcnt vmcnt(17)
	v_mul_f32_e32 v32, v55, v111
	s_waitcnt vmcnt(16)
	v_mul_f32_e32 v33, v39, v112
	ds_write2_b32 v116, v32, v33 offset0:108 offset1:140
	s_waitcnt vmcnt(15)
	v_mul_f32_e32 v32, v56, v113
	s_waitcnt vmcnt(14)
	v_mul_f32_e32 v33, v40, v122
	ds_write2_b32 v117, v32, v33 offset0:64 offset1:96
	s_waitcnt vmcnt(13)
	v_mul_f32_e32 v32, v57, v123
	s_waitcnt vmcnt(12)
	v_mul_f32_e32 v33, v41, v124
	ds_write2_b32 v117, v32, v33 offset0:132 offset1:164
	s_waitcnt vmcnt(11)
	v_mul_f32_e32 v32, v58, v125
	s_waitcnt vmcnt(10)
	v_mul_f32_e32 v33, v42, v126
	ds_write2_b32 v117, v32, v33 offset0:200 offset1:232
	s_waitcnt vmcnt(9)
	v_mul_f32_e32 v32, v59, v127
	s_waitcnt vmcnt(8)
	v_mul_f32_e32 v33, v43, v160
	ds_write2_b32 v118, v32, v33 offset0:12 offset1:44
	s_waitcnt vmcnt(7)
	v_mul_f32_e32 v32, v60, v161
	s_waitcnt vmcnt(6)
	v_mul_f32_e32 v33, v44, v164
	ds_write2_b32 v119, v32, v33 offset0:96 offset1:128
	s_waitcnt vmcnt(5)
	v_mul_f32_e32 v32, v61, v165
	s_waitcnt vmcnt(4)
	v_mul_f32_e32 v33, v45, v94
	ds_write2_b32 v119, v32, v33 offset0:164 offset1:196
	s_waitcnt vmcnt(3)
	v_mul_f32_e32 v32, v62, v95
	s_waitcnt vmcnt(2)
	v_mul_f32_e32 v33, v46, v100
	ds_write2_b32 v120, v32, v33 offset0:104 offset1:136
	s_waitcnt vmcnt(1)
	v_mul_f32_e32 v32, v63, v101
	s_waitcnt vmcnt(0)
	v_mul_f32_e32 v33, v47, v81
	v_ashrrev_i32_e32 v81, 31, v80
	ds_write2_b32 v121, v32, v33 offset0:44 offset1:76
	v_add_u32_e32 v128, 0, v80
	v_ashrrev_i32_e32 v129, 31, v128
	v_lshlrev_b64 v[128:129], 12, v[128:129]
	v_lshl_add_u64 v[128:129], s[16:17], 0, v[128:129]
	v_lshl_add_u64 v[128:129], v[96:97], 2, v[128:129]
	global_load_dwordx4 v[128:131], v[128:129], off nt
	v_add_u32_e32 v132, 4, v80
	v_ashrrev_i32_e32 v133, 31, v132
	v_lshlrev_b64 v[132:133], 12, v[132:133]
	v_lshl_add_u64 v[132:133], s[16:17], 0, v[132:133]
	v_lshl_add_u64 v[132:133], v[96:97], 2, v[132:133]
	global_load_dwordx4 v[132:135], v[132:133], off nt
	v_add_u32_e32 v136, 8, v80
	v_ashrrev_i32_e32 v137, 31, v136
	v_lshlrev_b64 v[136:137], 12, v[136:137]
	v_lshl_add_u64 v[136:137], s[16:17], 0, v[136:137]
	v_lshl_add_u64 v[136:137], v[96:97], 2, v[136:137]
	global_load_dwordx4 v[136:139], v[136:137], off nt
	v_add_u32_e32 v140, 12, v80
	v_ashrrev_i32_e32 v141, 31, v140
	v_lshlrev_b64 v[140:141], 12, v[140:141]
	v_lshl_add_u64 v[140:141], s[16:17], 0, v[140:141]
	v_lshl_add_u64 v[140:141], v[96:97], 2, v[140:141]
	global_load_dwordx4 v[140:143], v[140:141], off nt
	v_add_u32_e32 v144, 16, v80
	v_ashrrev_i32_e32 v145, 31, v144
	v_lshlrev_b64 v[144:145], 12, v[144:145]
	v_lshl_add_u64 v[144:145], s[16:17], 0, v[144:145]
	v_lshl_add_u64 v[144:145], v[96:97], 2, v[144:145]
	global_load_dwordx4 v[144:147], v[144:145], off nt
	v_add_u32_e32 v148, 20, v80
	v_ashrrev_i32_e32 v149, 31, v148
	v_lshlrev_b64 v[148:149], 12, v[148:149]
	v_lshl_add_u64 v[148:149], s[16:17], 0, v[148:149]
	v_lshl_add_u64 v[148:149], v[96:97], 2, v[148:149]
	global_load_dwordx4 v[148:151], v[148:149], off nt
	v_add_u32_e32 v152, 24, v80
	v_ashrrev_i32_e32 v153, 31, v152
	v_lshlrev_b64 v[152:153], 12, v[152:153]
	v_lshl_add_u64 v[152:153], s[16:17], 0, v[152:153]
	v_lshl_add_u64 v[152:153], v[96:97], 2, v[152:153]
	global_load_dwordx4 v[152:155], v[152:153], off nt
	v_add_u32_e32 v156, 28, v80
	v_ashrrev_i32_e32 v157, 31, v156
	v_lshlrev_b64 v[156:157], 12, v[156:157]
	v_lshl_add_u64 v[156:157], s[16:17], 0, v[156:157]
	v_lshl_add_u64 v[156:157], v[96:97], 2, v[156:157]
	global_load_dwordx4 v[156:159], v[156:157], off nt
	s_and_saveexec_b64 s[2:3], vcc
	s_cbranch_execz .LBB0_2257
	v_lshlrev_b64 v[32:33], 12, v[80:81]
	v_lshl_add_u64 v[32:33], s[16:17], 0, v[32:33]
	v_lshl_add_u64 v[40:41], v[96:97], 2, v[32:33]
	ds_read_b128 v[36:39], v114
	s_waitcnt vmcnt(7) lgkmcnt(0)
	v_pk_add_f32 v[34:35], v[38:39], v[130:131]
	v_pk_add_f32 v[32:33], v[36:37], v[128:129]
	global_store_dwordx4 v[40:41], v[32:35], off

.LBB0_2271:
	s_or_b64 exec, exec, s[24:25]
	s_nop 0
	v_lshl_add_u64 v[46:47], v[66:67], 0, v[98:99]
	v_lshl_add_u64 v[48:49], v[68:69], 0, v[98:99]
	v_lshl_add_u64 v[50:51], v[70:71], 0, v[98:99]
	v_lshl_add_u64 v[52:53], v[72:73], 0, v[98:99]
	global_load_dword v54, v[46:47], off
	global_load_dword v55, v[46:47], off offset:128
	global_load_dword v56, v[48:49], off
	global_load_dword v57, v[48:49], off offset:128
	global_load_dword v58, v[50:51], off
	global_load_dword v59, v[50:51], off offset:128
	global_load_dword v60, v[52:53], off
	global_load_dword v61, v[52:53], off offset:128
	v_lshl_add_u64 v[46:47], v[74:75], 0, v[98:99]
	v_lshl_add_u64 v[48:49], v[76:77], 0, v[98:99]
	v_lshl_add_u64 v[50:51], v[78:79], 0, v[98:99]
	v_lshl_add_u64 v[52:53], v[82:83], 0, v[98:99]
	global_load_dword v62, v[46:47], off
	global_load_dword v63, v[46:47], off offset:128
	global_load_dword v66, v[48:49], off
	global_load_dword v67, v[48:49], off offset:128
	global_load_dword v68, v[50:51], off
	global_load_dword v69, v[50:51], off offset:128
	global_load_dword v70, v[52:53], off
	global_load_dword v71, v[52:53], off offset:128
	v_lshl_add_u64 v[46:47], v[84:85], 0, v[98:99]
	v_lshl_add_u64 v[48:49], v[86:87], 0, v[98:99]
	v_lshl_add_u64 v[50:51], v[88:89], 0, v[98:99]
	v_lshl_add_u64 v[52:53], v[90:91], 0, v[98:99]
	global_load_dword v72, v[46:47], off
	global_load_dword v73, v[46:47], off offset:128
	global_load_dword v74, v[48:49], off
	s_nop 0
	global_load_dword v48, v[48:49], off offset:128
	s_nop 0
	global_load_dword v49, v[50:51], off
	s_nop 0
	global_load_dword v50, v[50:51], off offset:128
	s_nop 0
	global_load_dword v51, v[52:53], off
	s_nop 0
	global_load_dword v52, v[52:53], off offset:128
	v_lshl_add_u64 v[46:47], v[92:93], 0, v[98:99]
	global_load_dword v53, v[46:47], off
	s_nop 0
	global_load_dword v46, v[46:47], off offset:128
	s_waitcnt vmcnt(25)
	v_mul_f32_e32 v16, v16, v54
	s_waitcnt vmcnt(24)
	v_mul_f32_e32 v0, v0, v55
	v_mul_f32_e32 v1, v1, v55
	v_mul_f32_e32 v17, v17, v54
	v_mul_f32_e32 v18, v18, v54
	v_mul_f32_e32 v2, v2, v55
	v_mul_f32_e32 v19, v19, v54
	v_mul_f32_e32 v3, v3, v55
	s_waitcnt vmcnt(23)
	v_mul_f32_e32 v20, v20, v56
	s_waitcnt vmcnt(22)
	v_mul_f32_e32 v4, v4, v57
	s_waitcnt vmcnt(21)
	v_mul_f32_e32 v21, v21, v58
	s_waitcnt vmcnt(20)
	v_mul_f32_e32 v5, v5, v59
	s_waitcnt vmcnt(19)
	v_mul_f32_e32 v22, v22, v60
	s_waitcnt vmcnt(18)
	v_mul_f32_e32 v6, v6, v61
	s_waitcnt vmcnt(17)
	v_mul_f32_e32 v23, v23, v62
	s_waitcnt vmcnt(16)
	v_mul_f32_e32 v7, v7, v63
	s_waitcnt vmcnt(15)
	v_mul_f32_e32 v24, v24, v66
	s_waitcnt vmcnt(14)
	v_mul_f32_e32 v8, v8, v67
	s_waitcnt vmcnt(13)
	v_mul_f32_e32 v25, v25, v68
	s_waitcnt vmcnt(12)
	v_mul_f32_e32 v9, v9, v69
	s_waitcnt vmcnt(11)
	v_mul_f32_e32 v26, v26, v70
	s_waitcnt vmcnt(10)
	v_mul_f32_e32 v10, v10, v71
	s_waitcnt vmcnt(9)
	v_mul_f32_e32 v27, v27, v72
	s_waitcnt vmcnt(8)
	v_mul_f32_e32 v11, v11, v73
	s_waitcnt vmcnt(7)
	v_mul_f32_e32 v28, v28, v74
	s_waitcnt vmcnt(6)
	v_mul_f32_e32 v12, v12, v48
	s_waitcnt vmcnt(5)
	v_mul_f32_e32 v29, v29, v49
	s_waitcnt vmcnt(4)
	v_mul_f32_e32 v13, v13, v50
	s_waitcnt vmcnt(3)
	v_mul_f32_e32 v30, v30, v51
	s_waitcnt vmcnt(2)
	v_mul_f32_e32 v14, v14, v52
	ds_write2_b32 v162, v16, v0 offset1:32
	ds_write2_b32 v162, v17, v1 offset0:68 offset1:100
	ds_write2_b32 v162, v18, v2 offset0:136 offset1:168
	ds_write2_b32 v162, v19, v3 offset0:204 offset1:236
	ds_write2_b32 v115, v20, v4 offset0:32 offset1:64
	ds_write2_b32 v115, v21, v5 offset0:100 offset1:132
	ds_write2_b32 v115, v22, v6 offset0:168 offset1:200
	ds_write2_b32 v116, v23, v7 offset0:108 offset1:140
	ds_write2_b32 v117, v24, v8 offset0:64 offset1:96
	ds_write2_b32 v117, v25, v9 offset0:132 offset1:164
	ds_write2_b32 v117, v26, v10 offset0:200 offset1:232
	ds_write2_b32 v118, v27, v11 offset0:12 offset1:44
	ds_write2_b32 v119, v28, v12 offset0:96 offset1:128
	ds_write2_b32 v119, v29, v13 offset0:164 offset1:196
	ds_write2_b32 v120, v30, v14 offset0:104 offset1:136
	s_waitcnt vmcnt(1)
	v_mul_f32_e32 v0, v31, v53
	s_waitcnt vmcnt(0)
	v_mul_f32_e32 v1, v15, v46
	ds_write2_b32 v121, v0, v1 offset0:44 offset1:76
	v_add_u32_e32 v128, 0, v80
	v_ashrrev_i32_e32 v129, 31, v128
	v_lshlrev_b64 v[128:129], 12, v[128:129]
	v_lshl_add_u64 v[128:129], s[16:17], 0, v[128:129]
	v_lshl_add_u64 v[128:129], v[64:65], 2, v[128:129]
	global_load_dwordx4 v[128:131], v[128:129], off offset:256 nt
	v_add_u32_e32 v132, 4, v80
	v_ashrrev_i32_e32 v133, 31, v132
	v_lshlrev_b64 v[132:133], 12, v[132:133]
	v_lshl_add_u64 v[132:133], s[16:17], 0, v[132:133]
	v_lshl_add_u64 v[132:133], v[64:65], 2, v[132:133]
	global_load_dwordx4 v[132:135], v[132:133], off offset:256 nt
	v_add_u32_e32 v136, 8, v80
	v_ashrrev_i32_e32 v137, 31, v136
	v_lshlrev_b64 v[136:137], 12, v[136:137]
	v_lshl_add_u64 v[136:137], s[16:17], 0, v[136:137]
	v_lshl_add_u64 v[136:137], v[64:65], 2, v[136:137]
	global_load_dwordx4 v[136:139], v[136:137], off offset:256 nt
	v_add_u32_e32 v140, 12, v80
	v_ashrrev_i32_e32 v141, 31, v140
	v_lshlrev_b64 v[140:141], 12, v[140:141]
	v_lshl_add_u64 v[140:141], s[16:17], 0, v[140:141]
	v_lshl_add_u64 v[140:141], v[64:65], 2, v[140:141]
	global_load_dwordx4 v[140:143], v[140:141], off offset:256 nt
	v_add_u32_e32 v144, 16, v80
	v_ashrrev_i32_e32 v145, 31, v144
	v_lshlrev_b64 v[144:145], 12, v[144:145]
	v_lshl_add_u64 v[144:145], s[16:17], 0, v[144:145]
	v_lshl_add_u64 v[144:145], v[64:65], 2, v[144:145]
	global_load_dwordx4 v[144:147], v[144:145], off offset:256 nt
	v_add_u32_e32 v148, 20, v80
	v_ashrrev_i32_e32 v149, 31, v148
	v_lshlrev_b64 v[148:149], 12, v[148:149]
	v_lshl_add_u64 v[148:149], s[16:17], 0, v[148:149]
	v_lshl_add_u64 v[148:149], v[64:65], 2, v[148:149]
	global_load_dwordx4 v[148:151], v[148:149], off offset:256 nt
	v_add_u32_e32 v152, 24, v80
	v_ashrrev_i32_e32 v153, 31, v152
	v_lshlrev_b64 v[152:153], 12, v[152:153]
	v_lshl_add_u64 v[152:153], s[16:17], 0, v[152:153]
	v_lshl_add_u64 v[152:153], v[64:65], 2, v[152:153]
	global_load_dwordx4 v[152:155], v[152:153], off offset:256 nt
	v_add_u32_e32 v156, 28, v80
	v_ashrrev_i32_e32 v157, 31, v156
	v_lshlrev_b64 v[156:157], 12, v[156:157]
	v_lshl_add_u64 v[156:157], s[16:17], 0, v[156:157]
	v_lshl_add_u64 v[156:157], v[64:65], 2, v[156:157]
	global_load_dwordx4 v[156:159], v[156:157], off offset:256 nt
	s_and_saveexec_b64 s[24:25], vcc
	s_cbranch_execz .LBB0_2279
	v_lshlrev_b64 v[0:1], 12, v[80:81]
	v_lshl_add_u64 v[0:1], s[16:17], 0, v[0:1]
	v_lshl_add_u64 v[8:9], v[64:65], 2, v[0:1]
	ds_read_b128 v[4:7], v114
	s_waitcnt vmcnt(7) lgkmcnt(0)
	v_pk_add_f32 v[2:3], v[6:7], v[130:131]
	v_pk_add_f32 v[0:1], v[4:5], v[128:129]
	global_store_dwordx4 v[8:9], v[0:3], off offset:256
	s_or_b64 exec, exec, s[24:25]
	s_and_saveexec_b64 s[24:25], s[2:3]
	s_cbranch_execnz .LBB0_2280

.LBB0_4482:
	ds_read_b128 v[128:131], v238
	ds_read_b128 v[136:139], v253
	ds_read_b128 v[132:135], v238 offset:4096
	ds_read_b128 v[140:143], v253 offset:4096
	ds_read_b128 v[144:147], v253 offset:8192
	ds_read_b128 v[148:151], v253 offset:12288
	s_waitcnt lgkmcnt(6)
	v_mfma_f32_32x32x16_bf16 v[112:127], v[188:191], v[196:199], v[112:127]
	v_mfma_f32_32x32x16_bf16 v[48:63], v[192:195], v[196:199], v[48:63]
	v_mfma_f32_32x32x16_bf16 v[96:111], v[188:191], v[200:203], v[96:111]
	v_mfma_f32_32x32x16_bf16 v[32:47], v[192:195], v[200:203], v[32:47]
	v_mfma_f32_32x32x16_bf16 v[80:95], v[188:191], v[204:207], v[80:95]
	v_mfma_f32_32x32x16_bf16 v[16:31], v[192:195], v[204:207], v[16:31]
	v_mfma_f32_32x32x16_bf16 v[64:79], v[188:191], v[226:229], v[64:79]
	v_mfma_f32_32x32x16_bf16 v[0:15], v[192:195], v[226:229], v[0:15]
	ds_read_b128 v[188:191], v239
	ds_read_b128 v[196:199], v254
	ds_read_b128 v[192:195], v239 offset:4096
	ds_read_b128 v[200:203], v254 offset:4096
	ds_read_b128 v[204:207], v254 offset:8192
	ds_read_b128 v[226:229], v254 offset:12288
	s_waitcnt lgkmcnt(6)
	v_mfma_f32_32x32x16_bf16 v[112:127], v[128:131], v[136:139], v[112:127]
	v_mfma_f32_32x32x16_bf16 v[48:63], v[132:135], v[136:139], v[48:63]
	v_mfma_f32_32x32x16_bf16 v[96:111], v[128:131], v[140:143], v[96:111]
	v_mfma_f32_32x32x16_bf16 v[32:47], v[132:135], v[140:143], v[32:47]
	v_mfma_f32_32x32x16_bf16 v[80:95], v[128:131], v[144:147], v[80:95]
	v_mfma_f32_32x32x16_bf16 v[16:31], v[132:135], v[144:147], v[16:31]
	v_mfma_f32_32x32x16_bf16 v[64:79], v[128:131], v[148:151], v[64:79]
	v_mfma_f32_32x32x16_bf16 v[0:15], v[132:135], v[148:151], v[0:15]
	ds_read_b128 v[128:131], v240
	ds_read_b128 v[136:139], v255
	ds_read_b128 v[132:135], v240 offset:4096
	ds_read_b128 v[140:143], v255 offset:4096
	ds_read_b128 v[144:147], v255 offset:8192
	ds_read_b128 v[148:151], v255 offset:12288
	s_waitcnt lgkmcnt(6)
	v_mfma_f32_32x32x16_bf16 v[112:127], v[188:191], v[196:199], v[112:127]
	v_mfma_f32_32x32x16_bf16 v[48:63], v[192:195], v[196:199], v[48:63]
	v_mfma_f32_32x32x16_bf16 v[96:111], v[188:191], v[200:203], v[96:111]
	v_mfma_f32_32x32x16_bf16 v[32:47], v[192:195], v[200:203], v[32:47]
	v_mfma_f32_32x32x16_bf16 v[80:95], v[188:191], v[204:207], v[80:95]
	v_mfma_f32_32x32x16_bf16 v[16:31], v[192:195], v[204:207], v[16:31]
	v_mfma_f32_32x32x16_bf16 v[64:79], v[188:191], v[226:229], v[64:79]
	v_mfma_f32_32x32x16_bf16 v[0:15], v[192:195], v[226:229], v[0:15]
	s_waitcnt vmcnt(0) lgkmcnt(0)
	s_barrier
	v_mfma_f32_32x32x16_bf16 v[112:127], v[128:131], v[136:139], v[112:127]
	v_mfma_f32_32x32x16_bf16 v[48:63], v[132:135], v[136:139], v[48:63]
	v_mfma_f32_32x32x16_bf16 v[96:111], v[128:131], v[140:143], v[96:111]
	v_mfma_f32_32x32x16_bf16 v[32:47], v[132:135], v[140:143], v[32:47]
	v_mfma_f32_32x32x16_bf16 v[80:95], v[128:131], v[144:147], v[80:95]
	v_mfma_f32_32x32x16_bf16 v[16:31], v[132:135], v[144:147], v[16:31]
	v_mfma_f32_32x32x16_bf16 v[64:79], v[128:131], v[148:151], v[64:79]
	v_mfma_f32_32x32x16_bf16 v[0:15], v[132:135], v[148:151], v[0:15]
	s_lshl_b32 s2, s5, 8
	s_sub_i32 s2, s2, s6
	v_mov_b32_e32 v168, v214
	s_add_i32 s55, s4, s30
	s_or_b32 s26, s2, s31
	s_ashr_i32 s27, s26, 31
	s_load_dwordx2 s[24:25], s[0:1], 0x140
	v_ashrrev_i32_e32 v180, 3, v168
	v_and_b32_e32 v183, -4, v180
	v_add_u32_e32 v225, s55, v183
	v_add_u32_e32 v190, 8, v225
	v_min_i32_e32 v190, 0x7fff, v190
	v_ashrrev_i32_e32 v190, 12, v190
	v_add_u32_e32 v190, 16, v190
	v_mul_hi_i32_i24_e32 v191, 0x3000, v190
	v_mul_i32_i24_e32 v190, 0x3000, v190
	v_min_i32_e32 v184, 0x7fff, v225
	v_ashrrev_i32_e32 v184, 12, v184
	v_and_b32_e32 v182, 31, v168
	v_add_u32_e32 v184, 16, v184
	v_or_b32_e32 v180, s26, v182
	v_mul_hi_i32_i24_e32 v185, 0x3000, v184
	v_mul_i32_i24_e32 v184, 0x3000, v184
	v_ashrrev_i32_e32 v181, 31, v180
	s_waitcnt lgkmcnt(0)
	v_lshl_add_u64 v[184:185], s[24:25], 0, v[184:185]
	v_lshl_add_u64 v[184:185], v[184:185], 0, s[18:19]
	v_lshlrev_b64 v[180:181], 2, v[180:181]
	v_lshl_add_u64 v[196:197], v[184:185], 0, v[180:181]
	v_lshl_add_u64 v[186:187], s[24:25], 0, v[190:191]
	v_add_u32_e32 v188, 9, v225
	v_add_u32_e32 v190, 10, v225
	v_min_i32_e32 v188, 0x7fff, v188
	v_min_i32_e32 v190, 0x7fff, v190
	v_ashrrev_i32_e32 v188, 12, v188
	v_ashrrev_i32_e32 v190, 12, v190
	v_add_u32_e32 v188, 16, v188
	v_add_u32_e32 v190, 16, v190
	v_mul_hi_i32_i24_e32 v189, 0x3000, v188
	v_mul_i32_i24_e32 v188, 0x3000, v188
	v_mul_hi_i32_i24_e32 v191, 0x3000, v190
	v_mul_i32_i24_e32 v190, 0x3000, v190
	v_lshl_add_u64 v[188:189], s[24:25], 0, v[188:189]
	v_lshl_add_u64 v[190:191], s[24:25], 0, v[190:191]
	v_lshl_add_u64 v[186:187], v[186:187], 0, s[18:19]
	v_lshl_add_u64 v[188:189], v[188:189], 0, s[18:19]
	v_lshl_add_u64 v[190:191], v[190:191], 0, s[18:19]
	v_lshl_add_u64 v[206:207], v[186:187], 0, v[180:181]
	v_add_u32_e32 v208, 18, v225
	v_min_i32_e32 v208, 0x7fff, v208
	v_ashrrev_i32_e32 v208, 12, v208
	v_add_u32_e32 v208, 16, v208
	v_mul_hi_i32_i24_e32 v209, 0x3000, v208
	v_mul_i32_i24_e32 v208, 0x3000, v208
	v_lshl_add_u64 v[208:209], s[24:25], 0, v[208:209]
	v_lshl_add_u64 v[202:203], v[188:189], 0, v[180:181]
	v_lshl_add_u64 v[204:205], v[190:191], 0, v[180:181]
	global_load_dword v232, v[196:197], off
	global_load_dword v233, v[196:197], off offset:128
	global_load_dword v242, v[206:207], off
	global_load_dword v243, v[206:207], off offset:128
	global_load_dword v244, v[202:203], off
	global_load_dword v245, v[202:203], off offset:128
	global_load_dword v246, v[204:205], off
	global_load_dword v247, v[204:205], off offset:128
	v_add_u32_e32 v196, 17, v225
	v_min_i32_e32 v196, 0x7fff, v196
	v_ashrrev_i32_e32 v196, 12, v196
	v_add_u32_e32 v196, 16, v196
	v_mul_hi_i32_i24_e32 v197, 0x3000, v196
	v_mul_i32_i24_e32 v196, 0x3000, v196
	v_lshl_add_u64 v[196:197], s[24:25], 0, v[196:197]
	v_lshl_add_u64 v[196:197], v[196:197], 0, s[18:19]
	v_lshl_add_u64 v[206:207], v[196:197], 0, v[180:181]
	s_waitcnt vmcnt(7)
	s_nop 5
	v_mul_f32_e32 v112, v112, v232
	v_add_u32_e32 v192, 11, v225
	v_add_u32_e32 v194, 16, v225
	v_min_i32_e32 v192, 0x7fff, v192
	v_min_i32_e32 v194, 0x7fff, v194
	v_ashrrev_i32_e32 v192, 12, v192
	v_ashrrev_i32_e32 v194, 12, v194
	v_add_u32_e32 v192, 16, v192
	v_add_u32_e32 v194, 16, v194
	v_mul_hi_i32_i24_e32 v193, 0x3000, v192
	v_mul_i32_i24_e32 v192, 0x3000, v192
	v_mul_hi_i32_i24_e32 v195, 0x3000, v194
	v_mul_i32_i24_e32 v194, 0x3000, v194
	v_lshl_add_u64 v[192:193], s[24:25], 0, v[192:193]
	v_lshl_add_u64 v[194:195], s[24:25], 0, v[194:195]
	v_lshl_add_u64 v[192:193], v[192:193], 0, s[18:19]
	v_lshl_add_u64 v[194:195], v[194:195], 0, s[18:19]
	v_lshl_add_u64 v[202:203], v[192:193], 0, v[180:181]
	v_lshl_add_u64 v[204:205], v[194:195], 0, v[180:181]
	s_waitcnt vmcnt(6)
	s_nop 5
	v_mul_f32_e32 v96, v96, v233
	v_mul_f32_e32 v97, v97, v233
	v_lshl_add_u64 v[198:199], v[208:209], 0, s[18:19]
	v_lshl_add_u64 v[200:201], v[198:199], 0, v[180:181]
	global_load_dword v234, v[202:203], off
	global_load_dword v235, v[202:203], off offset:128
	global_load_dword v236, v[204:205], off
	global_load_dword v237, v[204:205], off offset:128
	global_load_dword v238, v[206:207], off
	global_load_dword v239, v[206:207], off offset:128
	global_load_dword v240, v[200:201], off
	global_load_dword v241, v[200:201], off offset:128
	v_add_u32_e32 v200, 19, v225
	v_add_u32_e32 v204, 25, v225
	v_add_u32_e32 v206, 26, v225
	v_min_i32_e32 v200, 0x7fff, v200
	v_add_u32_e32 v202, 24, v225
	v_min_i32_e32 v204, 0x7fff, v204
	v_min_i32_e32 v206, 0x7fff, v206
	v_ashrrev_i32_e32 v200, 12, v200
	v_min_i32_e32 v202, 0x7fff, v202
	v_ashrrev_i32_e32 v204, 12, v204
	v_ashrrev_i32_e32 v206, 12, v206
	v_add_u32_e32 v200, 16, v200
	v_ashrrev_i32_e32 v202, 12, v202
	v_add_u32_e32 v204, 16, v204
	v_add_u32_e32 v206, 16, v206
	v_mul_hi_i32_i24_e32 v201, 0x3000, v200
	v_mul_i32_i24_e32 v200, 0x3000, v200
	v_add_u32_e32 v202, 16, v202
	v_mul_hi_i32_i24_e32 v205, 0x3000, v204
	v_mul_i32_i24_e32 v204, 0x3000, v204
	v_mul_hi_i32_i24_e32 v207, 0x3000, v206
	v_mul_i32_i24_e32 v206, 0x3000, v206
	v_lshl_add_u64 v[200:201], s[24:25], 0, v[200:201]
	v_mul_hi_i32_i24_e32 v203, 0x3000, v202
	v_mul_i32_i24_e32 v202, 0x3000, v202
	v_lshl_add_u64 v[204:205], s[24:25], 0, v[204:205]
	v_lshl_add_u64 v[206:207], s[24:25], 0, v[206:207]
	v_lshl_add_u64 v[200:201], v[200:201], 0, s[18:19]
	v_lshl_add_u64 v[202:203], s[24:25], 0, v[202:203]
	v_lshl_add_u64 v[204:205], v[204:205], 0, s[18:19]
	v_lshl_add_u64 v[206:207], v[206:207], 0, s[18:19]
	v_lshl_add_u64 v[208:209], v[200:201], 0, v[180:181]
	v_lshl_add_u64 v[202:203], v[202:203], 0, s[18:19]
	v_lshl_add_u64 v[228:229], v[204:205], 0, v[180:181]
	v_lshl_add_u64 v[230:231], v[206:207], 0, v[180:181]
	v_lshl_add_u64 v[226:227], v[202:203], 0, v[180:181]
	global_load_dword v248, v[208:209], off
	global_load_dword v249, v[208:209], off offset:128
	global_load_dword v250, v[226:227], off
	global_load_dword v251, v[226:227], off offset:128
	global_load_dword v252, v[228:229], off
	s_nop 0
	global_load_dword v228, v[228:229], off offset:128
	s_nop 0
	global_load_dword v229, v[230:231], off
	s_nop 0
	global_load_dword v230, v[230:231], off offset:128
	v_add_u32_e32 v208, 27, v225
	v_min_i32_e32 v208, 0x7fff, v208
	v_ashrrev_i32_e32 v208, 12, v208
	v_add_u32_e32 v208, 16, v208
	v_mul_hi_i32_i24_e32 v209, 0x3000, v208
	v_mul_i32_i24_e32 v208, 0x3000, v208
	v_lshl_add_u64 v[208:209], s[24:25], 0, v[208:209]
	v_lshl_add_u64 v[208:209], v[208:209], 0, s[18:19]
	v_lshl_add_u64 v[226:227], v[208:209], 0, v[180:181]
	global_load_dword v225, v[226:227], off
	s_nop 0
	global_load_dword v226, v[226:227], off offset:128
	v_mad_u64_u32 v[160:161], s[2:3], v183, s36, v[182:183]
	v_lshl_add_u32 v162, v160, 2, s34
	ds_write2_b32 v162, v112, v96 offset1:32
	v_mul_f32_e32 v96, v113, v232
	ds_write2_b32 v162, v96, v97 offset0:68 offset1:100
	v_mul_f32_e32 v96, v114, v232
	v_mul_f32_e32 v97, v98, v233
	ds_write2_b32 v162, v96, v97 offset0:136 offset1:168
	v_mul_f32_e32 v96, v115, v232
	v_mul_f32_e32 v97, v99, v233
	ds_write2_b32 v162, v96, v97 offset0:204 offset1:236
	s_waitcnt vmcnt(23)
	v_mul_f32_e32 v96, v116, v242
	s_waitcnt vmcnt(22)
	v_mul_f32_e32 v97, v100, v243
	v_add_u32_e32 v115, 0x800, v162
	ds_write2_b32 v115, v96, v97 offset0:32 offset1:64
	s_waitcnt vmcnt(21)
	v_mul_f32_e32 v96, v117, v244
	s_waitcnt vmcnt(20)
	v_mul_f32_e32 v97, v101, v245
	ds_write2_b32 v115, v96, v97 offset0:100 offset1:132
	s_waitcnt vmcnt(19)
	v_mul_f32_e32 v96, v118, v246
	s_waitcnt vmcnt(18)
	v_mul_f32_e32 v97, v102, v247
	ds_write2_b32 v115, v96, v97 offset0:168 offset1:200
	v_add_u32_e32 v116, 0xa00, v162
	v_add_u32_e32 v117, 0x1000, v162
	s_waitcnt vmcnt(17)
	v_mul_f32_e32 v96, v119, v234
	s_waitcnt vmcnt(16)
	v_mul_f32_e32 v97, v103, v235
	ds_write2_b32 v116, v96, v97 offset0:108 offset1:140
	s_waitcnt vmcnt(15)
	v_mul_f32_e32 v96, v120, v236
	s_waitcnt vmcnt(14)
	v_mul_f32_e32 v97, v104, v237
	ds_write2_b32 v117, v96, v97 offset0:64 offset1:96
	s_waitcnt vmcnt(13)
	v_mul_f32_e32 v96, v121, v238
	s_waitcnt vmcnt(12)
	v_mul_f32_e32 v97, v105, v239
	ds_write2_b32 v117, v96, v97 offset0:132 offset1:164
	s_waitcnt vmcnt(11)
	v_mul_f32_e32 v96, v122, v240
	s_waitcnt vmcnt(10)
	v_mul_f32_e32 v97, v106, v241
	ds_write2_b32 v117, v96, v97 offset0:200 offset1:232
	v_add_u32_e32 v118, 0x1400, v162
	v_add_u32_e32 v119, 0x1800, v162
	v_ashrrev_i32_e32 v163, 4, v168
	v_and_b32_e32 v160, 15, v168
	v_add_u32_e32 v120, 0x1a00, v162
	v_mul_lo_u32 v164, v163, s37
	v_lshl_add_u32 v165, v160, 4, s34
	v_lshlrev_b32_e32 v168, 2, v160
	v_add_u32_e32 v160, s55, v163
	v_add_u32_e32 v121, 0x1c00, v162
	v_cmp_gt_i32_e32 vcc, s38, v160
	v_ashrrev_i32_e32 v161, 31, v160
	v_add_u32_e32 v114, v165, v164
	s_waitcnt vmcnt(9)
	v_mul_f32_e32 v96, v123, v248
	s_waitcnt vmcnt(8)
	v_mul_f32_e32 v97, v107, v249
	ds_write2_b32 v118, v96, v97 offset0:12 offset1:44
	s_waitcnt vmcnt(7)
	v_mul_f32_e32 v96, v124, v250
	s_waitcnt vmcnt(6)
	v_mul_f32_e32 v97, v108, v251
	ds_write2_b32 v119, v96, v97 offset0:96 offset1:128
	s_waitcnt vmcnt(5)
	v_mul_f32_e32 v96, v125, v252
	s_waitcnt vmcnt(4)
	v_mul_f32_e32 v97, v109, v228
	ds_write2_b32 v119, v96, v97 offset0:164 offset1:196
	s_waitcnt vmcnt(3)
	v_mul_f32_e32 v96, v126, v229
	s_waitcnt vmcnt(2)
	v_mul_f32_e32 v97, v110, v230
	ds_write2_b32 v120, v96, v97 offset0:104 offset1:136
	s_waitcnt vmcnt(1)
	v_mul_f32_e32 v96, v127, v225
	s_waitcnt vmcnt(0)
	v_mul_f32_e32 v97, v111, v226
	ds_write2_b32 v121, v96, v97 offset0:44 offset1:76
	v_or_b32_e32 v96, s26, v168
	v_mov_b32_e32 v97, s27
	v_add_u32_e32 v128, 0, v160
	v_ashrrev_i32_e32 v129, 31, v128
	v_lshlrev_b64 v[128:129], 12, v[128:129]
	v_lshl_add_u64 v[128:129], s[16:17], 0, v[128:129]
	v_lshl_add_u64 v[128:129], v[96:97], 2, v[128:129]
	global_load_dwordx4 v[128:131], v[128:129], off nt
	v_add_u32_e32 v132, 4, v160
	v_ashrrev_i32_e32 v133, 31, v132
	v_lshlrev_b64 v[132:133], 12, v[132:133]
	v_lshl_add_u64 v[132:133], s[16:17], 0, v[132:133]
	v_lshl_add_u64 v[132:133], v[96:97], 2, v[132:133]
	global_load_dwordx4 v[132:135], v[132:133], off nt
	v_add_u32_e32 v136, 8, v160
	v_ashrrev_i32_e32 v137, 31, v136
	v_lshlrev_b64 v[136:137], 12, v[136:137]
	v_lshl_add_u64 v[136:137], s[16:17], 0, v[136:137]
	v_lshl_add_u64 v[136:137], v[96:97], 2, v[136:137]
	global_load_dwordx4 v[136:139], v[136:137], off nt
	v_add_u32_e32 v140, 12, v160
	v_ashrrev_i32_e32 v141, 31, v140
	v_lshlrev_b64 v[140:141], 12, v[140:141]
	v_lshl_add_u64 v[140:141], s[16:17], 0, v[140:141]
	v_lshl_add_u64 v[140:141], v[96:97], 2, v[140:141]
	global_load_dwordx4 v[140:143], v[140:141], off nt
	v_add_u32_e32 v144, 16, v160
	v_ashrrev_i32_e32 v145, 31, v144
	v_lshlrev_b64 v[144:145], 12, v[144:145]
	v_lshl_add_u64 v[144:145], s[16:17], 0, v[144:145]
	v_lshl_add_u64 v[144:145], v[96:97], 2, v[144:145]
	global_load_dwordx4 v[144:147], v[144:145], off nt
	v_add_u32_e32 v148, 20, v160
	v_ashrrev_i32_e32 v149, 31, v148
	v_lshlrev_b64 v[148:149], 12, v[148:149]
	v_lshl_add_u64 v[148:149], s[16:17], 0, v[148:149]
	v_lshl_add_u64 v[148:149], v[96:97], 2, v[148:149]
	global_load_dwordx4 v[148:151], v[148:149], off nt
	v_add_u32_e32 v152, 24, v160
	v_ashrrev_i32_e32 v153, 31, v152
	v_lshlrev_b64 v[152:153], 12, v[152:153]
	v_lshl_add_u64 v[152:153], s[16:17], 0, v[152:153]
	v_lshl_add_u64 v[152:153], v[96:97], 2, v[152:153]
	global_load_dwordx4 v[152:155], v[152:153], off nt
	v_add_u32_e32 v156, 28, v160
	v_ashrrev_i32_e32 v157, 31, v156
	v_lshlrev_b64 v[156:157], 12, v[156:157]
	v_lshl_add_u64 v[156:157], s[16:17], 0, v[156:157]
	v_lshl_add_u64 v[156:157], v[96:97], 2, v[156:157]
	global_load_dwordx4 v[156:159], v[156:157], off nt
	s_and_saveexec_b64 s[2:3], vcc
	s_cbranch_execz .LBB0_4484
	v_lshlrev_b64 v[98:99], 12, v[160:161]
	v_lshl_add_u64 v[98:99], s[16:17], 0, v[98:99]
	v_lshl_add_u64 v[106:107], v[96:97], 2, v[98:99]
	ds_read_b128 v[102:105], v114
	s_waitcnt vmcnt(7) lgkmcnt(0)
	v_pk_add_f32 v[100:101], v[104:105], v[130:131]
	v_pk_add_f32 v[98:99], v[102:103], v[128:129]
	global_store_dwordx4 v[106:107], v[98:101], off

.LBB0_4514:
	s_or_b64 exec, exec, s[2:3]
	s_or_b32 s2, s55, 32
	v_add_u32_e32 v102, s2, v183
	v_min_i32_e32 v66, 0x7fff, v102
	v_add_u32_e32 v68, 8, v102
	v_add_u32_e32 v70, 9, v102
	v_add_u32_e32 v72, 10, v102
	v_ashrrev_i32_e32 v66, 12, v66
	v_min_i32_e32 v68, 0x7fff, v68
	v_min_i32_e32 v70, 0x7fff, v70
	v_min_i32_e32 v72, 0x7fff, v72
	v_add_u32_e32 v66, 16, v66
	v_ashrrev_i32_e32 v68, 12, v68
	v_ashrrev_i32_e32 v70, 12, v70
	v_ashrrev_i32_e32 v72, 12, v72
	v_mul_hi_i32_i24_e32 v67, 0x3000, v66
	v_mul_i32_i24_e32 v66, 0x3000, v66
	v_add_u32_e32 v68, 16, v68
	v_add_u32_e32 v70, 16, v70
	v_add_u32_e32 v72, 16, v72
	v_lshl_add_u64 v[66:67], s[24:25], 0, v[66:67]
	v_mul_hi_i32_i24_e32 v69, 0x3000, v68
	v_mul_i32_i24_e32 v68, 0x3000, v68
	v_mul_hi_i32_i24_e32 v71, 0x3000, v70
	v_mul_i32_i24_e32 v70, 0x3000, v70
	v_mul_hi_i32_i24_e32 v73, 0x3000, v72
	v_mul_i32_i24_e32 v72, 0x3000, v72
	v_lshl_add_u64 v[66:67], v[66:67], 0, s[18:19]
	v_lshl_add_u64 v[68:69], s[24:25], 0, v[68:69]
	v_lshl_add_u64 v[70:71], s[24:25], 0, v[70:71]
	v_lshl_add_u64 v[72:73], s[24:25], 0, v[72:73]
	v_lshl_add_u64 v[74:75], v[66:67], 0, v[180:181]
	v_lshl_add_u64 v[68:69], v[68:69], 0, s[18:19]
	v_lshl_add_u64 v[70:71], v[70:71], 0, s[18:19]
	v_lshl_add_u64 v[72:73], v[72:73], 0, s[18:19]
	v_lshl_add_u64 v[76:77], v[68:69], 0, v[180:181]
	v_lshl_add_u64 v[78:79], v[70:71], 0, v[180:181]
	v_lshl_add_u64 v[80:81], v[72:73], 0, v[180:181]
	global_load_dword v103, v[74:75], off
	global_load_dword v104, v[74:75], off offset:128
	global_load_dword v105, v[76:77], off
	global_load_dword v106, v[76:77], off offset:128
	global_load_dword v107, v[78:79], off
	global_load_dword v108, v[78:79], off offset:128
	global_load_dword v109, v[80:81], off
	global_load_dword v110, v[80:81], off offset:128
	v_add_u32_e32 v74, 11, v102
	v_add_u32_e32 v82, 18, v102
	v_min_i32_e32 v74, 0x7fff, v74
	v_add_u32_e32 v76, 16, v102
	v_add_u32_e32 v78, 17, v102
	v_min_i32_e32 v82, 0x7fff, v82
	v_ashrrev_i32_e32 v74, 12, v74
	v_min_i32_e32 v76, 0x7fff, v76
	v_min_i32_e32 v78, 0x7fff, v78
	v_ashrrev_i32_e32 v82, 12, v82
	v_add_u32_e32 v74, 16, v74
	v_ashrrev_i32_e32 v76, 12, v76
	v_ashrrev_i32_e32 v78, 12, v78
	v_add_u32_e32 v82, 16, v82
	v_mul_hi_i32_i24_e32 v75, 0x3000, v74
	v_mul_i32_i24_e32 v74, 0x3000, v74
	v_add_u32_e32 v76, 16, v76
	v_add_u32_e32 v78, 16, v78
	v_mul_hi_i32_i24_e32 v83, 0x3000, v82
	v_mul_i32_i24_e32 v82, 0x3000, v82
	v_lshl_add_u64 v[74:75], s[24:25], 0, v[74:75]
	v_mul_hi_i32_i24_e32 v77, 0x3000, v76
	v_mul_i32_i24_e32 v76, 0x3000, v76
	v_mul_hi_i32_i24_e32 v79, 0x3000, v78
	v_mul_i32_i24_e32 v78, 0x3000, v78
	v_lshl_add_u64 v[82:83], s[24:25], 0, v[82:83]
	v_lshl_add_u64 v[74:75], v[74:75], 0, s[18:19]
	v_lshl_add_u64 v[76:77], s[24:25], 0, v[76:77]
	v_lshl_add_u64 v[78:79], s[24:25], 0, v[78:79]
	v_lshl_add_u64 v[82:83], v[82:83], 0, s[18:19]
	v_lshl_add_u64 v[80:81], v[74:75], 0, v[180:181]
	v_lshl_add_u64 v[76:77], v[76:77], 0, s[18:19]
	v_lshl_add_u64 v[78:79], v[78:79], 0, s[18:19]
	v_lshl_add_u64 v[88:89], v[82:83], 0, v[180:181]
	v_lshl_add_u64 v[84:85], v[76:77], 0, v[180:181]
	v_lshl_add_u64 v[86:87], v[78:79], 0, v[180:181]
	global_load_dword v111, v[80:81], off
	global_load_dword v112, v[80:81], off offset:128
	global_load_dword v113, v[84:85], off
	global_load_dword v122, v[84:85], off offset:128
	global_load_dword v123, v[86:87], off
	global_load_dword v124, v[86:87], off offset:128
	global_load_dword v125, v[88:89], off
	global_load_dword v126, v[88:89], off offset:128
	v_add_u32_e32 v80, 19, v102
	v_add_u32_e32 v88, 25, v102
	v_add_u32_e32 v90, 26, v102
	v_min_i32_e32 v80, 0x7fff, v80
	v_add_u32_e32 v86, 24, v102
	v_min_i32_e32 v88, 0x7fff, v88
	v_min_i32_e32 v90, 0x7fff, v90
	v_ashrrev_i32_e32 v80, 12, v80
	v_min_i32_e32 v86, 0x7fff, v86
	v_ashrrev_i32_e32 v88, 12, v88
	v_ashrrev_i32_e32 v90, 12, v90
	v_add_u32_e32 v80, 16, v80
	v_ashrrev_i32_e32 v86, 12, v86
	v_add_u32_e32 v88, 16, v88
	v_add_u32_e32 v90, 16, v90
	v_mul_hi_i32_i24_e32 v81, 0x3000, v80
	v_mul_i32_i24_e32 v80, 0x3000, v80
	v_add_u32_e32 v86, 16, v86
	v_mul_hi_i32_i24_e32 v89, 0x3000, v88
	v_mul_i32_i24_e32 v88, 0x3000, v88
	v_mul_hi_i32_i24_e32 v91, 0x3000, v90
	v_mul_i32_i24_e32 v90, 0x3000, v90
	v_lshl_add_u64 v[80:81], s[24:25], 0, v[80:81]
	v_mul_hi_i32_i24_e32 v87, 0x3000, v86
	v_mul_i32_i24_e32 v86, 0x3000, v86
	v_lshl_add_u64 v[88:89], s[24:25], 0, v[88:89]
	v_lshl_add_u64 v[90:91], s[24:25], 0, v[90:91]
	v_lshl_add_u64 v[84:85], v[80:81], 0, s[18:19]
	v_lshl_add_u64 v[86:87], s[24:25], 0, v[86:87]
	v_lshl_add_u64 v[88:89], v[88:89], 0, s[18:19]
	v_lshl_add_u64 v[90:91], v[90:91], 0, s[18:19]
	v_lshl_add_u64 v[80:81], v[84:85], 0, v[180:181]
	v_lshl_add_u64 v[86:87], v[86:87], 0, s[18:19]
	v_lshl_add_u64 v[94:95], v[88:89], 0, v[180:181]
	v_lshl_add_u64 v[100:101], v[90:91], 0, v[180:181]
	v_lshl_add_u64 v[92:93], v[86:87], 0, v[180:181]
	global_load_dword v127, v[80:81], off
	global_load_dword v160, v[80:81], off offset:128
	global_load_dword v161, v[92:93], off
	global_load_dword v164, v[92:93], off offset:128
	global_load_dword v165, v[94:95], off
	s_nop 0
	global_load_dword v94, v[94:95], off offset:128
	s_nop 0
	global_load_dword v95, v[100:101], off
	s_nop 0
	global_load_dword v100, v[100:101], off offset:128
	v_add_u32_e32 v80, 27, v102
	v_min_i32_e32 v80, 0x7fff, v80
	v_ashrrev_i32_e32 v80, 12, v80
	v_add_u32_e32 v80, 16, v80
	v_mul_hi_i32_i24_e32 v81, 0x3000, v80
	v_mul_i32_i24_e32 v80, 0x3000, v80
	v_lshl_add_u64 v[80:81], s[24:25], 0, v[80:81]
	v_lshl_add_u64 v[92:93], v[80:81], 0, s[18:19]
	v_lshl_add_u64 v[80:81], v[92:93], 0, v[180:181]
	global_load_dword v101, v[80:81], off
	s_nop 0
	global_load_dword v81, v[80:81], off offset:128
	s_waitcnt vmcnt(25)
	v_mul_f32_e32 v48, v48, v103
	s_waitcnt vmcnt(24)
	v_mul_f32_e32 v32, v32, v104
	ds_write2_b32 v162, v48, v32 offset1:32
	v_mul_f32_e32 v32, v49, v103
	v_mul_f32_e32 v33, v33, v104
	ds_write2_b32 v162, v32, v33 offset0:68 offset1:100
	v_mul_f32_e32 v32, v50, v103
	v_mul_f32_e32 v33, v34, v104
	ds_write2_b32 v162, v32, v33 offset0:136 offset1:168
	v_mul_f32_e32 v32, v51, v103
	v_mul_f32_e32 v33, v35, v104
	ds_write2_b32 v162, v32, v33 offset0:204 offset1:236
	s_waitcnt vmcnt(23)
	v_mul_f32_e32 v32, v52, v105
	s_waitcnt vmcnt(22)
	v_mul_f32_e32 v33, v36, v106
	ds_write2_b32 v115, v32, v33 offset0:32 offset1:64
	s_waitcnt vmcnt(21)
	v_mul_f32_e32 v32, v53, v107
	s_waitcnt vmcnt(20)
	v_mul_f32_e32 v33, v37, v108
	ds_write2_b32 v115, v32, v33 offset0:100 offset1:132
	s_waitcnt vmcnt(19)
	v_mul_f32_e32 v32, v54, v109
	s_waitcnt vmcnt(18)
	v_mul_f32_e32 v33, v38, v110
	ds_write2_b32 v115, v32, v33 offset0:168 offset1:200
	v_add_u32_e32 v80, s2, v163
	v_cmp_gt_i32_e32 vcc, s38, v80
	s_waitcnt vmcnt(17)
	v_mul_f32_e32 v32, v55, v111
	s_waitcnt vmcnt(16)
	v_mul_f32_e32 v33, v39, v112
	ds_write2_b32 v116, v32, v33 offset0:108 offset1:140
	s_waitcnt vmcnt(15)
	v_mul_f32_e32 v32, v56, v113
	s_waitcnt vmcnt(14)
	v_mul_f32_e32 v33, v40, v122
	ds_write2_b32 v117, v32, v33 offset0:64 offset1:96
	s_waitcnt vmcnt(13)
	v_mul_f32_e32 v32, v57, v123
	s_waitcnt vmcnt(12)
	v_mul_f32_e32 v33, v41, v124
	ds_write2_b32 v117, v32, v33 offset0:132 offset1:164
	s_waitcnt vmcnt(11)
	v_mul_f32_e32 v32, v58, v125
	s_waitcnt vmcnt(10)
	v_mul_f32_e32 v33, v42, v126
	ds_write2_b32 v117, v32, v33 offset0:200 offset1:232
	s_waitcnt vmcnt(9)
	v_mul_f32_e32 v32, v59, v127
	s_waitcnt vmcnt(8)
	v_mul_f32_e32 v33, v43, v160
	ds_write2_b32 v118, v32, v33 offset0:12 offset1:44
	s_waitcnt vmcnt(7)
	v_mul_f32_e32 v32, v60, v161
	s_waitcnt vmcnt(6)
	v_mul_f32_e32 v33, v44, v164
	ds_write2_b32 v119, v32, v33 offset0:96 offset1:128
	s_waitcnt vmcnt(5)
	v_mul_f32_e32 v32, v61, v165
	s_waitcnt vmcnt(4)
	v_mul_f32_e32 v33, v45, v94
	ds_write2_b32 v119, v32, v33 offset0:164 offset1:196
	s_waitcnt vmcnt(3)
	v_mul_f32_e32 v32, v62, v95
	s_waitcnt vmcnt(2)
	v_mul_f32_e32 v33, v46, v100
	ds_write2_b32 v120, v32, v33 offset0:104 offset1:136
	s_waitcnt vmcnt(1)
	v_mul_f32_e32 v32, v63, v101
	s_waitcnt vmcnt(0)
	v_mul_f32_e32 v33, v47, v81
	v_ashrrev_i32_e32 v81, 31, v80
	ds_write2_b32 v121, v32, v33 offset0:44 offset1:76
	v_add_u32_e32 v128, 0, v80
	v_ashrrev_i32_e32 v129, 31, v128
	v_lshlrev_b64 v[128:129], 12, v[128:129]
	v_lshl_add_u64 v[128:129], s[16:17], 0, v[128:129]
	v_lshl_add_u64 v[128:129], v[96:97], 2, v[128:129]
	global_load_dwordx4 v[128:131], v[128:129], off nt
	v_add_u32_e32 v132, 4, v80
	v_ashrrev_i32_e32 v133, 31, v132
	v_lshlrev_b64 v[132:133], 12, v[132:133]
	v_lshl_add_u64 v[132:133], s[16:17], 0, v[132:133]
	v_lshl_add_u64 v[132:133], v[96:97], 2, v[132:133]
	global_load_dwordx4 v[132:135], v[132:133], off nt
	v_add_u32_e32 v136, 8, v80
	v_ashrrev_i32_e32 v137, 31, v136
	v_lshlrev_b64 v[136:137], 12, v[136:137]
	v_lshl_add_u64 v[136:137], s[16:17], 0, v[136:137]
	v_lshl_add_u64 v[136:137], v[96:97], 2, v[136:137]
	global_load_dwordx4 v[136:139], v[136:137], off nt
	v_add_u32_e32 v140, 12, v80
	v_ashrrev_i32_e32 v141, 31, v140
	v_lshlrev_b64 v[140:141], 12, v[140:141]
	v_lshl_add_u64 v[140:141], s[16:17], 0, v[140:141]
	v_lshl_add_u64 v[140:141], v[96:97], 2, v[140:141]
	global_load_dwordx4 v[140:143], v[140:141], off nt
	v_add_u32_e32 v144, 16, v80
	v_ashrrev_i32_e32 v145, 31, v144
	v_lshlrev_b64 v[144:145], 12, v[144:145]
	v_lshl_add_u64 v[144:145], s[16:17], 0, v[144:145]
	v_lshl_add_u64 v[144:145], v[96:97], 2, v[144:145]
	global_load_dwordx4 v[144:147], v[144:145], off nt
	v_add_u32_e32 v148, 20, v80
	v_ashrrev_i32_e32 v149, 31, v148
	v_lshlrev_b64 v[148:149], 12, v[148:149]
	v_lshl_add_u64 v[148:149], s[16:17], 0, v[148:149]
	v_lshl_add_u64 v[148:149], v[96:97], 2, v[148:149]
	global_load_dwordx4 v[148:151], v[148:149], off nt
	v_add_u32_e32 v152, 24, v80
	v_ashrrev_i32_e32 v153, 31, v152
	v_lshlrev_b64 v[152:153], 12, v[152:153]
	v_lshl_add_u64 v[152:153], s[16:17], 0, v[152:153]
	v_lshl_add_u64 v[152:153], v[96:97], 2, v[152:153]
	global_load_dwordx4 v[152:155], v[152:153], off nt
	v_add_u32_e32 v156, 28, v80
	v_ashrrev_i32_e32 v157, 31, v156
	v_lshlrev_b64 v[156:157], 12, v[156:157]
	v_lshl_add_u64 v[156:157], s[16:17], 0, v[156:157]
	v_lshl_add_u64 v[156:157], v[96:97], 2, v[156:157]
	global_load_dwordx4 v[156:159], v[156:157], off nt
	s_and_saveexec_b64 s[2:3], vcc
	s_cbranch_execz .LBB0_4516
	v_lshlrev_b64 v[32:33], 12, v[80:81]
	v_lshl_add_u64 v[32:33], s[16:17], 0, v[32:33]
	v_lshl_add_u64 v[40:41], v[96:97], 2, v[32:33]
	ds_read_b128 v[36:39], v114
	s_waitcnt vmcnt(7) lgkmcnt(0)
	v_pk_add_f32 v[34:35], v[38:39], v[130:131]
	v_pk_add_f32 v[32:33], v[36:37], v[128:129]
	global_store_dwordx4 v[40:41], v[32:35], off

.LBB0_5644:
	ds_read_b128 v[128:131], v238
	ds_read_b128 v[136:139], v253
	ds_read_b128 v[132:135], v238 offset:4096
	ds_read_b128 v[140:143], v253 offset:4096
	ds_read_b128 v[144:147], v253 offset:8192
	ds_read_b128 v[148:151], v253 offset:12288
	s_waitcnt lgkmcnt(6)
	v_mfma_f32_32x32x16_bf16 v[112:127], v[188:191], v[196:199], v[112:127]
	v_mfma_f32_32x32x16_bf16 v[48:63], v[192:195], v[196:199], v[48:63]
	v_mfma_f32_32x32x16_bf16 v[96:111], v[188:191], v[200:203], v[96:111]
	v_mfma_f32_32x32x16_bf16 v[32:47], v[192:195], v[200:203], v[32:47]
	v_mfma_f32_32x32x16_bf16 v[80:95], v[188:191], v[204:207], v[80:95]
	v_mfma_f32_32x32x16_bf16 v[16:31], v[192:195], v[204:207], v[16:31]
	v_mfma_f32_32x32x16_bf16 v[64:79], v[188:191], v[226:229], v[64:79]
	v_mfma_f32_32x32x16_bf16 v[0:15], v[192:195], v[226:229], v[0:15]
	ds_read_b128 v[188:191], v239
	ds_read_b128 v[196:199], v254
	ds_read_b128 v[192:195], v239 offset:4096
	ds_read_b128 v[200:203], v254 offset:4096
	ds_read_b128 v[204:207], v254 offset:8192
	ds_read_b128 v[226:229], v254 offset:12288
	s_waitcnt lgkmcnt(6)
	v_mfma_f32_32x32x16_bf16 v[112:127], v[128:131], v[136:139], v[112:127]
	v_mfma_f32_32x32x16_bf16 v[48:63], v[132:135], v[136:139], v[48:63]
	v_mfma_f32_32x32x16_bf16 v[96:111], v[128:131], v[140:143], v[96:111]
	v_mfma_f32_32x32x16_bf16 v[32:47], v[132:135], v[140:143], v[32:47]
	v_mfma_f32_32x32x16_bf16 v[80:95], v[128:131], v[144:147], v[80:95]
	v_mfma_f32_32x32x16_bf16 v[16:31], v[132:135], v[144:147], v[16:31]
	v_mfma_f32_32x32x16_bf16 v[64:79], v[128:131], v[148:151], v[64:79]
	v_mfma_f32_32x32x16_bf16 v[0:15], v[132:135], v[148:151], v[0:15]
	ds_read_b128 v[128:131], v240
	ds_read_b128 v[136:139], v255
	ds_read_b128 v[132:135], v240 offset:4096
	ds_read_b128 v[140:143], v255 offset:4096
	ds_read_b128 v[144:147], v255 offset:8192
	ds_read_b128 v[148:151], v255 offset:12288
	s_waitcnt lgkmcnt(6)
	v_mfma_f32_32x32x16_bf16 v[112:127], v[188:191], v[196:199], v[112:127]
	v_mfma_f32_32x32x16_bf16 v[48:63], v[192:195], v[196:199], v[48:63]
	v_mfma_f32_32x32x16_bf16 v[96:111], v[188:191], v[200:203], v[96:111]
	v_mfma_f32_32x32x16_bf16 v[32:47], v[192:195], v[200:203], v[32:47]
	v_mfma_f32_32x32x16_bf16 v[80:95], v[188:191], v[204:207], v[80:95]
	v_mfma_f32_32x32x16_bf16 v[16:31], v[192:195], v[204:207], v[16:31]
	v_mfma_f32_32x32x16_bf16 v[64:79], v[188:191], v[226:229], v[64:79]
	v_mfma_f32_32x32x16_bf16 v[0:15], v[192:195], v[226:229], v[0:15]
	s_waitcnt vmcnt(0) lgkmcnt(0)
	s_barrier
	v_mfma_f32_32x32x16_bf16 v[112:127], v[128:131], v[136:139], v[112:127]
	v_mfma_f32_32x32x16_bf16 v[48:63], v[132:135], v[136:139], v[48:63]
	v_mfma_f32_32x32x16_bf16 v[96:111], v[128:131], v[140:143], v[96:111]
	v_mfma_f32_32x32x16_bf16 v[32:47], v[132:135], v[140:143], v[32:47]
	v_mfma_f32_32x32x16_bf16 v[80:95], v[128:131], v[144:147], v[80:95]
	v_mfma_f32_32x32x16_bf16 v[16:31], v[132:135], v[144:147], v[16:31]
	v_mfma_f32_32x32x16_bf16 v[64:79], v[128:131], v[148:151], v[64:79]
	v_mfma_f32_32x32x16_bf16 v[0:15], v[132:135], v[148:151], v[0:15]
	s_lshl_b32 s2, s5, 8
	s_sub_i32 s2, s2, s6
	v_mov_b32_e32 v168, v214
	s_add_i32 s55, s4, s30
	s_or_b32 s26, s2, s31
	s_ashr_i32 s27, s26, 31
	s_load_dwordx2 s[24:25], s[0:1], 0x140
	v_ashrrev_i32_e32 v180, 3, v168
	v_and_b32_e32 v183, -4, v180
	v_add_u32_e32 v225, s55, v183
	v_add_u32_e32 v190, 8, v225
	v_min_i32_e32 v190, 0x7fff, v190
	v_ashrrev_i32_e32 v190, 12, v190
	v_add_u32_e32 v190, 24, v190
	v_mul_hi_i32_i24_e32 v191, 0x3000, v190
	v_mul_i32_i24_e32 v190, 0x3000, v190
	v_min_i32_e32 v184, 0x7fff, v225
	v_ashrrev_i32_e32 v184, 12, v184
	v_and_b32_e32 v182, 31, v168
	v_add_u32_e32 v184, 24, v184
	v_or_b32_e32 v180, s26, v182
	v_mul_hi_i32_i24_e32 v185, 0x3000, v184
	v_mul_i32_i24_e32 v184, 0x3000, v184
	v_ashrrev_i32_e32 v181, 31, v180
	s_waitcnt lgkmcnt(0)
	v_lshl_add_u64 v[184:185], s[24:25], 0, v[184:185]
	v_lshl_add_u64 v[184:185], v[184:185], 0, s[18:19]
	v_lshlrev_b64 v[180:181], 2, v[180:181]
	v_lshl_add_u64 v[196:197], v[184:185], 0, v[180:181]
	v_lshl_add_u64 v[186:187], s[24:25], 0, v[190:191]
	v_add_u32_e32 v188, 9, v225
	v_add_u32_e32 v190, 10, v225
	v_min_i32_e32 v188, 0x7fff, v188
	v_min_i32_e32 v190, 0x7fff, v190
	v_ashrrev_i32_e32 v188, 12, v188
	v_ashrrev_i32_e32 v190, 12, v190
	v_add_u32_e32 v188, 24, v188
	v_add_u32_e32 v190, 24, v190
	v_mul_hi_i32_i24_e32 v189, 0x3000, v188
	v_mul_i32_i24_e32 v188, 0x3000, v188
	v_mul_hi_i32_i24_e32 v191, 0x3000, v190
	v_mul_i32_i24_e32 v190, 0x3000, v190
	v_lshl_add_u64 v[188:189], s[24:25], 0, v[188:189]
	v_lshl_add_u64 v[190:191], s[24:25], 0, v[190:191]
	v_lshl_add_u64 v[186:187], v[186:187], 0, s[18:19]
	v_lshl_add_u64 v[188:189], v[188:189], 0, s[18:19]
	v_lshl_add_u64 v[190:191], v[190:191], 0, s[18:19]
	v_lshl_add_u64 v[206:207], v[186:187], 0, v[180:181]
	v_add_u32_e32 v208, 18, v225
	v_min_i32_e32 v208, 0x7fff, v208
	v_ashrrev_i32_e32 v208, 12, v208
	v_add_u32_e32 v208, 24, v208
	v_mul_hi_i32_i24_e32 v209, 0x3000, v208
	v_mul_i32_i24_e32 v208, 0x3000, v208
	v_lshl_add_u64 v[208:209], s[24:25], 0, v[208:209]
	v_lshl_add_u64 v[202:203], v[188:189], 0, v[180:181]
	v_lshl_add_u64 v[204:205], v[190:191], 0, v[180:181]
	global_load_dword v232, v[196:197], off
	global_load_dword v233, v[196:197], off offset:128
	global_load_dword v242, v[206:207], off
	global_load_dword v243, v[206:207], off offset:128
	global_load_dword v244, v[202:203], off
	global_load_dword v245, v[202:203], off offset:128
	global_load_dword v246, v[204:205], off
	global_load_dword v247, v[204:205], off offset:128
	v_add_u32_e32 v196, 17, v225
	v_min_i32_e32 v196, 0x7fff, v196
	v_ashrrev_i32_e32 v196, 12, v196
	v_add_u32_e32 v196, 24, v196
	v_mul_hi_i32_i24_e32 v197, 0x3000, v196
	v_mul_i32_i24_e32 v196, 0x3000, v196
	v_lshl_add_u64 v[196:197], s[24:25], 0, v[196:197]
	v_lshl_add_u64 v[196:197], v[196:197], 0, s[18:19]
	v_lshl_add_u64 v[206:207], v[196:197], 0, v[180:181]
	s_waitcnt vmcnt(7)
	s_nop 5
	v_mul_f32_e32 v112, v112, v232
	v_add_u32_e32 v192, 11, v225
	v_add_u32_e32 v194, 16, v225
	v_min_i32_e32 v192, 0x7fff, v192
	v_min_i32_e32 v194, 0x7fff, v194
	v_ashrrev_i32_e32 v192, 12, v192
	v_ashrrev_i32_e32 v194, 12, v194
	v_add_u32_e32 v192, 24, v192
	v_add_u32_e32 v194, 24, v194
	v_mul_hi_i32_i24_e32 v193, 0x3000, v192
	v_mul_i32_i24_e32 v192, 0x3000, v192
	v_mul_hi_i32_i24_e32 v195, 0x3000, v194
	v_mul_i32_i24_e32 v194, 0x3000, v194
	v_lshl_add_u64 v[192:193], s[24:25], 0, v[192:193]
	v_lshl_add_u64 v[194:195], s[24:25], 0, v[194:195]
	v_lshl_add_u64 v[192:193], v[192:193], 0, s[18:19]
	v_lshl_add_u64 v[194:195], v[194:195], 0, s[18:19]
	v_lshl_add_u64 v[202:203], v[192:193], 0, v[180:181]
	v_lshl_add_u64 v[204:205], v[194:195], 0, v[180:181]
	s_waitcnt vmcnt(6)
	s_nop 5
	v_mul_f32_e32 v96, v96, v233
	v_mul_f32_e32 v97, v97, v233
	v_lshl_add_u64 v[198:199], v[208:209], 0, s[18:19]
	v_lshl_add_u64 v[200:201], v[198:199], 0, v[180:181]
	global_load_dword v234, v[202:203], off
	global_load_dword v235, v[202:203], off offset:128
	global_load_dword v236, v[204:205], off
	global_load_dword v237, v[204:205], off offset:128
	global_load_dword v238, v[206:207], off
	global_load_dword v239, v[206:207], off offset:128
	global_load_dword v240, v[200:201], off
	global_load_dword v241, v[200:201], off offset:128
	v_add_u32_e32 v200, 19, v225
	v_add_u32_e32 v204, 25, v225
	v_add_u32_e32 v206, 26, v225
	v_min_i32_e32 v200, 0x7fff, v200
	v_add_u32_e32 v202, 24, v225
	v_min_i32_e32 v204, 0x7fff, v204
	v_min_i32_e32 v206, 0x7fff, v206
	v_ashrrev_i32_e32 v200, 12, v200
	v_min_i32_e32 v202, 0x7fff, v202
	v_ashrrev_i32_e32 v204, 12, v204
	v_ashrrev_i32_e32 v206, 12, v206
	v_add_u32_e32 v200, 24, v200
	v_ashrrev_i32_e32 v202, 12, v202
	v_add_u32_e32 v204, 24, v204
	v_add_u32_e32 v206, 24, v206
	v_mul_hi_i32_i24_e32 v201, 0x3000, v200
	v_mul_i32_i24_e32 v200, 0x3000, v200
	v_add_u32_e32 v202, 24, v202
	v_mul_hi_i32_i24_e32 v205, 0x3000, v204
	v_mul_i32_i24_e32 v204, 0x3000, v204
	v_mul_hi_i32_i24_e32 v207, 0x3000, v206
	v_mul_i32_i24_e32 v206, 0x3000, v206
	v_lshl_add_u64 v[200:201], s[24:25], 0, v[200:201]
	v_mul_hi_i32_i24_e32 v203, 0x3000, v202
	v_mul_i32_i24_e32 v202, 0x3000, v202
	v_lshl_add_u64 v[204:205], s[24:25], 0, v[204:205]
	v_lshl_add_u64 v[206:207], s[24:25], 0, v[206:207]
	v_lshl_add_u64 v[200:201], v[200:201], 0, s[18:19]
	v_lshl_add_u64 v[202:203], s[24:25], 0, v[202:203]
	v_lshl_add_u64 v[204:205], v[204:205], 0, s[18:19]
	v_lshl_add_u64 v[206:207], v[206:207], 0, s[18:19]
	v_lshl_add_u64 v[208:209], v[200:201], 0, v[180:181]
	v_lshl_add_u64 v[202:203], v[202:203], 0, s[18:19]
	v_lshl_add_u64 v[228:229], v[204:205], 0, v[180:181]
	v_lshl_add_u64 v[230:231], v[206:207], 0, v[180:181]
	v_lshl_add_u64 v[226:227], v[202:203], 0, v[180:181]
	global_load_dword v248, v[208:209], off
	global_load_dword v249, v[208:209], off offset:128
	global_load_dword v250, v[226:227], off
	global_load_dword v251, v[226:227], off offset:128
	global_load_dword v252, v[228:229], off
	s_nop 0
	global_load_dword v228, v[228:229], off offset:128
	s_nop 0
	global_load_dword v229, v[230:231], off
	s_nop 0
	global_load_dword v230, v[230:231], off offset:128
	v_add_u32_e32 v208, 27, v225
	v_min_i32_e32 v208, 0x7fff, v208
	v_ashrrev_i32_e32 v208, 12, v208
	v_add_u32_e32 v208, 24, v208
	v_mul_hi_i32_i24_e32 v209, 0x3000, v208
	v_mul_i32_i24_e32 v208, 0x3000, v208
	v_lshl_add_u64 v[208:209], s[24:25], 0, v[208:209]
	v_lshl_add_u64 v[208:209], v[208:209], 0, s[18:19]
	v_lshl_add_u64 v[226:227], v[208:209], 0, v[180:181]
	global_load_dword v225, v[226:227], off
	s_nop 0
	global_load_dword v226, v[226:227], off offset:128
	v_mad_u64_u32 v[160:161], s[2:3], v183, s36, v[182:183]
	v_lshl_add_u32 v162, v160, 2, s34
	ds_write2_b32 v162, v112, v96 offset1:32
	v_mul_f32_e32 v96, v113, v232
	ds_write2_b32 v162, v96, v97 offset0:68 offset1:100
	v_mul_f32_e32 v96, v114, v232
	v_mul_f32_e32 v97, v98, v233
	ds_write2_b32 v162, v96, v97 offset0:136 offset1:168
	v_mul_f32_e32 v96, v115, v232
	v_mul_f32_e32 v97, v99, v233
	ds_write2_b32 v162, v96, v97 offset0:204 offset1:236
	s_waitcnt vmcnt(23)
	v_mul_f32_e32 v96, v116, v242
	s_waitcnt vmcnt(22)
	v_mul_f32_e32 v97, v100, v243
	v_add_u32_e32 v115, 0x800, v162
	ds_write2_b32 v115, v96, v97 offset0:32 offset1:64
	s_waitcnt vmcnt(21)
	v_mul_f32_e32 v96, v117, v244
	s_waitcnt vmcnt(20)
	v_mul_f32_e32 v97, v101, v245
	ds_write2_b32 v115, v96, v97 offset0:100 offset1:132
	s_waitcnt vmcnt(19)
	v_mul_f32_e32 v96, v118, v246
	s_waitcnt vmcnt(18)
	v_mul_f32_e32 v97, v102, v247
	ds_write2_b32 v115, v96, v97 offset0:168 offset1:200
	v_add_u32_e32 v116, 0xa00, v162
	v_add_u32_e32 v117, 0x1000, v162
	s_waitcnt vmcnt(17)
	v_mul_f32_e32 v96, v119, v234
	s_waitcnt vmcnt(16)
	v_mul_f32_e32 v97, v103, v235
	ds_write2_b32 v116, v96, v97 offset0:108 offset1:140
	s_waitcnt vmcnt(15)
	v_mul_f32_e32 v96, v120, v236
	s_waitcnt vmcnt(14)
	v_mul_f32_e32 v97, v104, v237
	ds_write2_b32 v117, v96, v97 offset0:64 offset1:96
	s_waitcnt vmcnt(13)
	v_mul_f32_e32 v96, v121, v238
	s_waitcnt vmcnt(12)
	v_mul_f32_e32 v97, v105, v239
	ds_write2_b32 v117, v96, v97 offset0:132 offset1:164
	s_waitcnt vmcnt(11)
	v_mul_f32_e32 v96, v122, v240
	s_waitcnt vmcnt(10)
	v_mul_f32_e32 v97, v106, v241
	ds_write2_b32 v117, v96, v97 offset0:200 offset1:232
	v_add_u32_e32 v118, 0x1400, v162
	v_add_u32_e32 v119, 0x1800, v162
	v_ashrrev_i32_e32 v163, 4, v168
	v_and_b32_e32 v160, 15, v168
	v_add_u32_e32 v120, 0x1a00, v162
	v_mul_lo_u32 v164, v163, s37
	v_lshl_add_u32 v165, v160, 4, s34
	v_lshlrev_b32_e32 v168, 2, v160
	v_add_u32_e32 v160, s55, v163
	v_add_u32_e32 v121, 0x1c00, v162
	v_cmp_gt_i32_e32 vcc, s38, v160
	v_ashrrev_i32_e32 v161, 31, v160
	v_add_u32_e32 v114, v165, v164
	s_waitcnt vmcnt(9)
	v_mul_f32_e32 v96, v123, v248
	s_waitcnt vmcnt(8)
	v_mul_f32_e32 v97, v107, v249
	ds_write2_b32 v118, v96, v97 offset0:12 offset1:44
	s_waitcnt vmcnt(7)
	v_mul_f32_e32 v96, v124, v250
	s_waitcnt vmcnt(6)
	v_mul_f32_e32 v97, v108, v251
	ds_write2_b32 v119, v96, v97 offset0:96 offset1:128
	s_waitcnt vmcnt(5)
	v_mul_f32_e32 v96, v125, v252
	s_waitcnt vmcnt(4)
	v_mul_f32_e32 v97, v109, v228
	ds_write2_b32 v119, v96, v97 offset0:164 offset1:196
	s_waitcnt vmcnt(3)
	v_mul_f32_e32 v96, v126, v229
	s_waitcnt vmcnt(2)
	v_mul_f32_e32 v97, v110, v230
	ds_write2_b32 v120, v96, v97 offset0:104 offset1:136
	s_waitcnt vmcnt(1)
	v_mul_f32_e32 v96, v127, v225
	s_waitcnt vmcnt(0)
	v_mul_f32_e32 v97, v111, v226
	ds_write2_b32 v121, v96, v97 offset0:44 offset1:76
	v_or_b32_e32 v96, s26, v168
	v_mov_b32_e32 v97, s27
	v_add_u32_e32 v128, 0, v160
	v_ashrrev_i32_e32 v129, 31, v128
	v_lshlrev_b64 v[128:129], 12, v[128:129]
	v_lshl_add_u64 v[128:129], s[16:17], 0, v[128:129]
	v_lshl_add_u64 v[128:129], v[96:97], 2, v[128:129]
	global_load_dwordx4 v[128:131], v[128:129], off nt
	v_add_u32_e32 v132, 4, v160
	v_ashrrev_i32_e32 v133, 31, v132
	v_lshlrev_b64 v[132:133], 12, v[132:133]
	v_lshl_add_u64 v[132:133], s[16:17], 0, v[132:133]
	v_lshl_add_u64 v[132:133], v[96:97], 2, v[132:133]
	global_load_dwordx4 v[132:135], v[132:133], off nt
	v_add_u32_e32 v136, 8, v160
	v_ashrrev_i32_e32 v137, 31, v136
	v_lshlrev_b64 v[136:137], 12, v[136:137]
	v_lshl_add_u64 v[136:137], s[16:17], 0, v[136:137]
	v_lshl_add_u64 v[136:137], v[96:97], 2, v[136:137]
	global_load_dwordx4 v[136:139], v[136:137], off nt
	v_add_u32_e32 v140, 12, v160
	v_ashrrev_i32_e32 v141, 31, v140
	v_lshlrev_b64 v[140:141], 12, v[140:141]
	v_lshl_add_u64 v[140:141], s[16:17], 0, v[140:141]
	v_lshl_add_u64 v[140:141], v[96:97], 2, v[140:141]
	global_load_dwordx4 v[140:143], v[140:141], off nt
	v_add_u32_e32 v144, 16, v160
	v_ashrrev_i32_e32 v145, 31, v144
	v_lshlrev_b64 v[144:145], 12, v[144:145]
	v_lshl_add_u64 v[144:145], s[16:17], 0, v[144:145]
	v_lshl_add_u64 v[144:145], v[96:97], 2, v[144:145]
	global_load_dwordx4 v[144:147], v[144:145], off nt
	v_add_u32_e32 v148, 20, v160
	v_ashrrev_i32_e32 v149, 31, v148
	v_lshlrev_b64 v[148:149], 12, v[148:149]
	v_lshl_add_u64 v[148:149], s[16:17], 0, v[148:149]
	v_lshl_add_u64 v[148:149], v[96:97], 2, v[148:149]
	global_load_dwordx4 v[148:151], v[148:149], off nt
	v_add_u32_e32 v152, 24, v160
	v_ashrrev_i32_e32 v153, 31, v152
	v_lshlrev_b64 v[152:153], 12, v[152:153]
	v_lshl_add_u64 v[152:153], s[16:17], 0, v[152:153]
	v_lshl_add_u64 v[152:153], v[96:97], 2, v[152:153]
	global_load_dwordx4 v[152:155], v[152:153], off nt
	v_add_u32_e32 v156, 28, v160
	v_ashrrev_i32_e32 v157, 31, v156
	v_lshlrev_b64 v[156:157], 12, v[156:157]
	v_lshl_add_u64 v[156:157], s[16:17], 0, v[156:157]
	v_lshl_add_u64 v[156:157], v[96:97], 2, v[156:157]
	global_load_dwordx4 v[156:159], v[156:157], off nt
	s_and_saveexec_b64 s[2:3], vcc
	s_cbranch_execz .LBB0_5646
	v_lshlrev_b64 v[98:99], 12, v[160:161]
	v_lshl_add_u64 v[98:99], s[16:17], 0, v[98:99]
	v_lshl_add_u64 v[106:107], v[96:97], 2, v[98:99]
	ds_read_b128 v[102:105], v114
	s_waitcnt vmcnt(7) lgkmcnt(0)
	v_pk_add_f32 v[100:101], v[104:105], v[130:131]
	v_pk_add_f32 v[98:99], v[102:103], v[128:129]
	global_store_dwordx4 v[106:107], v[98:101], off

.LBB0_5676:
	s_or_b64 exec, exec, s[2:3]
	s_or_b32 s2, s55, 32
	v_add_u32_e32 v102, s2, v183
	v_min_i32_e32 v66, 0x7fff, v102
	v_add_u32_e32 v68, 8, v102
	v_add_u32_e32 v70, 9, v102
	v_add_u32_e32 v72, 10, v102
	v_ashrrev_i32_e32 v66, 12, v66
	v_min_i32_e32 v68, 0x7fff, v68
	v_min_i32_e32 v70, 0x7fff, v70
	v_min_i32_e32 v72, 0x7fff, v72
	v_add_u32_e32 v66, 24, v66
	v_ashrrev_i32_e32 v68, 12, v68
	v_ashrrev_i32_e32 v70, 12, v70
	v_ashrrev_i32_e32 v72, 12, v72
	v_mul_hi_i32_i24_e32 v67, 0x3000, v66
	v_mul_i32_i24_e32 v66, 0x3000, v66
	v_add_u32_e32 v68, 24, v68
	v_add_u32_e32 v70, 24, v70
	v_add_u32_e32 v72, 24, v72
	v_lshl_add_u64 v[66:67], s[24:25], 0, v[66:67]
	v_mul_hi_i32_i24_e32 v69, 0x3000, v68
	v_mul_i32_i24_e32 v68, 0x3000, v68
	v_mul_hi_i32_i24_e32 v71, 0x3000, v70
	v_mul_i32_i24_e32 v70, 0x3000, v70
	v_mul_hi_i32_i24_e32 v73, 0x3000, v72
	v_mul_i32_i24_e32 v72, 0x3000, v72
	v_lshl_add_u64 v[66:67], v[66:67], 0, s[18:19]
	v_lshl_add_u64 v[68:69], s[24:25], 0, v[68:69]
	v_lshl_add_u64 v[70:71], s[24:25], 0, v[70:71]
	v_lshl_add_u64 v[72:73], s[24:25], 0, v[72:73]
	v_lshl_add_u64 v[74:75], v[66:67], 0, v[180:181]
	v_lshl_add_u64 v[68:69], v[68:69], 0, s[18:19]
	v_lshl_add_u64 v[70:71], v[70:71], 0, s[18:19]
	v_lshl_add_u64 v[72:73], v[72:73], 0, s[18:19]
	v_lshl_add_u64 v[76:77], v[68:69], 0, v[180:181]
	v_lshl_add_u64 v[78:79], v[70:71], 0, v[180:181]
	v_lshl_add_u64 v[80:81], v[72:73], 0, v[180:181]
	global_load_dword v103, v[74:75], off
	global_load_dword v104, v[74:75], off offset:128
	global_load_dword v105, v[76:77], off
	global_load_dword v106, v[76:77], off offset:128
	global_load_dword v107, v[78:79], off
	global_load_dword v108, v[78:79], off offset:128
	global_load_dword v109, v[80:81], off
	global_load_dword v110, v[80:81], off offset:128
	v_add_u32_e32 v74, 11, v102
	v_add_u32_e32 v82, 18, v102
	v_min_i32_e32 v74, 0x7fff, v74
	v_add_u32_e32 v76, 16, v102
	v_add_u32_e32 v78, 17, v102
	v_min_i32_e32 v82, 0x7fff, v82
	v_ashrrev_i32_e32 v74, 12, v74
	v_min_i32_e32 v76, 0x7fff, v76
	v_min_i32_e32 v78, 0x7fff, v78
	v_ashrrev_i32_e32 v82, 12, v82
	v_add_u32_e32 v74, 24, v74
	v_ashrrev_i32_e32 v76, 12, v76
	v_ashrrev_i32_e32 v78, 12, v78
	v_add_u32_e32 v82, 24, v82
	v_mul_hi_i32_i24_e32 v75, 0x3000, v74
	v_mul_i32_i24_e32 v74, 0x3000, v74
	v_add_u32_e32 v76, 24, v76
	v_add_u32_e32 v78, 24, v78
	v_mul_hi_i32_i24_e32 v83, 0x3000, v82
	v_mul_i32_i24_e32 v82, 0x3000, v82
	v_lshl_add_u64 v[74:75], s[24:25], 0, v[74:75]
	v_mul_hi_i32_i24_e32 v77, 0x3000, v76
	v_mul_i32_i24_e32 v76, 0x3000, v76
	v_mul_hi_i32_i24_e32 v79, 0x3000, v78
	v_mul_i32_i24_e32 v78, 0x3000, v78
	v_lshl_add_u64 v[82:83], s[24:25], 0, v[82:83]
	v_lshl_add_u64 v[74:75], v[74:75], 0, s[18:19]
	v_lshl_add_u64 v[76:77], s[24:25], 0, v[76:77]
	v_lshl_add_u64 v[78:79], s[24:25], 0, v[78:79]
	v_lshl_add_u64 v[82:83], v[82:83], 0, s[18:19]
	v_lshl_add_u64 v[80:81], v[74:75], 0, v[180:181]
	v_lshl_add_u64 v[76:77], v[76:77], 0, s[18:19]
	v_lshl_add_u64 v[78:79], v[78:79], 0, s[18:19]
	v_lshl_add_u64 v[88:89], v[82:83], 0, v[180:181]
	v_lshl_add_u64 v[84:85], v[76:77], 0, v[180:181]
	v_lshl_add_u64 v[86:87], v[78:79], 0, v[180:181]
	global_load_dword v111, v[80:81], off
	global_load_dword v112, v[80:81], off offset:128
	global_load_dword v113, v[84:85], off
	global_load_dword v122, v[84:85], off offset:128
	global_load_dword v123, v[86:87], off
	global_load_dword v124, v[86:87], off offset:128
	global_load_dword v125, v[88:89], off
	global_load_dword v126, v[88:89], off offset:128
	v_add_u32_e32 v80, 19, v102
	v_add_u32_e32 v88, 25, v102
	v_add_u32_e32 v90, 26, v102
	v_min_i32_e32 v80, 0x7fff, v80
	v_add_u32_e32 v86, 24, v102
	v_min_i32_e32 v88, 0x7fff, v88
	v_min_i32_e32 v90, 0x7fff, v90
	v_ashrrev_i32_e32 v80, 12, v80
	v_min_i32_e32 v86, 0x7fff, v86
	v_ashrrev_i32_e32 v88, 12, v88
	v_ashrrev_i32_e32 v90, 12, v90
	v_add_u32_e32 v80, 24, v80
	v_ashrrev_i32_e32 v86, 12, v86
	v_add_u32_e32 v88, 24, v88
	v_add_u32_e32 v90, 24, v90
	v_mul_hi_i32_i24_e32 v81, 0x3000, v80
	v_mul_i32_i24_e32 v80, 0x3000, v80
	v_add_u32_e32 v86, 24, v86
	v_mul_hi_i32_i24_e32 v89, 0x3000, v88
	v_mul_i32_i24_e32 v88, 0x3000, v88
	v_mul_hi_i32_i24_e32 v91, 0x3000, v90
	v_mul_i32_i24_e32 v90, 0x3000, v90
	v_lshl_add_u64 v[80:81], s[24:25], 0, v[80:81]
	v_mul_hi_i32_i24_e32 v87, 0x3000, v86
	v_mul_i32_i24_e32 v86, 0x3000, v86
	v_lshl_add_u64 v[88:89], s[24:25], 0, v[88:89]
	v_lshl_add_u64 v[90:91], s[24:25], 0, v[90:91]
	v_lshl_add_u64 v[84:85], v[80:81], 0, s[18:19]
	v_lshl_add_u64 v[86:87], s[24:25], 0, v[86:87]
	v_lshl_add_u64 v[88:89], v[88:89], 0, s[18:19]
	v_lshl_add_u64 v[90:91], v[90:91], 0, s[18:19]
	v_lshl_add_u64 v[80:81], v[84:85], 0, v[180:181]
	v_lshl_add_u64 v[86:87], v[86:87], 0, s[18:19]
	v_lshl_add_u64 v[94:95], v[88:89], 0, v[180:181]
	v_lshl_add_u64 v[100:101], v[90:91], 0, v[180:181]
	v_lshl_add_u64 v[92:93], v[86:87], 0, v[180:181]
	global_load_dword v127, v[80:81], off
	global_load_dword v160, v[80:81], off offset:128
	global_load_dword v161, v[92:93], off
	global_load_dword v164, v[92:93], off offset:128
	global_load_dword v165, v[94:95], off
	s_nop 0
	global_load_dword v94, v[94:95], off offset:128
	s_nop 0
	global_load_dword v95, v[100:101], off
	s_nop 0
	global_load_dword v100, v[100:101], off offset:128
	v_add_u32_e32 v80, 27, v102
	v_min_i32_e32 v80, 0x7fff, v80
	v_ashrrev_i32_e32 v80, 12, v80
	v_add_u32_e32 v80, 24, v80
	v_mul_hi_i32_i24_e32 v81, 0x3000, v80
	v_mul_i32_i24_e32 v80, 0x3000, v80
	v_lshl_add_u64 v[80:81], s[24:25], 0, v[80:81]
	v_lshl_add_u64 v[92:93], v[80:81], 0, s[18:19]
	v_lshl_add_u64 v[80:81], v[92:93], 0, v[180:181]
	global_load_dword v101, v[80:81], off
	s_nop 0
	global_load_dword v81, v[80:81], off offset:128
	s_waitcnt vmcnt(25)
	v_mul_f32_e32 v48, v48, v103
	s_waitcnt vmcnt(24)
	v_mul_f32_e32 v32, v32, v104
	ds_write2_b32 v162, v48, v32 offset1:32
	v_mul_f32_e32 v32, v49, v103
	v_mul_f32_e32 v33, v33, v104
	ds_write2_b32 v162, v32, v33 offset0:68 offset1:100
	v_mul_f32_e32 v32, v50, v103
	v_mul_f32_e32 v33, v34, v104
	ds_write2_b32 v162, v32, v33 offset0:136 offset1:168
	v_mul_f32_e32 v32, v51, v103
	v_mul_f32_e32 v33, v35, v104
	ds_write2_b32 v162, v32, v33 offset0:204 offset1:236
	s_waitcnt vmcnt(23)
	v_mul_f32_e32 v32, v52, v105
	s_waitcnt vmcnt(22)
	v_mul_f32_e32 v33, v36, v106
	ds_write2_b32 v115, v32, v33 offset0:32 offset1:64
	s_waitcnt vmcnt(21)
	v_mul_f32_e32 v32, v53, v107
	s_waitcnt vmcnt(20)
	v_mul_f32_e32 v33, v37, v108
	ds_write2_b32 v115, v32, v33 offset0:100 offset1:132
	s_waitcnt vmcnt(19)
	v_mul_f32_e32 v32, v54, v109
	s_waitcnt vmcnt(18)
	v_mul_f32_e32 v33, v38, v110
	ds_write2_b32 v115, v32, v33 offset0:168 offset1:200
	v_add_u32_e32 v80, s2, v163
	v_cmp_gt_i32_e32 vcc, s38, v80
	s_waitcnt vmcnt(17)
	v_mul_f32_e32 v32, v55, v111
	s_waitcnt vmcnt(16)
	v_mul_f32_e32 v33, v39, v112
	ds_write2_b32 v116, v32, v33 offset0:108 offset1:140
	s_waitcnt vmcnt(15)
	v_mul_f32_e32 v32, v56, v113
	s_waitcnt vmcnt(14)
	v_mul_f32_e32 v33, v40, v122
	ds_write2_b32 v117, v32, v33 offset0:64 offset1:96
	s_waitcnt vmcnt(13)
	v_mul_f32_e32 v32, v57, v123
	s_waitcnt vmcnt(12)
	v_mul_f32_e32 v33, v41, v124
	ds_write2_b32 v117, v32, v33 offset0:132 offset1:164
	s_waitcnt vmcnt(11)
	v_mul_f32_e32 v32, v58, v125
	s_waitcnt vmcnt(10)
	v_mul_f32_e32 v33, v42, v126
	ds_write2_b32 v117, v32, v33 offset0:200 offset1:232
	s_waitcnt vmcnt(9)
	v_mul_f32_e32 v32, v59, v127
	s_waitcnt vmcnt(8)
	v_mul_f32_e32 v33, v43, v160
	ds_write2_b32 v118, v32, v33 offset0:12 offset1:44
	s_waitcnt vmcnt(7)
	v_mul_f32_e32 v32, v60, v161
	s_waitcnt vmcnt(6)
	v_mul_f32_e32 v33, v44, v164
	ds_write2_b32 v119, v32, v33 offset0:96 offset1:128
	s_waitcnt vmcnt(5)
	v_mul_f32_e32 v32, v61, v165
	s_waitcnt vmcnt(4)
	v_mul_f32_e32 v33, v45, v94
	ds_write2_b32 v119, v32, v33 offset0:164 offset1:196
	s_waitcnt vmcnt(3)
	v_mul_f32_e32 v32, v62, v95
	s_waitcnt vmcnt(2)
	v_mul_f32_e32 v33, v46, v100
	ds_write2_b32 v120, v32, v33 offset0:104 offset1:136
	s_waitcnt vmcnt(1)
	v_mul_f32_e32 v32, v63, v101
	s_waitcnt vmcnt(0)
	v_mul_f32_e32 v33, v47, v81
	v_ashrrev_i32_e32 v81, 31, v80
	ds_write2_b32 v121, v32, v33 offset0:44 offset1:76
	v_add_u32_e32 v128, 0, v80
	v_ashrrev_i32_e32 v129, 31, v128
	v_lshlrev_b64 v[128:129], 12, v[128:129]
	v_lshl_add_u64 v[128:129], s[16:17], 0, v[128:129]
	v_lshl_add_u64 v[128:129], v[96:97], 2, v[128:129]
	global_load_dwordx4 v[128:131], v[128:129], off nt
	v_add_u32_e32 v132, 4, v80
	v_ashrrev_i32_e32 v133, 31, v132
	v_lshlrev_b64 v[132:133], 12, v[132:133]
	v_lshl_add_u64 v[132:133], s[16:17], 0, v[132:133]
	v_lshl_add_u64 v[132:133], v[96:97], 2, v[132:133]
	global_load_dwordx4 v[132:135], v[132:133], off nt
	v_add_u32_e32 v136, 8, v80
	v_ashrrev_i32_e32 v137, 31, v136
	v_lshlrev_b64 v[136:137], 12, v[136:137]
	v_lshl_add_u64 v[136:137], s[16:17], 0, v[136:137]
	v_lshl_add_u64 v[136:137], v[96:97], 2, v[136:137]
	global_load_dwordx4 v[136:139], v[136:137], off nt
	v_add_u32_e32 v140, 12, v80
	v_ashrrev_i32_e32 v141, 31, v140
	v_lshlrev_b64 v[140:141], 12, v[140:141]
	v_lshl_add_u64 v[140:141], s[16:17], 0, v[140:141]
	v_lshl_add_u64 v[140:141], v[96:97], 2, v[140:141]
	global_load_dwordx4 v[140:143], v[140:141], off nt
	v_add_u32_e32 v144, 16, v80
	v_ashrrev_i32_e32 v145, 31, v144
	v_lshlrev_b64 v[144:145], 12, v[144:145]
	v_lshl_add_u64 v[144:145], s[16:17], 0, v[144:145]
	v_lshl_add_u64 v[144:145], v[96:97], 2, v[144:145]
	global_load_dwordx4 v[144:147], v[144:145], off nt
	v_add_u32_e32 v148, 20, v80
	v_ashrrev_i32_e32 v149, 31, v148
	v_lshlrev_b64 v[148:149], 12, v[148:149]
	v_lshl_add_u64 v[148:149], s[16:17], 0, v[148:149]
	v_lshl_add_u64 v[148:149], v[96:97], 2, v[148:149]
	global_load_dwordx4 v[148:151], v[148:149], off nt
	v_add_u32_e32 v152, 24, v80
	v_ashrrev_i32_e32 v153, 31, v152
	v_lshlrev_b64 v[152:153], 12, v[152:153]
	v_lshl_add_u64 v[152:153], s[16:17], 0, v[152:153]
	v_lshl_add_u64 v[152:153], v[96:97], 2, v[152:153]
	global_load_dwordx4 v[152:155], v[152:153], off nt
	v_add_u32_e32 v156, 28, v80
	v_ashrrev_i32_e32 v157, 31, v156
	v_lshlrev_b64 v[156:157], 12, v[156:157]
	v_lshl_add_u64 v[156:157], s[16:17], 0, v[156:157]
	v_lshl_add_u64 v[156:157], v[96:97], 2, v[156:157]
	global_load_dwordx4 v[156:159], v[156:157], off nt
	s_and_saveexec_b64 s[2:3], vcc
	s_cbranch_execz .LBB0_5678
	v_lshlrev_b64 v[32:33], 12, v[80:81]
	v_lshl_add_u64 v[32:33], s[16:17], 0, v[32:33]
	v_lshl_add_u64 v[40:41], v[96:97], 2, v[32:33]
	ds_read_b128 v[36:39], v114
	s_waitcnt vmcnt(7) lgkmcnt(0)
	v_pk_add_f32 v[34:35], v[38:39], v[130:131]
	v_pk_add_f32 v[32:33], v[36:37], v[128:129]
	global_store_dwordx4 v[40:41], v[32:35], off
